# GLA prep: the 16-token meta unit leaves the serial gate loop after step 15 (its later steps are padding with ls = 0)
# baseline (speedup 1.0000x reference)
; #define LAS __attribute__((address_space(3)))
; __device__ __forceinline__ void gla_prep(LAS unsigned char* lds, const bf16_t* QK, const float* gz, const float* Wg, const float* bias,
;                                          bf16_t* QPimg, bf16_t* KTimg, bf16_t* Aimg, float* dec, int G) {
;     ...
;         { LAS bf16_t* dstb = (tid & 64) ? Ks : Qs; const int colb = ((tid & 127) * 8) & 511;
; #pragma unroll
;           for (int i = 0; i < 16; ++i) *(LAS u32x4*)(dstb + (4 * i + (tid >> 7)) * GP_PITCH + colb) = raw[i]; }
;         __syncthreads();
;         float bb[64]; float bs = 0.f;
; #pragma unroll
;         for (int t = 0; t < 64; ++t) {
;             float x = bi;
; #pragma unroll
;             for (int q4 = 0; q4 < 4; ++q4) { const f32x4 g4 = *(const LAS f32x4*)(gzs + t * 16 + q4 * 4); x += g4.x * wg[4 * q4] + g4.y * wg[4 * q4 + 1] + g4.z * wg[4 * q4 + 2] + g4.w * wg[4 * q4 + 3]; }
;             float ls = (fminf(x, 0.f) - __logf(1.f + __expf(-fabsf(x)))) * (1.f / 16.f);
;             if (t >= ntok) ls = 0.f;
;             bs += ls; bb[t] = bs;
.LBB0_241:
	s_or_b64 exec, exec, s[72:73]
	s_waitcnt vmcnt(0)
	ds_write_b128 v15, v[6:9]
	ds_write_b128 v15, v[2:5] offset:4160
	ds_write_b128 v15, v[18:21] offset:8320
	ds_write_b128 v15, v[10:13] offset:12480
	ds_write_b128 v15, v[26:29] offset:16640
	ds_write_b128 v15, v[22:25] offset:20800
	ds_write_b128 v15, v[34:37] offset:24960
	ds_write_b128 v15, v[30:33] offset:29120
	ds_write_b128 v15, v[42:45] offset:33280
	ds_write_b128 v15, v[38:41] offset:37440
	ds_write_b128 v15, v[50:53] offset:41600
	ds_write_b128 v15, v[46:49] offset:45760
	ds_write_b128 v15, v[58:61] offset:49920
	ds_write_b128 v15, v[54:57] offset:54080
	ds_write_b128 v15, v[66:69] offset:58240
	ds_write_b128 v15, v[62:65] offset:62400
	s_waitcnt lgkmcnt(0)
	s_barrier
	ds_read_b128 v[2:5], v1
	ds_read_b128 v[6:9], v1 offset:16
	ds_read_b128 v[10:13], v1 offset:32
	ds_read_b128 v[18:21], v1 offset:48
	s_mov_b32 s4, 0xbfb8aa3b
	s_waitcnt lgkmcnt(3)
	v_mov_b32_e32 v22, v2
	s_waitcnt lgkmcnt(2)
	v_mov_b32_e32 v23, v6
	v_mov_b32_e32 v6, v3
	v_pk_mul_f32 v[2:3], v[76:77], v[6:7]
	v_mov_b32_e32 v6, v4
	v_pk_fma_f32 v[2:3], v[74:75], v[22:23], v[2:3]
	v_mov_b32_e32 v7, v8
	v_pk_fma_f32 v[2:3], v[80:81], v[6:7], v[2:3]
	v_mov_b32_e32 v8, v5
	v_pk_fma_f32 v[2:3], v[78:79], v[8:9], v[2:3]
	s_mov_b32 s3, 0x800000
	v_add_f32_e32 v2, v17, v2
	v_add_f32_e32 v6, v2, v3
	s_waitcnt lgkmcnt(0)
	v_mov_b32_e32 v3, v18
	v_mov_b32_e32 v18, v11
	v_mov_b32_e32 v2, v10
	v_pk_mul_f32 v[4:5], v[84:85], v[18:19]
	s_mov_b32 s5, 0x3f317217
	v_pk_fma_f32 v[2:3], v[88:89], v[2:3], v[4:5]
	v_mov_b32_e32 v4, v12
	v_mov_b32_e32 v5, v20
	v_pk_fma_f32 v[2:3], v[86:87], v[4:5], v[2:3]
	v_mov_b32_e32 v20, v13
	v_pk_fma_f32 v[2:3], v[82:83], v[20:21], v[2:3]
	s_mov_b32 s33, 0x7f800000
	v_add_f32_e32 v2, v6, v2
	v_add_f32_e32 v2, v2, v3
	v_min_f32_e32 v3, 0, v2
	v_mul_f32_e64 v2, |v2|, s4
	v_exp_f32_e32 v2, v2
	ds_read_b128 v[6:9], v1 offset:64
	ds_read_b128 v[10:13], v1 offset:80
	s_mov_b32 s2, 0x3d800000
	s_add_i32 s86, s86, s94
	v_add_f32_e32 v2, 1.0, v2
	v_cmp_gt_f32_e64 s[82:83], s3, v2
	s_nop 1
	v_cndmask_b32_e64 v4, 0, 32, s[82:83]
	v_ldexp_f32 v2, v2, v4
	v_log_f32_e32 v2, v2
	s_nop 0
	v_mul_f32_e32 v4, 0x3f317217, v2
	v_fma_f32 v4, v2, s5, -v4
	v_fmac_f32_e32 v4, 0x3377d1cf, v2
	v_fmac_f32_e32 v4, 0x3f317217, v2
	v_cmp_lt_f32_e64 s[84:85], |v2|, s33
	s_nop 1
	v_cndmask_b32_e64 v2, v2, v4, s[84:85]
	v_cndmask_b32_e64 v4, 0, v208, s[82:83]
	v_sub_f32_e32 v2, v2, v4
	v_sub_f32_e32 v2, v3, v2
	s_waitcnt lgkmcnt(0)
	v_mov_b32_e32 v3, v10
	v_mov_b32_e32 v10, v7
	v_fma_f32 v4, v2, s2, 0
	v_mov_b32_e32 v2, v6
	v_pk_mul_f32 v[6:7], v[76:77], v[10:11]
	s_mov_b32 s2, 0x18870000
	v_pk_fma_f32 v[2:3], v[74:75], v[2:3], v[6:7]
	v_mov_b32_e32 v6, v8
	v_mov_b32_e32 v7, v12
	v_pk_fma_f32 v[2:3], v[80:81], v[6:7], v[2:3]
	v_mov_b32_e32 v12, v9
	v_pk_fma_f32 v[2:3], v[78:79], v[12:13], v[2:3]
	ds_read_b128 v[6:9], v1 offset:96
	ds_read_b128 v[10:13], v1 offset:112
	v_add_f32_e32 v2, v17, v2
	v_add_f32_e32 v5, v2, v3
	s_waitcnt lgkmcnt(1)
	v_mov_b32_e32 v2, v6
	s_waitcnt lgkmcnt(0)
	v_mov_b32_e32 v3, v10
	v_mov_b32_e32 v10, v7
	v_pk_mul_f32 v[6:7], v[84:85], v[10:11]
	s_nop 0
	v_pk_fma_f32 v[2:3], v[88:89], v[2:3], v[6:7]
	v_mov_b32_e32 v6, v8
	v_mov_b32_e32 v7, v12
	v_pk_fma_f32 v[2:3], v[86:87], v[6:7], v[2:3]
	v_mov_b32_e32 v12, v9
	v_pk_fma_f32 v[2:3], v[82:83], v[12:13], v[2:3]
	ds_read_b128 v[6:9], v1 offset:128
	ds_read_b128 v[10:13], v1 offset:144
	v_add_f32_e32 v2, v5, v2
	v_add_f32_e32 v2, v2, v3
	v_min_f32_e32 v3, 0, v2
	v_mul_f32_e64 v2, |v2|, s4
	v_exp_f32_e32 v2, v2
	s_nop 0
	v_add_f32_e32 v2, 1.0, v2
	v_cmp_gt_f32_e64 s[82:83], s3, v2
	s_nop 1
	v_cndmask_b32_e64 v5, 0, 32, s[82:83]
	v_ldexp_f32 v2, v2, v5
	v_log_f32_e32 v2, v2
	s_nop 0
	v_mul_f32_e32 v5, 0x3f317217, v2
	v_fma_f32 v5, v2, s5, -v5
	v_fmac_f32_e32 v5, 0x3377d1cf, v2
	v_fmac_f32_e32 v5, 0x3f317217, v2
	v_cmp_lt_f32_e64 s[84:85], |v2|, s33
	s_nop 1
	v_cndmask_b32_e64 v2, v2, v5, s[84:85]
	v_cndmask_b32_e64 v5, 0, v208, s[82:83]
	v_sub_f32_e32 v2, v2, v5
	v_sub_f32_e32 v2, v3, v2
	s_waitcnt lgkmcnt(0)
	v_mov_b32_e32 v3, v10
	v_mov_b32_e32 v10, v7
	v_fmamk_f32 v5, v2, 0x3d800000, v4
	v_mov_b32_e32 v2, v6
	v_pk_mul_f32 v[6:7], v[76:77], v[10:11]
	s_nop 0
	v_pk_fma_f32 v[2:3], v[74:75], v[2:3], v[6:7]
	v_mov_b32_e32 v6, v8
	v_mov_b32_e32 v7, v12
	v_pk_fma_f32 v[2:3], v[80:81], v[6:7], v[2:3]
	v_mov_b32_e32 v12, v9
	v_pk_fma_f32 v[2:3], v[78:79], v[12:13], v[2:3]
	ds_read_b128 v[6:9], v1 offset:160
	ds_read_b128 v[10:13], v1 offset:176
	v_add_f32_e32 v2, v17, v2
	v_add_f32_e32 v18, v2, v3
	s_waitcnt lgkmcnt(1)
	v_mov_b32_e32 v2, v6
	s_waitcnt lgkmcnt(0)
	v_mov_b32_e32 v3, v10
	v_mov_b32_e32 v10, v7
	v_pk_mul_f32 v[6:7], v[84:85], v[10:11]
	s_nop 0
	v_pk_fma_f32 v[2:3], v[88:89], v[2:3], v[6:7]
	v_mov_b32_e32 v6, v8
	v_mov_b32_e32 v7, v12
	v_pk_fma_f32 v[2:3], v[86:87], v[6:7], v[2:3]
	v_mov_b32_e32 v12, v9
	v_pk_fma_f32 v[2:3], v[82:83], v[12:13], v[2:3]
	s_nop 0
	v_add_f32_e32 v2, v18, v2
	v_add_f32_e32 v2, v2, v3
	v_min_f32_e32 v3, 0, v2
	v_mul_f32_e64 v2, |v2|, s4
	v_exp_f32_e32 v2, v2
	ds_read_b128 v[8:11], v1 offset:192
	ds_read_b128 v[18:21], v1 offset:208
	v_add_f32_e32 v2, 1.0, v2
	v_cmp_gt_f32_e64 s[82:83], s3, v2
	s_nop 1
	v_cndmask_b32_e64 v6, 0, 32, s[82:83]
	v_ldexp_f32 v2, v2, v6
	v_log_f32_e32 v2, v2
	s_nop 0
	v_mul_f32_e32 v6, 0x3f317217, v2
	v_fma_f32 v6, v2, s5, -v6
	v_fmac_f32_e32 v6, 0x3377d1cf, v2
	v_fmac_f32_e32 v6, 0x3f317217, v2
	v_cmp_lt_f32_e64 s[84:85], |v2|, s33
	s_nop 1
	v_cndmask_b32_e64 v2, v2, v6, s[84:85]
	v_cndmask_b32_e64 v6, 0, v208, s[82:83]
	v_sub_f32_e32 v2, v2, v6
	v_sub_f32_e32 v2, v3, v2
	s_waitcnt lgkmcnt(0)
; #define LAS __attribute__((address_space(3)))
; __device__ __forceinline__ void gla_prep(LAS unsigned char* lds, const bf16_t* QK, const float* gz, const float* Wg, const float* bias,
;                                          bf16_t* QPimg, bf16_t* KTimg, bf16_t* Aimg, float* dec, int G) {
;     ...
;         float bb[64]; float bs = 0.f;
; #pragma unroll
;         for (int t = 0; t < 64; ++t) {
;             float x = bi;
; #pragma unroll
;             for (int q4 = 0; q4 < 4; ++q4) { const f32x4 g4 = *(const LAS f32x4*)(gzs + t * 16 + q4 * 4); x += g4.x * wg[4 * q4] + g4.y * wg[4 * q4 + 1] + g4.z * wg[4 * q4 + 2] + g4.w * wg[4 * q4 + 3]; }
;             float ls = (fminf(x, 0.f) - __logf(1.f + __expf(-fabsf(x)))) * (1.f / 16.f);
;             if (t >= ntok) ls = 0.f;
;             bs += ls; bb[t] = bs;
	v_mov_b32_e32 v3, v18
	v_mov_b32_e32 v18, v9
	v_fmamk_f32 v6, v2, 0x3d800000, v5
	v_mov_b32_e32 v2, v8
	v_pk_mul_f32 v[8:9], v[76:77], v[18:19]
	s_nop 0
	v_pk_fma_f32 v[2:3], v[74:75], v[2:3], v[8:9]
	v_mov_b32_e32 v8, v10
	v_mov_b32_e32 v9, v20
	v_pk_fma_f32 v[2:3], v[80:81], v[8:9], v[2:3]
	v_mov_b32_e32 v20, v11
	v_pk_fma_f32 v[2:3], v[78:79], v[20:21], v[2:3]
	ds_read_b128 v[8:11], v1 offset:224
	ds_read_b128 v[18:21], v1 offset:240
	v_add_f32_e32 v2, v17, v2
	v_add_f32_e32 v7, v2, v3
	s_waitcnt lgkmcnt(1)
	v_mov_b32_e32 v2, v8
	s_waitcnt lgkmcnt(0)
	v_mov_b32_e32 v3, v18
	v_mov_b32_e32 v18, v9
	v_pk_mul_f32 v[8:9], v[84:85], v[18:19]
	s_nop 0
	v_pk_fma_f32 v[2:3], v[88:89], v[2:3], v[8:9]
	v_mov_b32_e32 v8, v10
	v_mov_b32_e32 v9, v20
	v_pk_fma_f32 v[2:3], v[86:87], v[8:9], v[2:3]
	v_mov_b32_e32 v20, v11
	v_pk_fma_f32 v[2:3], v[82:83], v[20:21], v[2:3]
	ds_read_b128 v[8:11], v1 offset:256
	ds_read_b128 v[18:21], v1 offset:272
	v_add_f32_e32 v2, v7, v2
	v_add_f32_e32 v2, v2, v3
	v_min_f32_e32 v3, 0, v2
	v_mul_f32_e64 v2, |v2|, s4
	v_exp_f32_e32 v2, v2
	s_nop 0
	v_add_f32_e32 v2, 1.0, v2
	v_cmp_gt_f32_e64 s[82:83], s3, v2
	s_nop 1
	v_cndmask_b32_e64 v7, 0, 32, s[82:83]
	v_ldexp_f32 v2, v2, v7
	v_log_f32_e32 v2, v2
	s_nop 0
	v_mul_f32_e32 v7, 0x3f317217, v2
	v_fma_f32 v7, v2, s5, -v7
	v_fmac_f32_e32 v7, 0x3377d1cf, v2
	v_fmac_f32_e32 v7, 0x3f317217, v2
	v_cmp_lt_f32_e64 s[84:85], |v2|, s33
	s_nop 1
	v_cndmask_b32_e64 v2, v2, v7, s[84:85]
	v_cndmask_b32_e64 v7, 0, v208, s[82:83]
	v_sub_f32_e32 v2, v2, v7
	v_sub_f32_e32 v2, v3, v2
	s_waitcnt lgkmcnt(0)
	v_mov_b32_e32 v3, v18
	v_mov_b32_e32 v18, v9
	v_fmamk_f32 v7, v2, 0x3d800000, v6
	v_mov_b32_e32 v2, v8
	v_pk_mul_f32 v[8:9], v[76:77], v[18:19]
	s_nop 0
	v_pk_fma_f32 v[2:3], v[74:75], v[2:3], v[8:9]
	v_mov_b32_e32 v8, v10
	v_mov_b32_e32 v9, v20
	v_pk_fma_f32 v[2:3], v[80:81], v[8:9], v[2:3]
	v_mov_b32_e32 v20, v11
	v_pk_fma_f32 v[2:3], v[78:79], v[20:21], v[2:3]
	ds_read_b128 v[8:11], v1 offset:288
	ds_read_b128 v[18:21], v1 offset:304
	v_add_f32_e32 v2, v17, v2
	v_add_f32_e32 v12, v2, v3
	s_waitcnt lgkmcnt(1)
	v_mov_b32_e32 v2, v8
	s_waitcnt lgkmcnt(0)
	v_mov_b32_e32 v3, v18
	v_mov_b32_e32 v18, v9
	v_pk_mul_f32 v[8:9], v[84:85], v[18:19]
	s_nop 0
	v_pk_fma_f32 v[2:3], v[88:89], v[2:3], v[8:9]
	v_mov_b32_e32 v8, v10
	v_mov_b32_e32 v9, v20
	v_pk_fma_f32 v[2:3], v[86:87], v[8:9], v[2:3]
	v_mov_b32_e32 v20, v11
	v_pk_fma_f32 v[2:3], v[82:83], v[20:21], v[2:3]
	s_nop 0
	v_add_f32_e32 v2, v12, v2
	v_add_f32_e32 v2, v2, v3
	v_min_f32_e32 v3, 0, v2
	v_mul_f32_e64 v2, |v2|, s4
	v_exp_f32_e32 v2, v2
	ds_read_b128 v[10:13], v1 offset:320
	ds_read_b128 v[18:21], v1 offset:336
	v_add_f32_e32 v2, 1.0, v2
	v_cmp_gt_f32_e64 s[82:83], s3, v2
	s_nop 1
	v_cndmask_b32_e64 v8, 0, 32, s[82:83]
	v_ldexp_f32 v2, v2, v8
	v_log_f32_e32 v2, v2
	s_nop 0
	v_mul_f32_e32 v8, 0x3f317217, v2
	v_fma_f32 v8, v2, s5, -v8
	v_fmac_f32_e32 v8, 0x3377d1cf, v2
	v_fmac_f32_e32 v8, 0x3f317217, v2
	v_cmp_lt_f32_e64 s[84:85], |v2|, s33
	s_nop 1
	v_cndmask_b32_e64 v2, v2, v8, s[84:85]
	v_cndmask_b32_e64 v8, 0, v208, s[82:83]
	v_sub_f32_e32 v2, v2, v8
	v_sub_f32_e32 v2, v3, v2
	s_waitcnt lgkmcnt(0)
	v_mov_b32_e32 v3, v18
	v_mov_b32_e32 v18, v11
	v_fmamk_f32 v8, v2, 0x3d800000, v7
	v_mov_b32_e32 v2, v10
	v_pk_mul_f32 v[10:11], v[76:77], v[18:19]
	s_nop 0
	v_pk_fma_f32 v[2:3], v[74:75], v[2:3], v[10:11]
	v_mov_b32_e32 v10, v12
	v_mov_b32_e32 v11, v20
	v_pk_fma_f32 v[2:3], v[80:81], v[10:11], v[2:3]
	v_mov_b32_e32 v20, v13
	v_pk_fma_f32 v[2:3], v[78:79], v[20:21], v[2:3]
	ds_read_b128 v[10:13], v1 offset:352
	ds_read_b128 v[18:21], v1 offset:368
	v_add_f32_e32 v2, v17, v2
	v_add_f32_e32 v9, v2, v3
	s_waitcnt lgkmcnt(1)
	v_mov_b32_e32 v2, v10
	s_waitcnt lgkmcnt(0)
	v_mov_b32_e32 v3, v18
	v_mov_b32_e32 v18, v11
	v_pk_mul_f32 v[10:11], v[84:85], v[18:19]
	s_nop 0
	v_pk_fma_f32 v[2:3], v[88:89], v[2:3], v[10:11]
	v_mov_b32_e32 v10, v12
	v_mov_b32_e32 v11, v20
	v_pk_fma_f32 v[2:3], v[86:87], v[10:11], v[2:3]
	v_mov_b32_e32 v20, v13
	v_pk_fma_f32 v[2:3], v[82:83], v[20:21], v[2:3]
	ds_read_b128 v[18:21], v1 offset:384
	ds_read_b128 v[22:25], v1 offset:400
	v_add_f32_e32 v2, v9, v2
	v_add_f32_e32 v2, v2, v3
	v_min_f32_e32 v3, 0, v2
	v_mul_f32_e64 v2, |v2|, s4
	v_exp_f32_e32 v2, v2
	s_nop 0
	v_add_f32_e32 v2, 1.0, v2
	v_cmp_gt_f32_e64 s[82:83], s3, v2
	s_nop 1
	v_cndmask_b32_e64 v9, 0, 32, s[82:83]
	v_ldexp_f32 v2, v2, v9
	v_log_f32_e32 v2, v2
	s_nop 0
	v_mul_f32_e32 v9, 0x3f317217, v2
	v_fma_f32 v9, v2, s5, -v9
	v_fmac_f32_e32 v9, 0x3377d1cf, v2
	v_fmac_f32_e32 v9, 0x3f317217, v2
	v_cmp_lt_f32_e64 s[84:85], |v2|, s33
	s_nop 1
	v_cndmask_b32_e64 v2, v2, v9, s[84:85]
	v_cndmask_b32_e64 v9, 0, v208, s[82:83]
	v_sub_f32_e32 v2, v2, v9
	v_sub_f32_e32 v2, v3, v2
	s_waitcnt lgkmcnt(0)
	v_mov_b32_e32 v3, v22
	v_mov_b32_e32 v22, v19
	v_fmamk_f32 v10, v2, 0x3d800000, v8
	v_mov_b32_e32 v2, v18
	v_pk_mul_f32 v[12:13], v[76:77], v[22:23]
	s_nop 0
	v_pk_fma_f32 v[2:3], v[74:75], v[2:3], v[12:13]
	v_mov_b32_e32 v12, v20
	v_mov_b32_e32 v13, v24
	v_pk_fma_f32 v[2:3], v[80:81], v[12:13], v[2:3]
	v_mov_b32_e32 v24, v21
	v_pk_fma_f32 v[2:3], v[78:79], v[24:25], v[2:3]
	ds_read_b128 v[18:21], v1 offset:416
	ds_read_b128 v[22:25], v1 offset:432
	v_add_f32_e32 v2, v17, v2
	v_add_f32_e32 v9, v2, v3
	s_waitcnt lgkmcnt(1)
	v_mov_b32_e32 v2, v18
	s_waitcnt lgkmcnt(0)
; #define LAS __attribute__((address_space(3)))
; __device__ __forceinline__ void gla_prep(LAS unsigned char* lds, const bf16_t* QK, const float* gz, const float* Wg, const float* bias,
;                                          bf16_t* QPimg, bf16_t* KTimg, bf16_t* Aimg, float* dec, int G) {
;     ...
;         float bb[64]; float bs = 0.f;
; #pragma unroll
;         for (int t = 0; t < 64; ++t) {
;             float x = bi;
; #pragma unroll
;             for (int q4 = 0; q4 < 4; ++q4) { const f32x4 g4 = *(const LAS f32x4*)(gzs + t * 16 + q4 * 4); x += g4.x * wg[4 * q4] + g4.y * wg[4 * q4 + 1] + g4.z * wg[4 * q4 + 2] + g4.w * wg[4 * q4 + 3]; }
;             float ls = (fminf(x, 0.f) - __logf(1.f + __expf(-fabsf(x)))) * (1.f / 16.f);
;             if (t >= ntok) ls = 0.f;
;             bs += ls; bb[t] = bs;
	v_mov_b32_e32 v3, v22
	v_mov_b32_e32 v22, v19
	v_pk_mul_f32 v[12:13], v[84:85], v[22:23]
	s_nop 0
	v_pk_fma_f32 v[2:3], v[88:89], v[2:3], v[12:13]
	v_mov_b32_e32 v12, v20
	v_mov_b32_e32 v13, v24
	v_pk_fma_f32 v[2:3], v[86:87], v[12:13], v[2:3]
	v_mov_b32_e32 v24, v21
	v_pk_fma_f32 v[2:3], v[82:83], v[24:25], v[2:3]
	ds_read_b128 v[18:21], v1 offset:448
	ds_read_b128 v[22:25], v1 offset:464
	v_add_f32_e32 v2, v9, v2
	v_add_f32_e32 v2, v2, v3
	v_min_f32_e32 v3, 0, v2
	v_mul_f32_e64 v2, |v2|, s4
	v_exp_f32_e32 v2, v2
	s_nop 0
	v_add_f32_e32 v2, 1.0, v2
	v_cmp_gt_f32_e64 s[82:83], s3, v2
	s_nop 1
	v_cndmask_b32_e64 v9, 0, 32, s[82:83]
	v_ldexp_f32 v2, v2, v9
	v_log_f32_e32 v2, v2
	s_nop 0
	v_mul_f32_e32 v9, 0x3f317217, v2
	v_fma_f32 v9, v2, s5, -v9
	v_fmac_f32_e32 v9, 0x3377d1cf, v2
	v_fmac_f32_e32 v9, 0x3f317217, v2
	v_cmp_lt_f32_e64 s[84:85], |v2|, s33
	s_nop 1
	v_cndmask_b32_e64 v2, v2, v9, s[84:85]
	v_cndmask_b32_e64 v9, 0, v208, s[82:83]
	v_sub_f32_e32 v2, v2, v9
	v_sub_f32_e32 v2, v3, v2
	s_waitcnt lgkmcnt(0)
	v_mov_b32_e32 v3, v22
	v_mov_b32_e32 v22, v19
	v_fmamk_f32 v11, v2, 0x3d800000, v10
	v_mov_b32_e32 v2, v18
	v_pk_mul_f32 v[12:13], v[76:77], v[22:23]
	s_nop 0
	v_pk_fma_f32 v[2:3], v[74:75], v[2:3], v[12:13]
	v_mov_b32_e32 v12, v20
	v_mov_b32_e32 v13, v24
	v_pk_fma_f32 v[2:3], v[80:81], v[12:13], v[2:3]
	v_mov_b32_e32 v24, v21
	v_pk_fma_f32 v[2:3], v[78:79], v[24:25], v[2:3]
	ds_read_b128 v[18:21], v1 offset:480
	ds_read_b128 v[22:25], v1 offset:496
	v_add_f32_e32 v2, v17, v2
	v_add_f32_e32 v9, v2, v3
	s_waitcnt lgkmcnt(1)
	v_mov_b32_e32 v2, v18
	s_waitcnt lgkmcnt(0)
	v_mov_b32_e32 v3, v22
	v_mov_b32_e32 v22, v19
	v_pk_mul_f32 v[12:13], v[84:85], v[22:23]
	s_nop 0
	v_pk_fma_f32 v[2:3], v[88:89], v[2:3], v[12:13]
	v_mov_b32_e32 v12, v20
	v_mov_b32_e32 v13, v24
	v_pk_fma_f32 v[2:3], v[86:87], v[12:13], v[2:3]
	v_mov_b32_e32 v24, v21
	v_pk_fma_f32 v[2:3], v[82:83], v[24:25], v[2:3]
	ds_read_b128 v[18:21], v1 offset:512
	ds_read_b128 v[22:25], v1 offset:528
	v_add_f32_e32 v2, v9, v2
	v_add_f32_e32 v2, v2, v3
	v_min_f32_e32 v3, 0, v2
	v_mul_f32_e64 v2, |v2|, s4
	v_exp_f32_e32 v2, v2
	s_nop 0
	v_add_f32_e32 v2, 1.0, v2
	v_cmp_gt_f32_e64 s[82:83], s3, v2
	s_nop 1
	v_cndmask_b32_e64 v9, 0, 32, s[82:83]
	v_ldexp_f32 v2, v2, v9
	v_log_f32_e32 v2, v2
	s_nop 0
	v_mul_f32_e32 v9, 0x3f317217, v2
	v_fma_f32 v9, v2, s5, -v9
	v_fmac_f32_e32 v9, 0x3377d1cf, v2
	v_fmac_f32_e32 v9, 0x3f317217, v2
	v_cmp_lt_f32_e64 s[84:85], |v2|, s33
	s_nop 1
	v_cndmask_b32_e64 v2, v2, v9, s[84:85]
	v_cndmask_b32_e64 v9, 0, v208, s[82:83]
	v_sub_f32_e32 v2, v2, v9
	v_sub_f32_e32 v2, v3, v2
	s_waitcnt lgkmcnt(0)
	v_mov_b32_e32 v3, v22
	v_mov_b32_e32 v22, v19
	v_fmamk_f32 v9, v2, 0x3d800000, v11
	v_mov_b32_e32 v2, v18
	v_pk_mul_f32 v[12:13], v[76:77], v[22:23]
	s_nop 0
	v_pk_fma_f32 v[2:3], v[74:75], v[2:3], v[12:13]
	v_mov_b32_e32 v12, v20
	v_mov_b32_e32 v13, v24
	v_pk_fma_f32 v[2:3], v[80:81], v[12:13], v[2:3]
	v_mov_b32_e32 v24, v21
	v_pk_fma_f32 v[2:3], v[78:79], v[24:25], v[2:3]
	ds_read_b128 v[18:21], v1 offset:544
	ds_read_b128 v[22:25], v1 offset:560
	v_add_f32_e32 v2, v17, v2
	v_add_f32_e32 v26, v2, v3
	s_waitcnt lgkmcnt(1)
	v_mov_b32_e32 v2, v18
	s_waitcnt lgkmcnt(0)
	v_mov_b32_e32 v3, v22
	v_mov_b32_e32 v22, v19
	v_pk_mul_f32 v[12:13], v[84:85], v[22:23]
	s_nop 0
	v_pk_fma_f32 v[2:3], v[88:89], v[2:3], v[12:13]
	v_mov_b32_e32 v12, v20
	v_mov_b32_e32 v13, v24
	v_pk_fma_f32 v[2:3], v[86:87], v[12:13], v[2:3]
	v_mov_b32_e32 v24, v21
	v_pk_fma_f32 v[2:3], v[82:83], v[24:25], v[2:3]
	ds_read_b128 v[18:21], v1 offset:576
	ds_read_b128 v[22:25], v1 offset:592
	v_add_f32_e32 v2, v26, v2
	v_add_f32_e32 v2, v2, v3
	v_min_f32_e32 v3, 0, v2
	v_mul_f32_e64 v2, |v2|, s4
	v_exp_f32_e32 v2, v2
	s_nop 0
	v_add_f32_e32 v2, 1.0, v2
	v_cmp_gt_f32_e64 s[82:83], s3, v2
	s_nop 1
	v_cndmask_b32_e64 v12, 0, 32, s[82:83]
	v_ldexp_f32 v2, v2, v12
	v_log_f32_e32 v2, v2
	s_nop 0
	v_mul_f32_e32 v12, 0x3f317217, v2
	v_fma_f32 v12, v2, s5, -v12
	v_fmac_f32_e32 v12, 0x3377d1cf, v2
	v_fmac_f32_e32 v12, 0x3f317217, v2
	v_cmp_lt_f32_e64 s[84:85], |v2|, s33
	s_nop 1
	v_cndmask_b32_e64 v2, v2, v12, s[84:85]
	v_cndmask_b32_e64 v12, 0, v208, s[82:83]
	v_sub_f32_e32 v2, v2, v12
	v_sub_f32_e32 v2, v3, v2
	s_waitcnt lgkmcnt(0)
	v_mov_b32_e32 v3, v22
	v_mov_b32_e32 v22, v19
	v_fmamk_f32 v12, v2, 0x3d800000, v9
	v_mov_b32_e32 v2, v18
	v_pk_mul_f32 v[18:19], v[76:77], v[22:23]
	s_nop 0
	v_pk_fma_f32 v[2:3], v[74:75], v[2:3], v[18:19]
	v_mov_b32_e32 v18, v20
	v_mov_b32_e32 v19, v24
	v_pk_fma_f32 v[2:3], v[80:81], v[18:19], v[2:3]
	v_mov_b32_e32 v24, v21
	v_pk_fma_f32 v[2:3], v[78:79], v[24:25], v[2:3]
	ds_read_b128 v[18:21], v1 offset:608
	ds_read_b128 v[22:25], v1 offset:624
	v_add_f32_e32 v2, v17, v2
	v_add_f32_e32 v13, v2, v3
	s_waitcnt lgkmcnt(1)
	v_mov_b32_e32 v2, v18
	s_waitcnt lgkmcnt(0)
	v_mov_b32_e32 v3, v22
	v_mov_b32_e32 v22, v19
	v_pk_mul_f32 v[18:19], v[84:85], v[22:23]
	s_nop 0
	v_pk_fma_f32 v[2:3], v[88:89], v[2:3], v[18:19]
	v_mov_b32_e32 v18, v20
	v_mov_b32_e32 v19, v24
	v_pk_fma_f32 v[2:3], v[86:87], v[18:19], v[2:3]
	v_mov_b32_e32 v24, v21
	v_pk_fma_f32 v[2:3], v[82:83], v[24:25], v[2:3]
	ds_read_b128 v[18:21], v1 offset:640
	ds_read_b128 v[22:25], v1 offset:656
	v_add_f32_e32 v2, v13, v2
	v_add_f32_e32 v2, v2, v3
	v_min_f32_e32 v3, 0, v2
	v_mul_f32_e64 v2, |v2|, s4
	v_exp_f32_e32 v2, v2
	s_nop 0
	v_add_f32_e32 v2, 1.0, v2
	v_cmp_gt_f32_e64 s[82:83], s3, v2
	s_nop 1
	v_cndmask_b32_e64 v13, 0, 32, s[82:83]
	v_ldexp_f32 v2, v2, v13
	v_log_f32_e32 v2, v2
	s_nop 0
	v_mul_f32_e32 v13, 0x3f317217, v2
	v_fma_f32 v13, v2, s5, -v13
	v_fmac_f32_e32 v13, 0x3377d1cf, v2
	v_fmac_f32_e32 v13, 0x3f317217, v2
	v_cmp_lt_f32_e64 s[84:85], |v2|, s33
	s_nop 1
	v_cndmask_b32_e64 v2, v2, v13, s[84:85]
	v_cndmask_b32_e64 v13, 0, v208, s[82:83]
	v_sub_f32_e32 v2, v2, v13
	v_sub_f32_e32 v2, v3, v2
	s_waitcnt lgkmcnt(0)
; #define LAS __attribute__((address_space(3)))
; __device__ __forceinline__ void gla_prep(LAS unsigned char* lds, const bf16_t* QK, const float* gz, const float* Wg, const float* bias,
;                                          bf16_t* QPimg, bf16_t* KTimg, bf16_t* Aimg, float* dec, int G) {
;     ...
;         float bb[64]; float bs = 0.f;
; #pragma unroll
;         for (int t = 0; t < 64; ++t) {
;             float x = bi;
; #pragma unroll
;             for (int q4 = 0; q4 < 4; ++q4) { const f32x4 g4 = *(const LAS f32x4*)(gzs + t * 16 + q4 * 4); x += g4.x * wg[4 * q4] + g4.y * wg[4 * q4 + 1] + g4.z * wg[4 * q4 + 2] + g4.w * wg[4 * q4 + 3]; }
;             float ls = (fminf(x, 0.f) - __logf(1.f + __expf(-fabsf(x)))) * (1.f / 16.f);
;             if (t >= ntok) ls = 0.f;
;             bs += ls; bb[t] = bs;
	v_mov_b32_e32 v3, v22
	v_mov_b32_e32 v22, v19
	v_fmamk_f32 v13, v2, 0x3d800000, v12
	v_mov_b32_e32 v2, v18
	v_pk_mul_f32 v[18:19], v[76:77], v[22:23]
	s_nop 0
	v_pk_fma_f32 v[2:3], v[74:75], v[2:3], v[18:19]
	v_mov_b32_e32 v18, v20
	v_mov_b32_e32 v19, v24
	v_pk_fma_f32 v[2:3], v[80:81], v[18:19], v[2:3]
	v_mov_b32_e32 v24, v21
	v_pk_fma_f32 v[2:3], v[78:79], v[24:25], v[2:3]
	ds_read_b128 v[18:21], v1 offset:672
	ds_read_b128 v[22:25], v1 offset:688
	v_add_f32_e32 v2, v17, v2
	v_add_f32_e32 v26, v2, v3
	s_waitcnt lgkmcnt(1)
	v_mov_b32_e32 v2, v18
	s_waitcnt lgkmcnt(0)
	v_mov_b32_e32 v3, v22
	v_mov_b32_e32 v22, v19
	v_pk_mul_f32 v[18:19], v[84:85], v[22:23]
	s_nop 0
	v_pk_fma_f32 v[2:3], v[88:89], v[2:3], v[18:19]
	v_mov_b32_e32 v18, v20
	v_mov_b32_e32 v19, v24
	v_pk_fma_f32 v[2:3], v[86:87], v[18:19], v[2:3]
	v_mov_b32_e32 v24, v21
	v_pk_fma_f32 v[2:3], v[82:83], v[24:25], v[2:3]
	s_nop 0
	v_add_f32_e32 v2, v26, v2
	v_add_f32_e32 v2, v2, v3
	v_min_f32_e32 v3, 0, v2
	v_mul_f32_e64 v2, |v2|, s4
	v_exp_f32_e32 v2, v2
	ds_read_b128 v[20:23], v1 offset:704
	ds_read_b128 v[24:27], v1 offset:720
	v_add_f32_e32 v2, 1.0, v2
	v_cmp_gt_f32_e64 s[82:83], s3, v2
	s_nop 1
	v_cndmask_b32_e64 v18, 0, 32, s[82:83]
	v_ldexp_f32 v2, v2, v18
	v_log_f32_e32 v2, v2
	s_nop 0
	v_mul_f32_e32 v18, 0x3f317217, v2
	v_fma_f32 v18, v2, s5, -v18
	v_fmac_f32_e32 v18, 0x3377d1cf, v2
	v_fmac_f32_e32 v18, 0x3f317217, v2
	v_cmp_lt_f32_e64 s[84:85], |v2|, s33
	s_nop 1
	v_cndmask_b32_e64 v2, v2, v18, s[84:85]
	v_cndmask_b32_e64 v18, 0, v208, s[82:83]
	v_sub_f32_e32 v2, v2, v18
	v_sub_f32_e32 v2, v3, v2
	s_waitcnt lgkmcnt(0)
	v_mov_b32_e32 v3, v24
	v_mov_b32_e32 v24, v21
	v_fmamk_f32 v18, v2, 0x3d800000, v13
	v_mov_b32_e32 v2, v20
	v_pk_mul_f32 v[20:21], v[76:77], v[24:25]
	s_nop 0
	v_pk_fma_f32 v[2:3], v[74:75], v[2:3], v[20:21]
	v_mov_b32_e32 v20, v22
	v_mov_b32_e32 v21, v26
	v_pk_fma_f32 v[2:3], v[80:81], v[20:21], v[2:3]
	v_mov_b32_e32 v26, v23
	v_pk_fma_f32 v[2:3], v[78:79], v[26:27], v[2:3]
	ds_read_b128 v[20:23], v1 offset:736
	ds_read_b128 v[24:27], v1 offset:752
	v_add_f32_e32 v2, v17, v2
	v_add_f32_e32 v19, v2, v3
	s_waitcnt lgkmcnt(1)
	v_mov_b32_e32 v2, v20
	s_waitcnt lgkmcnt(0)
	v_mov_b32_e32 v3, v24
	v_mov_b32_e32 v24, v21
	v_pk_mul_f32 v[20:21], v[84:85], v[24:25]
	s_nop 0
	v_pk_fma_f32 v[2:3], v[88:89], v[2:3], v[20:21]
	v_mov_b32_e32 v20, v22
	v_mov_b32_e32 v21, v26
	v_pk_fma_f32 v[2:3], v[86:87], v[20:21], v[2:3]
	v_mov_b32_e32 v26, v23
	v_pk_fma_f32 v[2:3], v[82:83], v[26:27], v[2:3]
	ds_read_b128 v[20:23], v1 offset:768
	ds_read_b128 v[24:27], v1 offset:784
	v_add_f32_e32 v2, v19, v2
	v_add_f32_e32 v2, v2, v3
	v_min_f32_e32 v3, 0, v2
	v_mul_f32_e64 v2, |v2|, s4
	v_exp_f32_e32 v2, v2
	s_nop 0
	v_add_f32_e32 v2, 1.0, v2
	v_cmp_gt_f32_e64 s[82:83], s3, v2
	s_nop 1
	v_cndmask_b32_e64 v19, 0, 32, s[82:83]
	v_ldexp_f32 v2, v2, v19
	v_log_f32_e32 v2, v2
	s_nop 0
	v_mul_f32_e32 v19, 0x3f317217, v2
	v_fma_f32 v19, v2, s5, -v19
	v_fmac_f32_e32 v19, 0x3377d1cf, v2
	v_fmac_f32_e32 v19, 0x3f317217, v2
	v_cmp_lt_f32_e64 s[84:85], |v2|, s33
	s_nop 1
	v_cndmask_b32_e64 v2, v2, v19, s[84:85]
	v_cndmask_b32_e64 v19, 0, v208, s[82:83]
	v_sub_f32_e32 v2, v2, v19
	v_sub_f32_e32 v2, v3, v2
	s_waitcnt lgkmcnt(0)
	v_mov_b32_e32 v3, v24
	v_mov_b32_e32 v24, v21
	v_fmamk_f32 v19, v2, 0x3d800000, v18
	v_mov_b32_e32 v2, v20
	v_pk_mul_f32 v[20:21], v[76:77], v[24:25]
	s_nop 0
	v_pk_fma_f32 v[2:3], v[74:75], v[2:3], v[20:21]
	v_mov_b32_e32 v20, v22
	v_mov_b32_e32 v21, v26
	v_pk_fma_f32 v[2:3], v[80:81], v[20:21], v[2:3]
	v_mov_b32_e32 v26, v23
	v_pk_fma_f32 v[2:3], v[78:79], v[26:27], v[2:3]
	ds_read_b128 v[20:23], v1 offset:800
	ds_read_b128 v[24:27], v1 offset:816
	v_add_f32_e32 v2, v17, v2
	v_add_f32_e32 v28, v2, v3
	s_waitcnt lgkmcnt(1)
	v_mov_b32_e32 v2, v20
	s_waitcnt lgkmcnt(0)
	v_mov_b32_e32 v3, v24
	v_mov_b32_e32 v24, v21
	v_pk_mul_f32 v[20:21], v[84:85], v[24:25]
	s_nop 0
	v_pk_fma_f32 v[2:3], v[88:89], v[2:3], v[20:21]
	v_mov_b32_e32 v20, v22
	v_mov_b32_e32 v21, v26
	v_pk_fma_f32 v[2:3], v[86:87], v[20:21], v[2:3]
	v_mov_b32_e32 v26, v23
	v_pk_fma_f32 v[2:3], v[82:83], v[26:27], v[2:3]
	s_nop 0
	v_add_f32_e32 v2, v28, v2
	v_add_f32_e32 v2, v2, v3
	v_min_f32_e32 v3, 0, v2
	v_mul_f32_e64 v2, |v2|, s4
	v_exp_f32_e32 v2, v2
	ds_read_b128 v[22:25], v1 offset:832
	ds_read_b128 v[26:29], v1 offset:848
	v_add_f32_e32 v2, 1.0, v2
	v_cmp_gt_f32_e64 s[82:83], s3, v2
	s_nop 1
	v_cndmask_b32_e64 v20, 0, 32, s[82:83]
	v_ldexp_f32 v2, v2, v20
	v_log_f32_e32 v2, v2
	s_nop 0
	v_mul_f32_e32 v20, 0x3f317217, v2
	v_fma_f32 v20, v2, s5, -v20
	v_fmac_f32_e32 v20, 0x3377d1cf, v2
	v_fmac_f32_e32 v20, 0x3f317217, v2
	v_cmp_lt_f32_e64 s[84:85], |v2|, s33
	s_nop 1
	v_cndmask_b32_e64 v2, v2, v20, s[84:85]
	v_cndmask_b32_e64 v20, 0, v208, s[82:83]
	v_sub_f32_e32 v2, v2, v20
	v_sub_f32_e32 v2, v3, v2
	s_waitcnt lgkmcnt(0)
	v_mov_b32_e32 v3, v26
	v_mov_b32_e32 v26, v23
	v_fmamk_f32 v20, v2, 0x3d800000, v19
	v_mov_b32_e32 v2, v22
	v_pk_mul_f32 v[22:23], v[76:77], v[26:27]
	s_nop 0
	v_pk_fma_f32 v[2:3], v[74:75], v[2:3], v[22:23]
	v_mov_b32_e32 v22, v24
	v_mov_b32_e32 v23, v28
	v_pk_fma_f32 v[2:3], v[80:81], v[22:23], v[2:3]
	v_mov_b32_e32 v28, v25
	v_pk_fma_f32 v[2:3], v[78:79], v[28:29], v[2:3]
	ds_read_b128 v[22:25], v1 offset:864
	ds_read_b128 v[26:29], v1 offset:880
	v_add_f32_e32 v2, v17, v2
	v_add_f32_e32 v21, v2, v3
	s_waitcnt lgkmcnt(1)
	v_mov_b32_e32 v2, v22
	s_waitcnt lgkmcnt(0)
; #define LAS __attribute__((address_space(3)))
; __device__ __forceinline__ void gla_prep(LAS unsigned char* lds, const bf16_t* QK, const float* gz, const float* Wg, const float* bias,
;                                          bf16_t* QPimg, bf16_t* KTimg, bf16_t* Aimg, float* dec, int G) {
;     ...
;         float bb[64]; float bs = 0.f;
; #pragma unroll
;         for (int t = 0; t < 64; ++t) {
;             float x = bi;
; #pragma unroll
;             for (int q4 = 0; q4 < 4; ++q4) { const f32x4 g4 = *(const LAS f32x4*)(gzs + t * 16 + q4 * 4); x += g4.x * wg[4 * q4] + g4.y * wg[4 * q4 + 1] + g4.z * wg[4 * q4 + 2] + g4.w * wg[4 * q4 + 3]; }
;             float ls = (fminf(x, 0.f) - __logf(1.f + __expf(-fabsf(x)))) * (1.f / 16.f);
;             if (t >= ntok) ls = 0.f;
;             bs += ls; bb[t] = bs;
	v_mov_b32_e32 v3, v26
	v_mov_b32_e32 v26, v23
	v_pk_mul_f32 v[22:23], v[84:85], v[26:27]
	s_nop 0
	v_pk_fma_f32 v[2:3], v[88:89], v[2:3], v[22:23]
	v_mov_b32_e32 v22, v24
	v_mov_b32_e32 v23, v28
	v_pk_fma_f32 v[2:3], v[86:87], v[22:23], v[2:3]
	v_mov_b32_e32 v28, v25
	v_pk_fma_f32 v[2:3], v[82:83], v[28:29], v[2:3]
	ds_read_b128 v[24:27], v1 offset:896
	ds_read_b128 v[28:31], v1 offset:912
	v_add_f32_e32 v2, v21, v2
	v_add_f32_e32 v2, v2, v3
	v_min_f32_e32 v3, 0, v2
	v_mul_f32_e64 v2, |v2|, s4
	v_exp_f32_e32 v2, v2
	s_nop 0
	v_add_f32_e32 v2, 1.0, v2
	v_cmp_gt_f32_e64 s[82:83], s3, v2
	s_nop 1
	v_cndmask_b32_e64 v21, 0, 32, s[82:83]
	v_ldexp_f32 v2, v2, v21
	v_log_f32_e32 v2, v2
	s_nop 0
	v_mul_f32_e32 v21, 0x3f317217, v2
	v_fma_f32 v21, v2, s5, -v21
	v_fmac_f32_e32 v21, 0x3377d1cf, v2
	v_fmac_f32_e32 v21, 0x3f317217, v2
	v_cmp_lt_f32_e64 s[84:85], |v2|, s33
	s_nop 1
	v_cndmask_b32_e64 v2, v2, v21, s[84:85]
	v_cndmask_b32_e64 v21, 0, v208, s[82:83]
	v_sub_f32_e32 v2, v2, v21
	v_sub_f32_e32 v2, v3, v2
	s_waitcnt lgkmcnt(0)
	v_mov_b32_e32 v3, v28
	v_mov_b32_e32 v28, v25
	v_fmamk_f32 v22, v2, 0x3d800000, v20
	v_mov_b32_e32 v2, v24
	v_pk_mul_f32 v[24:25], v[76:77], v[28:29]
	s_nop 0
	v_pk_fma_f32 v[2:3], v[74:75], v[2:3], v[24:25]
	v_mov_b32_e32 v24, v26
	v_mov_b32_e32 v25, v30
	v_pk_fma_f32 v[2:3], v[80:81], v[24:25], v[2:3]
	v_mov_b32_e32 v30, v27
	v_pk_fma_f32 v[2:3], v[78:79], v[30:31], v[2:3]
	ds_read_b128 v[24:27], v1 offset:928
	ds_read_b128 v[28:31], v1 offset:944
	v_add_f32_e32 v2, v17, v2
	v_add_f32_e32 v21, v2, v3
	s_waitcnt lgkmcnt(1)
	v_mov_b32_e32 v2, v24
	s_waitcnt lgkmcnt(0)
	v_mov_b32_e32 v3, v28
	v_mov_b32_e32 v28, v25
	v_pk_mul_f32 v[24:25], v[84:85], v[28:29]
	s_nop 0
	v_pk_fma_f32 v[2:3], v[88:89], v[2:3], v[24:25]
	v_mov_b32_e32 v24, v26
	v_mov_b32_e32 v25, v30
	v_pk_fma_f32 v[2:3], v[86:87], v[24:25], v[2:3]
	v_mov_b32_e32 v30, v27
	v_pk_fma_f32 v[2:3], v[82:83], v[30:31], v[2:3]
	ds_read_b128 v[24:27], v1 offset:960
	ds_read_b128 v[28:31], v1 offset:976
	v_add_f32_e32 v2, v21, v2
	v_add_f32_e32 v2, v2, v3
	v_min_f32_e32 v3, 0, v2
	v_mul_f32_e64 v2, |v2|, s4
	v_exp_f32_e32 v2, v2
	s_nop 0
	v_add_f32_e32 v2, 1.0, v2
	v_cmp_gt_f32_e64 s[82:83], s3, v2
	s_nop 1
	v_cndmask_b32_e64 v21, 0, 32, s[82:83]
	v_ldexp_f32 v2, v2, v21
	v_log_f32_e32 v2, v2
	s_nop 0
	v_mul_f32_e32 v21, 0x3f317217, v2
	v_fma_f32 v21, v2, s5, -v21
	v_fmac_f32_e32 v21, 0x3377d1cf, v2
	v_fmac_f32_e32 v21, 0x3f317217, v2
	v_cmp_lt_f32_e64 s[84:85], |v2|, s33
	s_nop 1
	v_cndmask_b32_e64 v2, v2, v21, s[84:85]
	v_cndmask_b32_e64 v21, 0, v208, s[82:83]
	v_sub_f32_e32 v2, v2, v21
	v_sub_f32_e32 v2, v3, v2
	s_waitcnt lgkmcnt(0)
	v_mov_b32_e32 v3, v28
	v_mov_b32_e32 v28, v25
	v_fmamk_f32 v23, v2, 0x3d800000, v22
	v_mov_b32_e32 v2, v24
	v_pk_mul_f32 v[24:25], v[76:77], v[28:29]
	s_nop 0
	v_pk_fma_f32 v[2:3], v[74:75], v[2:3], v[24:25]
	v_mov_b32_e32 v24, v26
	v_mov_b32_e32 v25, v30
	v_pk_fma_f32 v[2:3], v[80:81], v[24:25], v[2:3]
	v_mov_b32_e32 v30, v27
	v_pk_fma_f32 v[2:3], v[78:79], v[30:31], v[2:3]
	ds_read_b128 v[24:27], v1 offset:992
	ds_read_b128 v[28:31], v1 offset:1008
	v_add_f32_e32 v2, v17, v2
	v_add_f32_e32 v21, v2, v3
	s_waitcnt lgkmcnt(1)
	v_mov_b32_e32 v2, v24
	s_waitcnt lgkmcnt(0)
	v_mov_b32_e32 v3, v28
	v_mov_b32_e32 v28, v25
	v_pk_mul_f32 v[24:25], v[84:85], v[28:29]
	s_nop 0
	v_pk_fma_f32 v[2:3], v[88:89], v[2:3], v[24:25]
	v_mov_b32_e32 v24, v26
	v_mov_b32_e32 v25, v30
	v_pk_fma_f32 v[2:3], v[86:87], v[24:25], v[2:3]
	v_mov_b32_e32 v30, v27
	v_pk_fma_f32 v[2:3], v[82:83], v[30:31], v[2:3]
	ds_read_b128 v[24:27], v1 offset:1024
	ds_read_b128 v[28:31], v1 offset:1040
	v_add_f32_e32 v2, v21, v2
	v_add_f32_e32 v2, v2, v3
	v_min_f32_e32 v3, 0, v2
	v_mul_f32_e64 v2, |v2|, s4
	v_exp_f32_e32 v2, v2
	s_nop 0
	v_add_f32_e32 v2, 1.0, v2
	v_cmp_gt_f32_e64 s[82:83], s3, v2
	s_nop 1
	v_cndmask_b32_e64 v21, 0, 32, s[82:83]
	v_ldexp_f32 v2, v2, v21
	v_log_f32_e32 v2, v2
	s_nop 0
	v_mul_f32_e32 v21, 0x3f317217, v2
	v_fma_f32 v21, v2, s5, -v21
	v_fmac_f32_e32 v21, 0x3377d1cf, v2
	v_fmac_f32_e32 v21, 0x3f317217, v2
	v_cmp_lt_f32_e64 s[84:85], |v2|, s33
	s_nop 1
	v_cndmask_b32_e64 v2, v2, v21, s[84:85]
	v_cndmask_b32_e64 v21, 0, v208, s[82:83]
	v_sub_f32_e32 v2, v2, v21
	v_sub_f32_e32 v2, v3, v2
	s_waitcnt lgkmcnt(0)
	v_mov_b32_e32 v3, v28
	v_mov_b32_e32 v28, v25
	v_fmamk_f32 v21, v2, 0x3d800000, v23
	s_cmp_eq_u64 s[12:13], 0
	s_cbranch_scc1 .Lprep_gate_full
	s_waitcnt lgkmcnt(0)
	v_mov_b32_e32 v24, v21
	v_mov_b32_e32 v25, v21
	v_mov_b32_e32 v26, v21
	v_mov_b32_e32 v27, v21
	v_mov_b32_e32 v28, v21
	v_mov_b32_e32 v30, v21
	v_mov_b32_e32 v31, v21
	v_mov_b32_e32 v29, v21
	v_mov_b32_e32 v32, v21
	v_mov_b32_e32 v33, v21
	v_mov_b32_e32 v34, v21
	v_mov_b32_e32 v35, v21
	v_mov_b32_e32 v36, v21
	v_mov_b32_e32 v37, v21
	v_mov_b32_e32 v38, v21
	v_mov_b32_e32 v39, v21
	v_mov_b32_e32 v40, v21
	v_mov_b32_e32 v41, v21
	v_mov_b32_e32 v42, v21
	v_mov_b32_e32 v43, v21
	v_mov_b32_e32 v44, v21
	v_mov_b32_e32 v45, v21
	v_mov_b32_e32 v46, v21
	v_mov_b32_e32 v47, v21
	v_mov_b32_e32 v48, v21
	v_mov_b32_e32 v49, v21
	v_mov_b32_e32 v50, v21
	v_mov_b32_e32 v51, v21
	v_mov_b32_e32 v52, v21
	v_mov_b32_e32 v53, v21
	v_mov_b32_e32 v55, v21
	v_mov_b32_e32 v57, v21
	v_mov_b32_e32 v60, v21
	v_mov_b32_e32 v61, v21
	v_mov_b32_e32 v62, v21
	v_mov_b32_e32 v63, v21
	v_mov_b32_e32 v64, v21
	v_mov_b32_e32 v65, v21
	v_mov_b32_e32 v66, v21
	v_mov_b32_e32 v67, v21
	v_mov_b32_e32 v68, v21
	v_mov_b32_e32 v69, v21
	v_mov_b32_e32 v70, v21
	v_mov_b32_e32 v71, v21
	v_mov_b32_e32 v54, v21
	v_mov_b32_e32 v56, v21
	v_mov_b32_e32 v59, v21
	v_mov_b32_e32 v58, v21
	v_readlane_b32 s4, v254, 17
	v_readlane_b32 s5, v254, 18
	ds_read_u16 v72, v139
	s_branch .Lprep_gate_done
; #define LAS __attribute__((address_space(3)))
; __device__ __forceinline__ void gla_prep(LAS unsigned char* lds, const bf16_t* QK, const float* gz, const float* Wg, const float* bias,
;                                          bf16_t* QPimg, bf16_t* KTimg, bf16_t* Aimg, float* dec, int G) {
;     ...
;         float bb[64]; float bs = 0.f;
; #pragma unroll
;         for (int t = 0; t < 64; ++t) {
;             float x = bi;
; #pragma unroll
;             for (int q4 = 0; q4 < 4; ++q4) { const f32x4 g4 = *(const LAS f32x4*)(gzs + t * 16 + q4 * 4); x += g4.x * wg[4 * q4] + g4.y * wg[4 * q4 + 1] + g4.z * wg[4 * q4 + 2] + g4.w * wg[4 * q4 + 3]; }
;             float ls = (fminf(x, 0.f) - __logf(1.f + __expf(-fabsf(x)))) * (1.f / 16.f);
;             if (t >= ntok) ls = 0.f;
;             bs += ls; bb[t] = bs;
.Lprep_gate_full:
	v_mov_b32_e32 v2, v24
	v_pk_mul_f32 v[24:25], v[76:77], v[28:29]
	s_nop 0
	v_pk_fma_f32 v[2:3], v[74:75], v[2:3], v[24:25]
	v_mov_b32_e32 v24, v26
	v_mov_b32_e32 v25, v30
	v_pk_fma_f32 v[2:3], v[80:81], v[24:25], v[2:3]
	v_mov_b32_e32 v30, v27
	v_pk_fma_f32 v[2:3], v[78:79], v[30:31], v[2:3]
	ds_read_b128 v[24:27], v1 offset:1056
	ds_read_b128 v[28:31], v1 offset:1072
	v_add_f32_e32 v2, v17, v2
	v_add_f32_e32 v32, v2, v3
	s_waitcnt lgkmcnt(1)
	v_mov_b32_e32 v2, v24
	s_waitcnt lgkmcnt(0)
	v_mov_b32_e32 v3, v28
	v_mov_b32_e32 v28, v25
	v_pk_mul_f32 v[24:25], v[84:85], v[28:29]
	s_nop 0
	v_pk_fma_f32 v[2:3], v[88:89], v[2:3], v[24:25]
	v_mov_b32_e32 v24, v26
	v_mov_b32_e32 v25, v30
	v_pk_fma_f32 v[2:3], v[86:87], v[24:25], v[2:3]
	v_mov_b32_e32 v30, v27
	v_pk_fma_f32 v[2:3], v[82:83], v[30:31], v[2:3]
	s_nop 0
	v_add_f32_e32 v2, v32, v2
	v_add_f32_e32 v2, v2, v3
	v_min_f32_e32 v3, 0, v2
	v_mul_f32_e64 v2, |v2|, s4
	v_exp_f32_e32 v2, v2
	ds_read_b128 v[26:29], v1 offset:1088
	ds_read_b128 v[30:33], v1 offset:1104
	v_add_f32_e32 v2, 1.0, v2
	v_cmp_gt_f32_e64 s[82:83], s3, v2
	s_nop 1
	v_cndmask_b32_e64 v24, 0, 32, s[82:83]
	v_ldexp_f32 v2, v2, v24
	v_log_f32_e32 v2, v2
	s_nop 0
	v_mul_f32_e32 v24, 0x3f317217, v2
	v_fma_f32 v24, v2, s5, -v24
	v_fmac_f32_e32 v24, 0x3377d1cf, v2
	v_fmac_f32_e32 v24, 0x3f317217, v2
	v_cmp_lt_f32_e64 s[84:85], |v2|, s33
	s_nop 1
	v_cndmask_b32_e64 v2, v2, v24, s[84:85]
	v_cndmask_b32_e64 v24, 0, v208, s[82:83]
	v_sub_f32_e32 v2, v2, v24
	v_sub_f32_e32 v2, v3, v2
	v_mul_f32_e32 v2, 0x3d800000, v2
	v_cndmask_b32_e64 v2, v2, 0, s[12:13]
	s_waitcnt lgkmcnt(0)
	v_mov_b32_e32 v3, v30
	v_mov_b32_e32 v30, v27
	v_add_f32_e32 v24, v21, v2
	v_mov_b32_e32 v2, v26
	v_pk_mul_f32 v[26:27], v[76:77], v[30:31]
	s_nop 0
	v_pk_fma_f32 v[2:3], v[74:75], v[2:3], v[26:27]
	v_mov_b32_e32 v26, v28
	v_mov_b32_e32 v27, v32
	v_pk_fma_f32 v[2:3], v[80:81], v[26:27], v[2:3]
	v_mov_b32_e32 v32, v29
	v_pk_fma_f32 v[2:3], v[78:79], v[32:33], v[2:3]
	ds_read_b128 v[26:29], v1 offset:1120
	ds_read_b128 v[30:33], v1 offset:1136
	v_add_f32_e32 v2, v17, v2
	v_add_f32_e32 v25, v2, v3
	s_waitcnt lgkmcnt(1)
	v_mov_b32_e32 v2, v26
	s_waitcnt lgkmcnt(0)
	v_mov_b32_e32 v3, v30
	v_mov_b32_e32 v30, v27
	v_pk_mul_f32 v[26:27], v[84:85], v[30:31]
	s_nop 0
	v_pk_fma_f32 v[2:3], v[88:89], v[2:3], v[26:27]
	v_mov_b32_e32 v26, v28
	v_mov_b32_e32 v27, v32
	v_pk_fma_f32 v[2:3], v[86:87], v[26:27], v[2:3]
	v_mov_b32_e32 v32, v29
	v_pk_fma_f32 v[2:3], v[82:83], v[32:33], v[2:3]
	ds_read_b128 v[26:29], v1 offset:1152
	ds_read_b128 v[30:33], v1 offset:1168
	v_add_f32_e32 v2, v25, v2
	v_add_f32_e32 v2, v2, v3
	v_min_f32_e32 v3, 0, v2
	v_mul_f32_e64 v2, |v2|, s4
	v_exp_f32_e32 v2, v2
	s_nop 0
	v_add_f32_e32 v2, 1.0, v2
	v_cmp_gt_f32_e64 s[82:83], s3, v2
	s_nop 1
	v_cndmask_b32_e64 v25, 0, 32, s[82:83]
	v_ldexp_f32 v2, v2, v25
	v_log_f32_e32 v2, v2
	s_nop 0
	v_mul_f32_e32 v25, 0x3f317217, v2
	v_fma_f32 v25, v2, s5, -v25
	v_fmac_f32_e32 v25, 0x3377d1cf, v2
	v_fmac_f32_e32 v25, 0x3f317217, v2
	v_cmp_lt_f32_e64 s[84:85], |v2|, s33
	s_nop 1
	v_cndmask_b32_e64 v2, v2, v25, s[84:85]
	v_cndmask_b32_e64 v25, 0, v208, s[82:83]
	v_sub_f32_e32 v2, v2, v25
	v_sub_f32_e32 v2, v3, v2
	v_mul_f32_e32 v2, 0x3d800000, v2
	v_cndmask_b32_e64 v2, v2, 0, s[12:13]
	s_waitcnt lgkmcnt(0)
	v_mov_b32_e32 v3, v30
	v_mov_b32_e32 v30, v27
	v_add_f32_e32 v25, v24, v2
	v_mov_b32_e32 v2, v26
	v_pk_mul_f32 v[26:27], v[76:77], v[30:31]
	s_nop 0
	v_pk_fma_f32 v[2:3], v[74:75], v[2:3], v[26:27]
	v_mov_b32_e32 v26, v28
	v_mov_b32_e32 v27, v32
	v_pk_fma_f32 v[2:3], v[80:81], v[26:27], v[2:3]
	v_mov_b32_e32 v32, v29
	v_pk_fma_f32 v[2:3], v[78:79], v[32:33], v[2:3]
	ds_read_b128 v[26:29], v1 offset:1184
	ds_read_b128 v[30:33], v1 offset:1200
	v_add_f32_e32 v2, v17, v2
	v_add_f32_e32 v34, v2, v3
	s_waitcnt lgkmcnt(1)
	v_mov_b32_e32 v2, v26
	s_waitcnt lgkmcnt(0)
	v_mov_b32_e32 v3, v30
	v_mov_b32_e32 v30, v27
	v_pk_mul_f32 v[26:27], v[84:85], v[30:31]
	s_nop 0
	v_pk_fma_f32 v[2:3], v[88:89], v[2:3], v[26:27]
	v_mov_b32_e32 v26, v28
	v_mov_b32_e32 v27, v32
	v_pk_fma_f32 v[2:3], v[86:87], v[26:27], v[2:3]
	v_mov_b32_e32 v32, v29
	v_pk_fma_f32 v[2:3], v[82:83], v[32:33], v[2:3]
	s_nop 0
	v_add_f32_e32 v2, v34, v2
	v_add_f32_e32 v2, v2, v3
	v_min_f32_e32 v3, 0, v2
	v_mul_f32_e64 v2, |v2|, s4
	v_exp_f32_e32 v2, v2
	ds_read_b128 v[28:31], v1 offset:1216
	ds_read_b128 v[32:35], v1 offset:1232
	v_add_f32_e32 v2, 1.0, v2
	v_cmp_gt_f32_e64 s[82:83], s3, v2
	s_nop 1
	v_cndmask_b32_e64 v26, 0, 32, s[82:83]
	v_ldexp_f32 v2, v2, v26
	v_log_f32_e32 v2, v2
	s_nop 0
	v_mul_f32_e32 v26, 0x3f317217, v2
	v_fma_f32 v26, v2, s5, -v26
	v_fmac_f32_e32 v26, 0x3377d1cf, v2
	v_fmac_f32_e32 v26, 0x3f317217, v2
	v_cmp_lt_f32_e64 s[84:85], |v2|, s33
	s_nop 1
	v_cndmask_b32_e64 v2, v2, v26, s[84:85]
	v_cndmask_b32_e64 v26, 0, v208, s[82:83]
	v_sub_f32_e32 v2, v2, v26
	v_sub_f32_e32 v2, v3, v2
	v_mul_f32_e32 v2, 0x3d800000, v2
	v_cndmask_b32_e64 v2, v2, 0, s[12:13]
	s_waitcnt lgkmcnt(0)
	v_mov_b32_e32 v3, v32
	v_mov_b32_e32 v32, v29
	v_add_f32_e32 v26, v25, v2
	v_mov_b32_e32 v2, v28
	v_pk_mul_f32 v[28:29], v[76:77], v[32:33]
	s_nop 0
	v_pk_fma_f32 v[2:3], v[74:75], v[2:3], v[28:29]
	v_mov_b32_e32 v28, v30
	v_mov_b32_e32 v29, v34
	v_pk_fma_f32 v[2:3], v[80:81], v[28:29], v[2:3]
	v_mov_b32_e32 v34, v31
	v_pk_fma_f32 v[2:3], v[78:79], v[34:35], v[2:3]
	ds_read_b128 v[28:31], v1 offset:1248
	ds_read_b128 v[32:35], v1 offset:1264
	v_add_f32_e32 v2, v17, v2
	v_add_f32_e32 v27, v2, v3
	s_waitcnt lgkmcnt(1)
	v_mov_b32_e32 v2, v28
	s_waitcnt lgkmcnt(0)
; #define LAS __attribute__((address_space(3)))
; __device__ __forceinline__ void gla_prep(LAS unsigned char* lds, const bf16_t* QK, const float* gz, const float* Wg, const float* bias,
;                                          bf16_t* QPimg, bf16_t* KTimg, bf16_t* Aimg, float* dec, int G) {
;     ...
;         float bb[64]; float bs = 0.f;
; #pragma unroll
;         for (int t = 0; t < 64; ++t) {
;             float x = bi;
; #pragma unroll
;             for (int q4 = 0; q4 < 4; ++q4) { const f32x4 g4 = *(const LAS f32x4*)(gzs + t * 16 + q4 * 4); x += g4.x * wg[4 * q4] + g4.y * wg[4 * q4 + 1] + g4.z * wg[4 * q4 + 2] + g4.w * wg[4 * q4 + 3]; }
;             float ls = (fminf(x, 0.f) - __logf(1.f + __expf(-fabsf(x)))) * (1.f / 16.f);
;             if (t >= ntok) ls = 0.f;
;             bs += ls; bb[t] = bs;
	v_mov_b32_e32 v3, v32
	v_mov_b32_e32 v32, v29
	v_pk_mul_f32 v[28:29], v[84:85], v[32:33]
	s_nop 0
	v_pk_fma_f32 v[2:3], v[88:89], v[2:3], v[28:29]
	v_mov_b32_e32 v28, v30
	v_mov_b32_e32 v29, v34
	v_pk_fma_f32 v[2:3], v[86:87], v[28:29], v[2:3]
	v_mov_b32_e32 v34, v31
	v_pk_fma_f32 v[2:3], v[82:83], v[34:35], v[2:3]
	ds_read_b128 v[28:31], v1 offset:1280
	ds_read_b128 v[32:35], v1 offset:1296
	v_add_f32_e32 v2, v27, v2
	v_add_f32_e32 v2, v2, v3
	v_min_f32_e32 v3, 0, v2
	v_mul_f32_e64 v2, |v2|, s4
	v_exp_f32_e32 v2, v2
	s_nop 0
	v_add_f32_e32 v2, 1.0, v2
	v_cmp_gt_f32_e64 s[82:83], s3, v2
	s_nop 1
	v_cndmask_b32_e64 v27, 0, 32, s[82:83]
	v_ldexp_f32 v2, v2, v27
	v_log_f32_e32 v2, v2
	s_nop 0
	v_mul_f32_e32 v27, 0x3f317217, v2
	v_fma_f32 v27, v2, s5, -v27
	v_fmac_f32_e32 v27, 0x3377d1cf, v2
	v_fmac_f32_e32 v27, 0x3f317217, v2
	v_cmp_lt_f32_e64 s[84:85], |v2|, s33
	s_nop 1
	v_cndmask_b32_e64 v2, v2, v27, s[84:85]
	v_cndmask_b32_e64 v27, 0, v208, s[82:83]
	v_sub_f32_e32 v2, v2, v27
	v_sub_f32_e32 v2, v3, v2
	v_mul_f32_e32 v2, 0x3d800000, v2
	v_cndmask_b32_e64 v2, v2, 0, s[12:13]
	s_waitcnt lgkmcnt(0)
	v_mov_b32_e32 v3, v32
	v_mov_b32_e32 v32, v29
	v_add_f32_e32 v27, v26, v2
	v_mov_b32_e32 v2, v28
	v_pk_mul_f32 v[28:29], v[76:77], v[32:33]
	s_nop 0
	v_pk_fma_f32 v[2:3], v[74:75], v[2:3], v[28:29]
	v_mov_b32_e32 v28, v30
	v_mov_b32_e32 v29, v34
	v_pk_fma_f32 v[2:3], v[80:81], v[28:29], v[2:3]
	v_mov_b32_e32 v34, v31
	v_pk_fma_f32 v[2:3], v[78:79], v[34:35], v[2:3]
	ds_read_b128 v[28:31], v1 offset:1312
	ds_read_b128 v[32:35], v1 offset:1328
	v_add_f32_e32 v2, v17, v2
	v_add_f32_e32 v36, v2, v3
	s_waitcnt lgkmcnt(1)
	v_mov_b32_e32 v2, v28
	s_waitcnt lgkmcnt(0)
	v_mov_b32_e32 v3, v32
	v_mov_b32_e32 v32, v29
	v_pk_mul_f32 v[28:29], v[84:85], v[32:33]
	s_nop 0
	v_pk_fma_f32 v[2:3], v[88:89], v[2:3], v[28:29]
	v_mov_b32_e32 v28, v30
	v_mov_b32_e32 v29, v34
	v_pk_fma_f32 v[2:3], v[86:87], v[28:29], v[2:3]
	v_mov_b32_e32 v34, v31
	v_pk_fma_f32 v[2:3], v[82:83], v[34:35], v[2:3]
	s_nop 0
	v_add_f32_e32 v2, v36, v2
	v_add_f32_e32 v2, v2, v3
	v_min_f32_e32 v3, 0, v2
	v_mul_f32_e64 v2, |v2|, s4
	v_exp_f32_e32 v2, v2
	ds_read_b128 v[30:33], v1 offset:1344
	ds_read_b128 v[34:37], v1 offset:1360
	v_add_f32_e32 v2, 1.0, v2
	v_cmp_gt_f32_e64 s[82:83], s3, v2
	s_nop 1
	v_cndmask_b32_e64 v28, 0, 32, s[82:83]
	v_ldexp_f32 v2, v2, v28
	v_log_f32_e32 v2, v2
	s_nop 0
	v_mul_f32_e32 v28, 0x3f317217, v2
	v_fma_f32 v28, v2, s5, -v28
	v_fmac_f32_e32 v28, 0x3377d1cf, v2
	v_fmac_f32_e32 v28, 0x3f317217, v2
	v_cmp_lt_f32_e64 s[84:85], |v2|, s33
	s_nop 1
	v_cndmask_b32_e64 v2, v2, v28, s[84:85]
	v_cndmask_b32_e64 v28, 0, v208, s[82:83]
	v_sub_f32_e32 v2, v2, v28
	v_sub_f32_e32 v2, v3, v2
	v_mul_f32_e32 v2, 0x3d800000, v2
	v_cndmask_b32_e64 v2, v2, 0, s[12:13]
	s_waitcnt lgkmcnt(0)
	v_mov_b32_e32 v3, v34
	v_mov_b32_e32 v34, v31
	v_add_f32_e32 v28, v27, v2
	v_mov_b32_e32 v2, v30
	v_pk_mul_f32 v[30:31], v[76:77], v[34:35]
	s_nop 0
	v_pk_fma_f32 v[2:3], v[74:75], v[2:3], v[30:31]
	v_mov_b32_e32 v30, v32
	v_mov_b32_e32 v31, v36
	v_pk_fma_f32 v[2:3], v[80:81], v[30:31], v[2:3]
	v_mov_b32_e32 v36, v33
	v_pk_fma_f32 v[2:3], v[78:79], v[36:37], v[2:3]
	ds_read_b128 v[30:33], v1 offset:1376
	ds_read_b128 v[34:37], v1 offset:1392
	v_add_f32_e32 v2, v17, v2
	v_add_f32_e32 v29, v2, v3
	s_waitcnt lgkmcnt(1)
	v_mov_b32_e32 v2, v30
	s_waitcnt lgkmcnt(0)
	v_mov_b32_e32 v3, v34
	v_mov_b32_e32 v34, v31
	v_pk_mul_f32 v[30:31], v[84:85], v[34:35]
	s_nop 0
	v_pk_fma_f32 v[2:3], v[88:89], v[2:3], v[30:31]
	v_mov_b32_e32 v30, v32
	v_mov_b32_e32 v31, v36
	v_pk_fma_f32 v[2:3], v[86:87], v[30:31], v[2:3]
	v_mov_b32_e32 v36, v33
	v_pk_fma_f32 v[2:3], v[82:83], v[36:37], v[2:3]
	ds_read_b128 v[32:35], v1 offset:1408
	ds_read_b128 v[36:39], v1 offset:1424
	v_add_f32_e32 v2, v29, v2
	v_add_f32_e32 v2, v2, v3
	v_min_f32_e32 v3, 0, v2
	v_mul_f32_e64 v2, |v2|, s4
	v_exp_f32_e32 v2, v2
	s_nop 0
	v_add_f32_e32 v2, 1.0, v2
	v_cmp_gt_f32_e64 s[82:83], s3, v2
	s_nop 1
	v_cndmask_b32_e64 v29, 0, 32, s[82:83]
	v_ldexp_f32 v2, v2, v29
	v_log_f32_e32 v2, v2
	s_nop 0
	v_mul_f32_e32 v29, 0x3f317217, v2
	v_fma_f32 v29, v2, s5, -v29
	v_fmac_f32_e32 v29, 0x3377d1cf, v2
	v_fmac_f32_e32 v29, 0x3f317217, v2
	v_cmp_lt_f32_e64 s[84:85], |v2|, s33
	s_nop 1
	v_cndmask_b32_e64 v2, v2, v29, s[84:85]
	v_cndmask_b32_e64 v29, 0, v208, s[82:83]
	v_sub_f32_e32 v2, v2, v29
	v_sub_f32_e32 v2, v3, v2
	v_mul_f32_e32 v2, 0x3d800000, v2
	v_cndmask_b32_e64 v2, v2, 0, s[12:13]
	s_waitcnt lgkmcnt(0)
	v_mov_b32_e32 v3, v36
	v_mov_b32_e32 v36, v33
	v_add_f32_e32 v30, v28, v2
	v_mov_b32_e32 v2, v32
	v_pk_mul_f32 v[32:33], v[76:77], v[36:37]
	s_nop 0
	v_pk_fma_f32 v[2:3], v[74:75], v[2:3], v[32:33]
	v_mov_b32_e32 v32, v34
	v_mov_b32_e32 v33, v38
	v_pk_fma_f32 v[2:3], v[80:81], v[32:33], v[2:3]
	v_mov_b32_e32 v38, v35
	v_pk_fma_f32 v[2:3], v[78:79], v[38:39], v[2:3]
	ds_read_b128 v[32:35], v1 offset:1440
	ds_read_b128 v[36:39], v1 offset:1456
	v_add_f32_e32 v2, v17, v2
	v_add_f32_e32 v29, v2, v3
	s_waitcnt lgkmcnt(1)
	v_mov_b32_e32 v2, v32
	s_waitcnt lgkmcnt(0)
	v_mov_b32_e32 v3, v36
	v_mov_b32_e32 v36, v33
	v_pk_mul_f32 v[32:33], v[84:85], v[36:37]
	s_nop 0
	v_pk_fma_f32 v[2:3], v[88:89], v[2:3], v[32:33]
	v_mov_b32_e32 v32, v34
	v_mov_b32_e32 v33, v38
	v_pk_fma_f32 v[2:3], v[86:87], v[32:33], v[2:3]
	v_mov_b32_e32 v38, v35
	v_pk_fma_f32 v[2:3], v[82:83], v[38:39], v[2:3]
	ds_read_b128 v[32:35], v1 offset:1472
	ds_read_b128 v[36:39], v1 offset:1488
	v_add_f32_e32 v2, v29, v2
	v_add_f32_e32 v2, v2, v3
	v_min_f32_e32 v3, 0, v2
	v_mul_f32_e64 v2, |v2|, s4
	v_exp_f32_e32 v2, v2
	s_nop 0
	v_add_f32_e32 v2, 1.0, v2
	v_cmp_gt_f32_e64 s[82:83], s3, v2
	s_nop 1
	v_cndmask_b32_e64 v29, 0, 32, s[82:83]
	v_ldexp_f32 v2, v2, v29
	v_log_f32_e32 v2, v2
	s_nop 0
	v_mul_f32_e32 v29, 0x3f317217, v2
	v_fma_f32 v29, v2, s5, -v29
	v_fmac_f32_e32 v29, 0x3377d1cf, v2
	v_fmac_f32_e32 v29, 0x3f317217, v2
	v_cmp_lt_f32_e64 s[84:85], |v2|, s33
	s_nop 1
	v_cndmask_b32_e64 v2, v2, v29, s[84:85]
	v_cndmask_b32_e64 v29, 0, v208, s[82:83]
	v_sub_f32_e32 v2, v2, v29
	v_sub_f32_e32 v2, v3, v2
	v_mul_f32_e32 v2, 0x3d800000, v2
	v_cndmask_b32_e64 v2, v2, 0, s[12:13]
	s_waitcnt lgkmcnt(0)
; #define LAS __attribute__((address_space(3)))
; __device__ __forceinline__ void gla_prep(LAS unsigned char* lds, const bf16_t* QK, const float* gz, const float* Wg, const float* bias,
;                                          bf16_t* QPimg, bf16_t* KTimg, bf16_t* Aimg, float* dec, int G) {
;     ...
;         float bb[64]; float bs = 0.f;
; #pragma unroll
;         for (int t = 0; t < 64; ++t) {
;             float x = bi;
; #pragma unroll
;             for (int q4 = 0; q4 < 4; ++q4) { const f32x4 g4 = *(const LAS f32x4*)(gzs + t * 16 + q4 * 4); x += g4.x * wg[4 * q4] + g4.y * wg[4 * q4 + 1] + g4.z * wg[4 * q4 + 2] + g4.w * wg[4 * q4 + 3]; }
;             float ls = (fminf(x, 0.f) - __logf(1.f + __expf(-fabsf(x)))) * (1.f / 16.f);
;             if (t >= ntok) ls = 0.f;
;             bs += ls; bb[t] = bs;
	v_mov_b32_e32 v3, v36
	v_mov_b32_e32 v36, v33
	v_add_f32_e32 v31, v30, v2
	v_mov_b32_e32 v2, v32
	v_pk_mul_f32 v[32:33], v[76:77], v[36:37]
	s_nop 0
	v_pk_fma_f32 v[2:3], v[74:75], v[2:3], v[32:33]
	v_mov_b32_e32 v32, v34
	v_mov_b32_e32 v33, v38
	v_pk_fma_f32 v[2:3], v[80:81], v[32:33], v[2:3]
	v_mov_b32_e32 v38, v35
	v_pk_fma_f32 v[2:3], v[78:79], v[38:39], v[2:3]
	ds_read_b128 v[32:35], v1 offset:1504
	ds_read_b128 v[36:39], v1 offset:1520
	v_add_f32_e32 v2, v17, v2
	v_add_f32_e32 v29, v2, v3
	s_waitcnt lgkmcnt(1)
	v_mov_b32_e32 v2, v32
	s_waitcnt lgkmcnt(0)
	v_mov_b32_e32 v3, v36
	v_mov_b32_e32 v36, v33
	v_pk_mul_f32 v[32:33], v[84:85], v[36:37]
	s_nop 0
	v_pk_fma_f32 v[2:3], v[88:89], v[2:3], v[32:33]
	v_mov_b32_e32 v32, v34
	v_mov_b32_e32 v33, v38
	v_pk_fma_f32 v[2:3], v[86:87], v[32:33], v[2:3]
	v_mov_b32_e32 v38, v35
	v_pk_fma_f32 v[2:3], v[82:83], v[38:39], v[2:3]
	ds_read_b128 v[32:35], v1 offset:1536
	ds_read_b128 v[36:39], v1 offset:1552
	v_add_f32_e32 v2, v29, v2
	v_add_f32_e32 v2, v2, v3
	v_min_f32_e32 v3, 0, v2
	v_mul_f32_e64 v2, |v2|, s4
	v_exp_f32_e32 v2, v2
	s_nop 0
	v_add_f32_e32 v2, 1.0, v2
	v_cmp_gt_f32_e64 s[82:83], s3, v2
	s_nop 1
	v_cndmask_b32_e64 v29, 0, 32, s[82:83]
	v_ldexp_f32 v2, v2, v29
	v_log_f32_e32 v2, v2
	s_nop 0
	v_mul_f32_e32 v29, 0x3f317217, v2
	v_fma_f32 v29, v2, s5, -v29
	v_fmac_f32_e32 v29, 0x3377d1cf, v2
	v_fmac_f32_e32 v29, 0x3f317217, v2
	v_cmp_lt_f32_e64 s[84:85], |v2|, s33
	s_nop 1
	v_cndmask_b32_e64 v2, v2, v29, s[84:85]
	v_cndmask_b32_e64 v29, 0, v208, s[82:83]
	v_sub_f32_e32 v2, v2, v29
	v_sub_f32_e32 v2, v3, v2
	v_mul_f32_e32 v2, 0x3d800000, v2
	v_cndmask_b32_e64 v2, v2, 0, s[12:13]
	s_waitcnt lgkmcnt(0)
	v_mov_b32_e32 v3, v36
	v_mov_b32_e32 v36, v33
	v_add_f32_e32 v29, v31, v2
	v_mov_b32_e32 v2, v32
	v_pk_mul_f32 v[32:33], v[76:77], v[36:37]
	s_nop 0
	v_pk_fma_f32 v[2:3], v[74:75], v[2:3], v[32:33]
	v_mov_b32_e32 v32, v34
	v_mov_b32_e32 v33, v38
	v_pk_fma_f32 v[2:3], v[80:81], v[32:33], v[2:3]
	v_mov_b32_e32 v38, v35
	v_pk_fma_f32 v[2:3], v[78:79], v[38:39], v[2:3]
	ds_read_b128 v[32:35], v1 offset:1568
	ds_read_b128 v[36:39], v1 offset:1584
	v_add_f32_e32 v2, v17, v2
	v_add_f32_e32 v40, v2, v3
	s_waitcnt lgkmcnt(1)
	v_mov_b32_e32 v2, v32
	s_waitcnt lgkmcnt(0)
	v_mov_b32_e32 v3, v36
	v_mov_b32_e32 v36, v33
	v_pk_mul_f32 v[32:33], v[84:85], v[36:37]
	s_nop 0
	v_pk_fma_f32 v[2:3], v[88:89], v[2:3], v[32:33]
	v_mov_b32_e32 v32, v34
	v_mov_b32_e32 v33, v38
	v_pk_fma_f32 v[2:3], v[86:87], v[32:33], v[2:3]
	v_mov_b32_e32 v38, v35
	v_pk_fma_f32 v[2:3], v[82:83], v[38:39], v[2:3]
	s_nop 0
	v_add_f32_e32 v2, v40, v2
	v_add_f32_e32 v2, v2, v3
	v_min_f32_e32 v3, 0, v2
	v_mul_f32_e64 v2, |v2|, s4
	v_exp_f32_e32 v2, v2
	ds_read_b128 v[34:37], v1 offset:1600
	ds_read_b128 v[38:41], v1 offset:1616
	v_add_f32_e32 v2, 1.0, v2
	v_cmp_gt_f32_e64 s[82:83], s3, v2
	s_nop 1
	v_cndmask_b32_e64 v32, 0, 32, s[82:83]
	v_ldexp_f32 v2, v2, v32
	v_log_f32_e32 v2, v2
	s_nop 0
	v_mul_f32_e32 v32, 0x3f317217, v2
	v_fma_f32 v32, v2, s5, -v32
	v_fmac_f32_e32 v32, 0x3377d1cf, v2
	v_fmac_f32_e32 v32, 0x3f317217, v2
	v_cmp_lt_f32_e64 s[84:85], |v2|, s33
	s_nop 1
	v_cndmask_b32_e64 v2, v2, v32, s[84:85]
	v_cndmask_b32_e64 v32, 0, v208, s[82:83]
	v_sub_f32_e32 v2, v2, v32
	v_sub_f32_e32 v2, v3, v2
	v_mul_f32_e32 v2, 0x3d800000, v2
	v_cndmask_b32_e64 v2, v2, 0, s[12:13]
	s_waitcnt lgkmcnt(0)
	v_mov_b32_e32 v3, v38
	v_mov_b32_e32 v38, v35
	v_add_f32_e32 v32, v29, v2
	v_mov_b32_e32 v2, v34
	v_pk_mul_f32 v[34:35], v[76:77], v[38:39]
	s_nop 0
	v_pk_fma_f32 v[2:3], v[74:75], v[2:3], v[34:35]
	v_mov_b32_e32 v34, v36
	v_mov_b32_e32 v35, v40
	v_pk_fma_f32 v[2:3], v[80:81], v[34:35], v[2:3]
	v_mov_b32_e32 v40, v37
	v_pk_fma_f32 v[2:3], v[78:79], v[40:41], v[2:3]
	ds_read_b128 v[34:37], v1 offset:1632
	ds_read_b128 v[38:41], v1 offset:1648
	v_add_f32_e32 v2, v17, v2
	v_add_f32_e32 v33, v2, v3
	s_waitcnt lgkmcnt(1)
	v_mov_b32_e32 v2, v34
	s_waitcnt lgkmcnt(0)
	v_mov_b32_e32 v3, v38
	v_mov_b32_e32 v38, v35
	v_pk_mul_f32 v[34:35], v[84:85], v[38:39]
	s_nop 0
	v_pk_fma_f32 v[2:3], v[88:89], v[2:3], v[34:35]
	v_mov_b32_e32 v34, v36
	v_mov_b32_e32 v35, v40
	v_pk_fma_f32 v[2:3], v[86:87], v[34:35], v[2:3]
	v_mov_b32_e32 v40, v37
	v_pk_fma_f32 v[2:3], v[82:83], v[40:41], v[2:3]
	ds_read_b128 v[34:37], v1 offset:1664
	v_add_f32_e32 v2, v33, v2
	v_add_f32_e32 v2, v2, v3
	v_min_f32_e32 v3, 0, v2
	v_mul_f32_e64 v2, |v2|, s4
	v_exp_f32_e32 v2, v2
	s_nop 0
	v_add_f32_e32 v2, 1.0, v2
	v_cmp_gt_f32_e64 s[82:83], s3, v2
	s_nop 1
	v_cndmask_b32_e64 v33, 0, 32, s[82:83]
	v_ldexp_f32 v2, v2, v33
	v_log_f32_e32 v2, v2
	s_nop 0
	v_mul_f32_e32 v33, 0x3f317217, v2
	v_fma_f32 v33, v2, s5, -v33
	v_fmac_f32_e32 v33, 0x3377d1cf, v2
	v_fmac_f32_e32 v33, 0x3f317217, v2
	v_cmp_lt_f32_e64 s[84:85], |v2|, s33
	s_nop 1
	v_cndmask_b32_e64 v2, v2, v33, s[84:85]
	v_cndmask_b32_e64 v33, 0, v208, s[82:83]
	v_sub_f32_e32 v2, v2, v33
	v_sub_f32_e32 v2, v3, v2
	v_mul_f32_e32 v2, 0x3d800000, v2
	v_cndmask_b32_e64 v2, v2, 0, s[12:13]
	v_add_f32_e32 v33, v32, v2
	s_waitcnt lgkmcnt(0)
	v_mul_f32_e32 v2, v76, v35
	v_fmac_f32_e32 v2, v74, v34
	v_fmac_f32_e32 v2, v80, v36
	v_fmac_f32_e32 v2, v78, v37
	ds_read_b128 v[34:37], v1 offset:1680
	v_add_f32_e32 v2, v17, v2
	s_waitcnt lgkmcnt(0)
	v_mul_f32_e32 v3, v77, v35
	v_fmac_f32_e32 v3, v75, v34
	v_fmac_f32_e32 v3, v81, v36
	v_fmac_f32_e32 v3, v79, v37
	ds_read_b128 v[34:37], v1 offset:1696
	ds_read_b128 v[38:41], v1 offset:1712
	v_add_f32_e32 v42, v2, v3
	s_waitcnt lgkmcnt(1)
	v_mov_b32_e32 v2, v34
	s_waitcnt lgkmcnt(0)
; #define LAS __attribute__((address_space(3)))
; __device__ __forceinline__ void gla_prep(LAS unsigned char* lds, const bf16_t* QK, const float* gz, const float* Wg, const float* bias,
;                                          bf16_t* QPimg, bf16_t* KTimg, bf16_t* Aimg, float* dec, int G) {
;     ...
;         float bb[64]; float bs = 0.f;
; #pragma unroll
;         for (int t = 0; t < 64; ++t) {
;             float x = bi;
; #pragma unroll
;             for (int q4 = 0; q4 < 4; ++q4) { const f32x4 g4 = *(const LAS f32x4*)(gzs + t * 16 + q4 * 4); x += g4.x * wg[4 * q4] + g4.y * wg[4 * q4 + 1] + g4.z * wg[4 * q4 + 2] + g4.w * wg[4 * q4 + 3]; }
;             float ls = (fminf(x, 0.f) - __logf(1.f + __expf(-fabsf(x)))) * (1.f / 16.f);
;             if (t >= ntok) ls = 0.f;
;             bs += ls; bb[t] = bs;
	v_mov_b32_e32 v3, v38
	v_mov_b32_e32 v38, v35
	v_pk_mul_f32 v[34:35], v[84:85], v[38:39]
	s_nop 0
	v_pk_fma_f32 v[2:3], v[88:89], v[2:3], v[34:35]
	v_mov_b32_e32 v34, v36
	v_mov_b32_e32 v35, v40
	v_pk_fma_f32 v[2:3], v[86:87], v[34:35], v[2:3]
	v_mov_b32_e32 v40, v37
	v_pk_fma_f32 v[2:3], v[82:83], v[40:41], v[2:3]
	ds_read_b128 v[36:39], v1 offset:1728
	v_add_f32_e32 v2, v42, v2
	v_add_f32_e32 v2, v2, v3
	v_min_f32_e32 v3, 0, v2
	v_mul_f32_e64 v2, |v2|, s4
	v_exp_f32_e32 v2, v2
	s_nop 0
	v_add_f32_e32 v2, 1.0, v2
	v_cmp_gt_f32_e64 s[82:83], s3, v2
	s_nop 1
	v_cndmask_b32_e64 v34, 0, 32, s[82:83]
	v_ldexp_f32 v2, v2, v34
	v_log_f32_e32 v2, v2
	s_nop 0
	v_mul_f32_e32 v34, 0x3f317217, v2
	v_fma_f32 v34, v2, s5, -v34
	v_fmac_f32_e32 v34, 0x3377d1cf, v2
	v_fmac_f32_e32 v34, 0x3f317217, v2
	v_cmp_lt_f32_e64 s[84:85], |v2|, s33
	s_nop 1
	v_cndmask_b32_e64 v2, v2, v34, s[84:85]
	v_cndmask_b32_e64 v34, 0, v208, s[82:83]
	v_sub_f32_e32 v2, v2, v34
	v_sub_f32_e32 v2, v3, v2
	v_mul_f32_e32 v2, 0x3d800000, v2
	v_cndmask_b32_e64 v2, v2, 0, s[12:13]
	v_add_f32_e32 v34, v33, v2
	s_waitcnt lgkmcnt(0)
	v_mul_f32_e32 v2, v76, v37
	v_fmac_f32_e32 v2, v74, v36
	v_fmac_f32_e32 v2, v80, v38
	v_fmac_f32_e32 v2, v78, v39
	ds_read_b128 v[36:39], v1 offset:1744
	v_add_f32_e32 v2, v17, v2
	s_waitcnt lgkmcnt(0)
	v_mul_f32_e32 v3, v77, v37
	v_fmac_f32_e32 v3, v75, v36
	v_fmac_f32_e32 v3, v81, v38
	v_fmac_f32_e32 v3, v79, v39
	ds_read_b128 v[36:39], v1 offset:1760
	ds_read_b128 v[40:43], v1 offset:1776
	v_add_f32_e32 v35, v2, v3
	s_waitcnt lgkmcnt(1)
	v_mov_b32_e32 v2, v36
	s_waitcnt lgkmcnt(0)
	v_mov_b32_e32 v3, v40
	v_mov_b32_e32 v40, v37
	v_pk_mul_f32 v[36:37], v[84:85], v[40:41]
	s_nop 0
	v_pk_fma_f32 v[2:3], v[88:89], v[2:3], v[36:37]
	v_mov_b32_e32 v36, v38
	v_mov_b32_e32 v37, v42
	v_pk_fma_f32 v[2:3], v[86:87], v[36:37], v[2:3]
	v_mov_b32_e32 v42, v39
	v_pk_fma_f32 v[2:3], v[82:83], v[42:43], v[2:3]
	ds_read_b128 v[36:39], v1 offset:1792
	v_add_f32_e32 v2, v35, v2
	v_add_f32_e32 v2, v2, v3
	v_min_f32_e32 v3, 0, v2
	v_mul_f32_e64 v2, |v2|, s4
	v_exp_f32_e32 v2, v2
	s_nop 0
	v_add_f32_e32 v2, 1.0, v2
	v_cmp_gt_f32_e64 s[82:83], s3, v2
	s_nop 1
	v_cndmask_b32_e64 v35, 0, 32, s[82:83]
	v_ldexp_f32 v2, v2, v35
	v_log_f32_e32 v2, v2
	s_nop 0
	v_mul_f32_e32 v35, 0x3f317217, v2
	v_fma_f32 v35, v2, s5, -v35
	v_fmac_f32_e32 v35, 0x3377d1cf, v2
	v_fmac_f32_e32 v35, 0x3f317217, v2
	v_cmp_lt_f32_e64 s[84:85], |v2|, s33
	s_nop 1
	v_cndmask_b32_e64 v2, v2, v35, s[84:85]
	v_cndmask_b32_e64 v35, 0, v208, s[82:83]
	v_sub_f32_e32 v2, v2, v35
	v_sub_f32_e32 v2, v3, v2
	v_mul_f32_e32 v2, 0x3d800000, v2
	v_cndmask_b32_e64 v2, v2, 0, s[12:13]
	v_add_f32_e32 v35, v34, v2
	s_waitcnt lgkmcnt(0)
	v_mul_f32_e32 v2, v76, v37
	v_fmac_f32_e32 v2, v74, v36
	v_fmac_f32_e32 v2, v80, v38
	v_fmac_f32_e32 v2, v78, v39
	ds_read_b128 v[36:39], v1 offset:1808
	v_add_f32_e32 v2, v17, v2
	s_waitcnt lgkmcnt(0)
	v_mul_f32_e32 v3, v77, v37
	v_fmac_f32_e32 v3, v75, v36
	v_fmac_f32_e32 v3, v81, v38
	v_fmac_f32_e32 v3, v79, v39
	ds_read_b128 v[36:39], v1 offset:1824
	ds_read_b128 v[40:43], v1 offset:1840
	v_add_f32_e32 v44, v2, v3
	s_waitcnt lgkmcnt(1)
	v_mov_b32_e32 v2, v36
	s_waitcnt lgkmcnt(0)
	v_mov_b32_e32 v3, v40
	v_mov_b32_e32 v40, v37
	v_pk_mul_f32 v[36:37], v[84:85], v[40:41]
	s_nop 0
	v_pk_fma_f32 v[2:3], v[88:89], v[2:3], v[36:37]
	v_mov_b32_e32 v36, v38
	v_mov_b32_e32 v37, v42
	v_pk_fma_f32 v[2:3], v[86:87], v[36:37], v[2:3]
	v_mov_b32_e32 v42, v39
	v_pk_fma_f32 v[2:3], v[82:83], v[42:43], v[2:3]
	ds_read_b128 v[38:41], v1 offset:1856
	v_add_f32_e32 v2, v44, v2
	v_add_f32_e32 v2, v2, v3
	v_min_f32_e32 v3, 0, v2
	v_mul_f32_e64 v2, |v2|, s4
	v_exp_f32_e32 v2, v2
	s_nop 0
	v_add_f32_e32 v2, 1.0, v2
	v_cmp_gt_f32_e64 s[82:83], s3, v2
	s_nop 1
	v_cndmask_b32_e64 v36, 0, 32, s[82:83]
	v_ldexp_f32 v2, v2, v36
	v_log_f32_e32 v2, v2
	s_nop 0
	v_mul_f32_e32 v36, 0x3f317217, v2
	v_fma_f32 v36, v2, s5, -v36
	v_fmac_f32_e32 v36, 0x3377d1cf, v2
	v_fmac_f32_e32 v36, 0x3f317217, v2
	v_cmp_lt_f32_e64 s[84:85], |v2|, s33
	s_nop 1
	v_cndmask_b32_e64 v2, v2, v36, s[84:85]
	v_cndmask_b32_e64 v36, 0, v208, s[82:83]
	v_sub_f32_e32 v2, v2, v36
	v_sub_f32_e32 v2, v3, v2
	v_mul_f32_e32 v2, 0x3d800000, v2
	v_cndmask_b32_e64 v2, v2, 0, s[12:13]
	v_add_f32_e32 v36, v35, v2
	s_waitcnt lgkmcnt(0)
	v_mul_f32_e32 v2, v76, v39
	v_fmac_f32_e32 v2, v74, v38
	v_fmac_f32_e32 v2, v80, v40
	v_fmac_f32_e32 v2, v78, v41
	ds_read_b128 v[38:41], v1 offset:1872
	v_add_f32_e32 v2, v17, v2
	s_waitcnt lgkmcnt(0)
	v_mul_f32_e32 v3, v77, v39
	v_fmac_f32_e32 v3, v75, v38
	v_fmac_f32_e32 v3, v81, v40
	v_fmac_f32_e32 v3, v79, v41
	ds_read_b128 v[38:41], v1 offset:1888
	ds_read_b128 v[42:45], v1 offset:1904
	v_add_f32_e32 v37, v2, v3
	s_waitcnt lgkmcnt(1)
	v_mov_b32_e32 v2, v38
	s_waitcnt lgkmcnt(0)
	v_mov_b32_e32 v3, v42
	v_mov_b32_e32 v42, v39
	v_pk_mul_f32 v[38:39], v[84:85], v[42:43]
	s_nop 0
	v_pk_fma_f32 v[2:3], v[88:89], v[2:3], v[38:39]
	v_mov_b32_e32 v38, v40
	v_mov_b32_e32 v39, v44
	v_pk_fma_f32 v[2:3], v[86:87], v[38:39], v[2:3]
	v_mov_b32_e32 v44, v41
	v_pk_fma_f32 v[2:3], v[82:83], v[44:45], v[2:3]
	ds_read_b128 v[38:41], v1 offset:1920
	v_add_f32_e32 v2, v37, v2
	v_add_f32_e32 v2, v2, v3
	v_min_f32_e32 v3, 0, v2
	v_mul_f32_e64 v2, |v2|, s4
	v_exp_f32_e32 v2, v2
	s_nop 0
	v_add_f32_e32 v2, 1.0, v2
	v_cmp_gt_f32_e64 s[82:83], s3, v2
	s_nop 1
	v_cndmask_b32_e64 v37, 0, 32, s[82:83]
	v_ldexp_f32 v2, v2, v37
	v_log_f32_e32 v2, v2
	s_nop 0
	v_mul_f32_e32 v37, 0x3f317217, v2
	v_fma_f32 v37, v2, s5, -v37
	v_fmac_f32_e32 v37, 0x3377d1cf, v2
	v_fmac_f32_e32 v37, 0x3f317217, v2
	v_cmp_lt_f32_e64 s[84:85], |v2|, s33
	s_nop 1
	v_cndmask_b32_e64 v2, v2, v37, s[84:85]
	v_cndmask_b32_e64 v37, 0, v208, s[82:83]
	v_sub_f32_e32 v2, v2, v37
	v_sub_f32_e32 v2, v3, v2
	v_mul_f32_e32 v2, 0x3d800000, v2
	v_cndmask_b32_e64 v2, v2, 0, s[12:13]
	v_add_f32_e32 v37, v36, v2
	s_waitcnt lgkmcnt(0)
; #define LAS __attribute__((address_space(3)))
; __device__ __forceinline__ void gla_prep(LAS unsigned char* lds, const bf16_t* QK, const float* gz, const float* Wg, const float* bias,
;                                          bf16_t* QPimg, bf16_t* KTimg, bf16_t* Aimg, float* dec, int G) {
;     ...
;         float bb[64]; float bs = 0.f;
; #pragma unroll
;         for (int t = 0; t < 64; ++t) {
;             float x = bi;
; #pragma unroll
;             for (int q4 = 0; q4 < 4; ++q4) { const f32x4 g4 = *(const LAS f32x4*)(gzs + t * 16 + q4 * 4); x += g4.x * wg[4 * q4] + g4.y * wg[4 * q4 + 1] + g4.z * wg[4 * q4 + 2] + g4.w * wg[4 * q4 + 3]; }
;             float ls = (fminf(x, 0.f) - __logf(1.f + __expf(-fabsf(x)))) * (1.f / 16.f);
;             if (t >= ntok) ls = 0.f;
;             bs += ls; bb[t] = bs;
	v_mul_f32_e32 v2, v76, v39
	v_fmac_f32_e32 v2, v74, v38
	v_fmac_f32_e32 v2, v80, v40
	v_fmac_f32_e32 v2, v78, v41
	ds_read_b128 v[38:41], v1 offset:1936
	v_add_f32_e32 v2, v17, v2
	s_waitcnt lgkmcnt(0)
	v_mul_f32_e32 v3, v77, v39
	v_fmac_f32_e32 v3, v75, v38
	v_fmac_f32_e32 v3, v81, v40
	v_fmac_f32_e32 v3, v79, v41
	ds_read_b128 v[38:41], v1 offset:1952
	ds_read_b128 v[42:45], v1 offset:1968
	v_add_f32_e32 v46, v2, v3
	s_waitcnt lgkmcnt(1)
	v_mov_b32_e32 v2, v38
	s_waitcnt lgkmcnt(0)
	v_mov_b32_e32 v3, v42
	v_mov_b32_e32 v42, v39
	v_pk_mul_f32 v[38:39], v[84:85], v[42:43]
	s_nop 0
	v_pk_fma_f32 v[2:3], v[88:89], v[2:3], v[38:39]
	v_mov_b32_e32 v38, v40
	v_mov_b32_e32 v39, v44
	v_pk_fma_f32 v[2:3], v[86:87], v[38:39], v[2:3]
	v_mov_b32_e32 v44, v41
	v_pk_fma_f32 v[2:3], v[82:83], v[44:45], v[2:3]
	ds_read_b128 v[40:43], v1 offset:1984
	v_add_f32_e32 v2, v46, v2
	v_add_f32_e32 v2, v2, v3
	v_min_f32_e32 v3, 0, v2
	v_mul_f32_e64 v2, |v2|, s4
	v_exp_f32_e32 v2, v2
	s_nop 0
	v_add_f32_e32 v2, 1.0, v2
	v_cmp_gt_f32_e64 s[82:83], s3, v2
	s_nop 1
	v_cndmask_b32_e64 v38, 0, 32, s[82:83]
	v_ldexp_f32 v2, v2, v38
	v_log_f32_e32 v2, v2
	s_nop 0
	v_mul_f32_e32 v38, 0x3f317217, v2
	v_fma_f32 v38, v2, s5, -v38
	v_fmac_f32_e32 v38, 0x3377d1cf, v2
	v_fmac_f32_e32 v38, 0x3f317217, v2
	v_cmp_lt_f32_e64 s[84:85], |v2|, s33
	s_nop 1
	v_cndmask_b32_e64 v2, v2, v38, s[84:85]
	v_cndmask_b32_e64 v38, 0, v208, s[82:83]
	v_sub_f32_e32 v2, v2, v38
	v_sub_f32_e32 v2, v3, v2
	v_mul_f32_e32 v2, 0x3d800000, v2
	v_cndmask_b32_e64 v2, v2, 0, s[12:13]
	v_add_f32_e32 v38, v37, v2
	s_waitcnt lgkmcnt(0)
	v_mul_f32_e32 v2, v76, v41
	v_fmac_f32_e32 v2, v74, v40
	v_fmac_f32_e32 v2, v80, v42
	v_fmac_f32_e32 v2, v78, v43
	ds_read_b128 v[40:43], v1 offset:2000
	v_add_f32_e32 v2, v17, v2
	s_waitcnt lgkmcnt(0)
	v_mul_f32_e32 v3, v77, v41
	v_fmac_f32_e32 v3, v75, v40
	v_fmac_f32_e32 v3, v81, v42
	v_fmac_f32_e32 v3, v79, v43
	ds_read_b128 v[40:43], v1 offset:2016
	ds_read_b128 v[44:47], v1 offset:2032
	v_add_f32_e32 v39, v2, v3
	s_waitcnt lgkmcnt(1)
	v_mov_b32_e32 v2, v40
	s_waitcnt lgkmcnt(0)
	v_mov_b32_e32 v3, v44
	v_mov_b32_e32 v44, v41
	v_pk_mul_f32 v[40:41], v[84:85], v[44:45]
	s_nop 0
	v_pk_fma_f32 v[2:3], v[88:89], v[2:3], v[40:41]
	v_mov_b32_e32 v40, v42
	v_mov_b32_e32 v41, v46
	v_pk_fma_f32 v[2:3], v[86:87], v[40:41], v[2:3]
	v_mov_b32_e32 v46, v43
	v_pk_fma_f32 v[2:3], v[82:83], v[46:47], v[2:3]
	ds_read_b128 v[40:43], v1 offset:2048
	v_add_f32_e32 v2, v39, v2
	v_add_f32_e32 v2, v2, v3
	v_min_f32_e32 v3, 0, v2
	v_mul_f32_e64 v2, |v2|, s4
	v_exp_f32_e32 v2, v2
	s_nop 0
	v_add_f32_e32 v2, 1.0, v2
	v_cmp_gt_f32_e64 s[82:83], s3, v2
	s_nop 1
	v_cndmask_b32_e64 v39, 0, 32, s[82:83]
	v_ldexp_f32 v2, v2, v39
	v_log_f32_e32 v2, v2
	s_nop 0
	v_mul_f32_e32 v39, 0x3f317217, v2
	v_fma_f32 v39, v2, s5, -v39
	v_fmac_f32_e32 v39, 0x3377d1cf, v2
	v_fmac_f32_e32 v39, 0x3f317217, v2
	v_cmp_lt_f32_e64 s[84:85], |v2|, s33
	s_nop 1
	v_cndmask_b32_e64 v2, v2, v39, s[84:85]
	v_cndmask_b32_e64 v39, 0, v208, s[82:83]
	v_sub_f32_e32 v2, v2, v39
	v_sub_f32_e32 v2, v3, v2
	v_mul_f32_e32 v2, 0x3d800000, v2
	v_cndmask_b32_e64 v2, v2, 0, s[12:13]
	v_add_f32_e32 v39, v38, v2
	s_waitcnt lgkmcnt(0)
	v_mul_f32_e32 v2, v76, v41
	v_fmac_f32_e32 v2, v74, v40
	v_fmac_f32_e32 v2, v80, v42
	v_fmac_f32_e32 v2, v78, v43
	ds_read_b128 v[40:43], v1 offset:2064
	v_add_f32_e32 v2, v17, v2
	s_waitcnt lgkmcnt(0)
	v_mul_f32_e32 v3, v77, v41
	v_fmac_f32_e32 v3, v75, v40
	v_fmac_f32_e32 v3, v81, v42
	v_fmac_f32_e32 v3, v79, v43
	ds_read_b128 v[40:43], v1 offset:2080
	ds_read_b128 v[44:47], v1 offset:2096
	v_add_f32_e32 v48, v2, v3
	s_waitcnt lgkmcnt(1)
	v_mov_b32_e32 v2, v40
	s_waitcnt lgkmcnt(0)
	v_mov_b32_e32 v3, v44
	v_mov_b32_e32 v44, v41
	v_pk_mul_f32 v[40:41], v[84:85], v[44:45]
	s_nop 0
	v_pk_fma_f32 v[2:3], v[88:89], v[2:3], v[40:41]
	v_mov_b32_e32 v40, v42
	v_mov_b32_e32 v41, v46
	v_pk_fma_f32 v[2:3], v[86:87], v[40:41], v[2:3]
	v_mov_b32_e32 v46, v43
	v_pk_fma_f32 v[2:3], v[82:83], v[46:47], v[2:3]
	ds_read_b128 v[42:45], v1 offset:2112
	v_add_f32_e32 v2, v48, v2
	v_add_f32_e32 v2, v2, v3
	v_min_f32_e32 v3, 0, v2
	v_mul_f32_e64 v2, |v2|, s4
	v_exp_f32_e32 v2, v2
	s_nop 0
	v_add_f32_e32 v2, 1.0, v2
	v_cmp_gt_f32_e64 s[82:83], s3, v2
	s_nop 1
	v_cndmask_b32_e64 v40, 0, 32, s[82:83]
	v_ldexp_f32 v2, v2, v40
	v_log_f32_e32 v2, v2
	s_nop 0
	v_mul_f32_e32 v40, 0x3f317217, v2
	v_fma_f32 v40, v2, s5, -v40
	v_fmac_f32_e32 v40, 0x3377d1cf, v2
	v_fmac_f32_e32 v40, 0x3f317217, v2
	v_cmp_lt_f32_e64 s[84:85], |v2|, s33
	s_nop 1
	v_cndmask_b32_e64 v2, v2, v40, s[84:85]
	v_cndmask_b32_e64 v40, 0, v208, s[82:83]
	v_sub_f32_e32 v2, v2, v40
	v_sub_f32_e32 v2, v3, v2
	v_mul_f32_e32 v2, 0x3d800000, v2
	v_cndmask_b32_e64 v2, v2, 0, s[12:13]
	v_add_f32_e32 v40, v39, v2
	s_waitcnt lgkmcnt(0)
	v_mul_f32_e32 v2, v76, v43
	v_fmac_f32_e32 v2, v74, v42
	v_fmac_f32_e32 v2, v80, v44
	v_fmac_f32_e32 v2, v78, v45
	ds_read_b128 v[42:45], v1 offset:2128
	v_add_f32_e32 v2, v17, v2
	s_waitcnt lgkmcnt(0)
	v_mul_f32_e32 v3, v77, v43
	v_fmac_f32_e32 v3, v75, v42
	v_fmac_f32_e32 v3, v81, v44
	v_fmac_f32_e32 v3, v79, v45
	ds_read_b128 v[42:45], v1 offset:2144
	ds_read_b128 v[46:49], v1 offset:2160
	v_add_f32_e32 v41, v2, v3
	s_waitcnt lgkmcnt(1)
	v_mov_b32_e32 v2, v42
	s_waitcnt lgkmcnt(0)
; #define LAS __attribute__((address_space(3)))
; __device__ __forceinline__ void gla_prep(LAS unsigned char* lds, const bf16_t* QK, const float* gz, const float* Wg, const float* bias,
;                                          bf16_t* QPimg, bf16_t* KTimg, bf16_t* Aimg, float* dec, int G) {
;     ...
;         float bb[64]; float bs = 0.f;
; #pragma unroll
;         for (int t = 0; t < 64; ++t) {
;             float x = bi;
; #pragma unroll
;             for (int q4 = 0; q4 < 4; ++q4) { const f32x4 g4 = *(const LAS f32x4*)(gzs + t * 16 + q4 * 4); x += g4.x * wg[4 * q4] + g4.y * wg[4 * q4 + 1] + g4.z * wg[4 * q4 + 2] + g4.w * wg[4 * q4 + 3]; }
;             float ls = (fminf(x, 0.f) - __logf(1.f + __expf(-fabsf(x)))) * (1.f / 16.f);
;             if (t >= ntok) ls = 0.f;
;             bs += ls; bb[t] = bs;
	v_mov_b32_e32 v3, v46
	v_mov_b32_e32 v46, v43
	v_pk_mul_f32 v[42:43], v[84:85], v[46:47]
	s_nop 0
	v_pk_fma_f32 v[2:3], v[88:89], v[2:3], v[42:43]
	v_mov_b32_e32 v42, v44
	v_mov_b32_e32 v43, v48
	v_pk_fma_f32 v[2:3], v[86:87], v[42:43], v[2:3]
	v_mov_b32_e32 v48, v45
	v_pk_fma_f32 v[2:3], v[82:83], v[48:49], v[2:3]
	ds_read_b128 v[42:45], v1 offset:2176
	v_add_f32_e32 v2, v41, v2
	v_add_f32_e32 v2, v2, v3
	v_min_f32_e32 v3, 0, v2
	v_mul_f32_e64 v2, |v2|, s4
	v_exp_f32_e32 v2, v2
	s_nop 0
	v_add_f32_e32 v2, 1.0, v2
	v_cmp_gt_f32_e64 s[82:83], s3, v2
	s_nop 1
	v_cndmask_b32_e64 v41, 0, 32, s[82:83]
	v_ldexp_f32 v2, v2, v41
	v_log_f32_e32 v2, v2
	s_nop 0
	v_mul_f32_e32 v41, 0x3f317217, v2
	v_fma_f32 v41, v2, s5, -v41
	v_fmac_f32_e32 v41, 0x3377d1cf, v2
	v_fmac_f32_e32 v41, 0x3f317217, v2
	v_cmp_lt_f32_e64 s[84:85], |v2|, s33
	s_nop 1
	v_cndmask_b32_e64 v2, v2, v41, s[84:85]
	v_cndmask_b32_e64 v41, 0, v208, s[82:83]
	v_sub_f32_e32 v2, v2, v41
	v_sub_f32_e32 v2, v3, v2
	v_mul_f32_e32 v2, 0x3d800000, v2
	v_cndmask_b32_e64 v2, v2, 0, s[12:13]
	v_add_f32_e32 v41, v40, v2
	s_waitcnt lgkmcnt(0)
	v_mul_f32_e32 v2, v76, v43
	v_fmac_f32_e32 v2, v74, v42
	v_fmac_f32_e32 v2, v80, v44
	v_fmac_f32_e32 v2, v78, v45
	ds_read_b128 v[42:45], v1 offset:2192
	v_add_f32_e32 v2, v17, v2
	s_waitcnt lgkmcnt(0)
	v_mul_f32_e32 v3, v77, v43
	v_fmac_f32_e32 v3, v75, v42
	v_fmac_f32_e32 v3, v81, v44
	v_fmac_f32_e32 v3, v79, v45
	ds_read_b128 v[42:45], v1 offset:2208
	ds_read_b128 v[46:49], v1 offset:2224
	v_add_f32_e32 v50, v2, v3
	s_waitcnt lgkmcnt(1)
	v_mov_b32_e32 v2, v42
	s_waitcnt lgkmcnt(0)
	v_mov_b32_e32 v3, v46
	v_mov_b32_e32 v46, v43
	v_pk_mul_f32 v[42:43], v[84:85], v[46:47]
	s_nop 0
	v_pk_fma_f32 v[2:3], v[88:89], v[2:3], v[42:43]
	v_mov_b32_e32 v42, v44
	v_mov_b32_e32 v43, v48
	v_pk_fma_f32 v[2:3], v[86:87], v[42:43], v[2:3]
	v_mov_b32_e32 v48, v45
	v_pk_fma_f32 v[2:3], v[82:83], v[48:49], v[2:3]
	ds_read_b128 v[44:47], v1 offset:2240
	v_add_f32_e32 v2, v50, v2
	v_add_f32_e32 v2, v2, v3
	v_min_f32_e32 v3, 0, v2
	v_mul_f32_e64 v2, |v2|, s4
	v_exp_f32_e32 v2, v2
	s_nop 0
	v_add_f32_e32 v2, 1.0, v2
	v_cmp_gt_f32_e64 s[82:83], s3, v2
	s_nop 1
	v_cndmask_b32_e64 v42, 0, 32, s[82:83]
	v_ldexp_f32 v2, v2, v42
	v_log_f32_e32 v2, v2
	s_nop 0
	v_mul_f32_e32 v42, 0x3f317217, v2
	v_fma_f32 v42, v2, s5, -v42
	v_fmac_f32_e32 v42, 0x3377d1cf, v2
	v_fmac_f32_e32 v42, 0x3f317217, v2
	v_cmp_lt_f32_e64 s[84:85], |v2|, s33
	s_nop 1
	v_cndmask_b32_e64 v2, v2, v42, s[84:85]
	v_cndmask_b32_e64 v42, 0, v208, s[82:83]
	v_sub_f32_e32 v2, v2, v42
	v_sub_f32_e32 v2, v3, v2
	v_mul_f32_e32 v2, 0x3d800000, v2
	v_cndmask_b32_e64 v2, v2, 0, s[12:13]
	v_add_f32_e32 v42, v41, v2
	s_waitcnt lgkmcnt(0)
	v_mul_f32_e32 v2, v76, v45
	v_fmac_f32_e32 v2, v74, v44
	v_fmac_f32_e32 v2, v80, v46
	v_fmac_f32_e32 v2, v78, v47
	ds_read_b128 v[44:47], v1 offset:2256
	v_add_f32_e32 v2, v17, v2
	s_waitcnt lgkmcnt(0)
	v_mul_f32_e32 v3, v77, v45
	v_fmac_f32_e32 v3, v75, v44
	v_fmac_f32_e32 v3, v81, v46
	v_fmac_f32_e32 v3, v79, v47
	ds_read_b128 v[44:47], v1 offset:2272
	ds_read_b128 v[48:51], v1 offset:2288
	v_add_f32_e32 v43, v2, v3
	s_waitcnt lgkmcnt(1)
	v_mov_b32_e32 v2, v44
	s_waitcnt lgkmcnt(0)
	v_mov_b32_e32 v3, v48
	v_mov_b32_e32 v48, v45
	v_pk_mul_f32 v[44:45], v[84:85], v[48:49]
	s_nop 0
	v_pk_fma_f32 v[2:3], v[88:89], v[2:3], v[44:45]
	v_mov_b32_e32 v44, v46
	v_mov_b32_e32 v45, v50
	v_pk_fma_f32 v[2:3], v[86:87], v[44:45], v[2:3]
	v_mov_b32_e32 v50, v47
	v_pk_fma_f32 v[2:3], v[82:83], v[50:51], v[2:3]
	ds_read_b128 v[44:47], v1 offset:2304
	v_add_f32_e32 v2, v43, v2
	v_add_f32_e32 v2, v2, v3
	v_min_f32_e32 v3, 0, v2
	v_mul_f32_e64 v2, |v2|, s4
	v_exp_f32_e32 v2, v2
	s_nop 0
	v_add_f32_e32 v2, 1.0, v2
	v_cmp_gt_f32_e64 s[82:83], s3, v2
	s_nop 1
	v_cndmask_b32_e64 v43, 0, 32, s[82:83]
	v_ldexp_f32 v2, v2, v43
	v_log_f32_e32 v2, v2
	s_nop 0
	v_mul_f32_e32 v43, 0x3f317217, v2
	v_fma_f32 v43, v2, s5, -v43
	v_fmac_f32_e32 v43, 0x3377d1cf, v2
	v_fmac_f32_e32 v43, 0x3f317217, v2
	v_cmp_lt_f32_e64 s[84:85], |v2|, s33
	s_nop 1
	v_cndmask_b32_e64 v2, v2, v43, s[84:85]
	v_cndmask_b32_e64 v43, 0, v208, s[82:83]
	v_sub_f32_e32 v2, v2, v43
	v_sub_f32_e32 v2, v3, v2
	v_mul_f32_e32 v2, 0x3d800000, v2
	v_cndmask_b32_e64 v2, v2, 0, s[12:13]
	v_add_f32_e32 v43, v42, v2
	s_waitcnt lgkmcnt(0)
	v_mul_f32_e32 v2, v76, v45
	v_fmac_f32_e32 v2, v74, v44
	v_fmac_f32_e32 v2, v80, v46
	v_fmac_f32_e32 v2, v78, v47
	ds_read_b128 v[44:47], v1 offset:2320
	v_add_f32_e32 v2, v17, v2
	s_waitcnt lgkmcnt(0)
	v_mul_f32_e32 v3, v77, v45
	v_fmac_f32_e32 v3, v75, v44
	v_fmac_f32_e32 v3, v81, v46
	v_fmac_f32_e32 v3, v79, v47
	ds_read_b128 v[44:47], v1 offset:2336
	ds_read_b128 v[48:51], v1 offset:2352
	v_add_f32_e32 v52, v2, v3
	s_waitcnt lgkmcnt(1)
	v_mov_b32_e32 v2, v44
	s_waitcnt lgkmcnt(0)
	v_mov_b32_e32 v3, v48
	v_mov_b32_e32 v48, v45
	v_pk_mul_f32 v[44:45], v[84:85], v[48:49]
	s_nop 0
	v_pk_fma_f32 v[2:3], v[88:89], v[2:3], v[44:45]
	v_mov_b32_e32 v44, v46
	v_mov_b32_e32 v45, v50
	v_pk_fma_f32 v[2:3], v[86:87], v[44:45], v[2:3]
	v_mov_b32_e32 v50, v47
	v_pk_fma_f32 v[2:3], v[82:83], v[50:51], v[2:3]
	ds_read_b128 v[46:49], v1 offset:2368
	v_add_f32_e32 v2, v52, v2
	v_add_f32_e32 v2, v2, v3
	v_min_f32_e32 v3, 0, v2
	v_mul_f32_e64 v2, |v2|, s4
	v_exp_f32_e32 v2, v2
	s_nop 0
	v_add_f32_e32 v2, 1.0, v2
	v_cmp_gt_f32_e64 s[82:83], s3, v2
	s_nop 1
	v_cndmask_b32_e64 v44, 0, 32, s[82:83]
	v_ldexp_f32 v2, v2, v44
	v_log_f32_e32 v2, v2
	s_nop 0
	v_mul_f32_e32 v44, 0x3f317217, v2
	v_fma_f32 v44, v2, s5, -v44
	v_fmac_f32_e32 v44, 0x3377d1cf, v2
	v_fmac_f32_e32 v44, 0x3f317217, v2
	v_cmp_lt_f32_e64 s[84:85], |v2|, s33
	s_nop 1
	v_cndmask_b32_e64 v2, v2, v44, s[84:85]
	v_cndmask_b32_e64 v44, 0, v208, s[82:83]
	v_sub_f32_e32 v2, v2, v44
	v_sub_f32_e32 v2, v3, v2
	v_mul_f32_e32 v2, 0x3d800000, v2
	v_cndmask_b32_e64 v2, v2, 0, s[12:13]
	v_add_f32_e32 v44, v43, v2
	s_waitcnt lgkmcnt(0)
; #define LAS __attribute__((address_space(3)))
; __device__ __forceinline__ void gla_prep(LAS unsigned char* lds, const bf16_t* QK, const float* gz, const float* Wg, const float* bias,
;                                          bf16_t* QPimg, bf16_t* KTimg, bf16_t* Aimg, float* dec, int G) {
;     ...
;         float bb[64]; float bs = 0.f;
; #pragma unroll
;         for (int t = 0; t < 64; ++t) {
;             float x = bi;
; #pragma unroll
;             for (int q4 = 0; q4 < 4; ++q4) { const f32x4 g4 = *(const LAS f32x4*)(gzs + t * 16 + q4 * 4); x += g4.x * wg[4 * q4] + g4.y * wg[4 * q4 + 1] + g4.z * wg[4 * q4 + 2] + g4.w * wg[4 * q4 + 3]; }
;             float ls = (fminf(x, 0.f) - __logf(1.f + __expf(-fabsf(x)))) * (1.f / 16.f);
;             if (t >= ntok) ls = 0.f;
;             bs += ls; bb[t] = bs;
	v_mul_f32_e32 v2, v76, v47
	v_fmac_f32_e32 v2, v74, v46
	v_fmac_f32_e32 v2, v80, v48
	v_fmac_f32_e32 v2, v78, v49
	ds_read_b128 v[46:49], v1 offset:2384
	v_add_f32_e32 v2, v17, v2
	s_waitcnt lgkmcnt(0)
	v_mul_f32_e32 v3, v77, v47
	v_fmac_f32_e32 v3, v75, v46
	v_fmac_f32_e32 v3, v81, v48
	v_fmac_f32_e32 v3, v79, v49
	ds_read_b128 v[46:49], v1 offset:2400
	ds_read_b128 v[50:53], v1 offset:2416
	v_add_f32_e32 v45, v2, v3
	s_waitcnt lgkmcnt(1)
	v_mov_b32_e32 v2, v46
	s_waitcnt lgkmcnt(0)
	v_mov_b32_e32 v3, v50
	v_mov_b32_e32 v50, v47
	v_pk_mul_f32 v[46:47], v[84:85], v[50:51]
	s_nop 0
	v_pk_fma_f32 v[2:3], v[88:89], v[2:3], v[46:47]
	v_mov_b32_e32 v46, v48
	v_mov_b32_e32 v47, v52
	v_pk_fma_f32 v[2:3], v[86:87], v[46:47], v[2:3]
	v_mov_b32_e32 v52, v49
	v_pk_fma_f32 v[2:3], v[82:83], v[52:53], v[2:3]
	ds_read_b128 v[46:49], v1 offset:2432
	v_add_f32_e32 v2, v45, v2
	v_add_f32_e32 v2, v2, v3
	v_min_f32_e32 v3, 0, v2
	v_mul_f32_e64 v2, |v2|, s4
	v_exp_f32_e32 v2, v2
	s_nop 0
	v_add_f32_e32 v2, 1.0, v2
	v_cmp_gt_f32_e64 s[82:83], s3, v2
	s_nop 1
	v_cndmask_b32_e64 v45, 0, 32, s[82:83]
	v_ldexp_f32 v2, v2, v45
	v_log_f32_e32 v2, v2
	s_nop 0
	v_mul_f32_e32 v45, 0x3f317217, v2
	v_fma_f32 v45, v2, s5, -v45
	v_fmac_f32_e32 v45, 0x3377d1cf, v2
	v_fmac_f32_e32 v45, 0x3f317217, v2
	v_cmp_lt_f32_e64 s[84:85], |v2|, s33
	s_nop 1
	v_cndmask_b32_e64 v2, v2, v45, s[84:85]
	v_cndmask_b32_e64 v45, 0, v208, s[82:83]
	v_sub_f32_e32 v2, v2, v45
	v_sub_f32_e32 v2, v3, v2
	v_mul_f32_e32 v2, 0x3d800000, v2
	v_cndmask_b32_e64 v2, v2, 0, s[12:13]
	v_add_f32_e32 v45, v44, v2
	s_waitcnt lgkmcnt(0)
	v_mul_f32_e32 v2, v76, v47
	v_fmac_f32_e32 v2, v74, v46
	v_fmac_f32_e32 v2, v80, v48
	v_fmac_f32_e32 v2, v78, v49
	ds_read_b128 v[46:49], v1 offset:2448
	v_add_f32_e32 v2, v17, v2
	s_waitcnt lgkmcnt(0)
	v_mul_f32_e32 v3, v77, v47
	v_fmac_f32_e32 v3, v75, v46
	v_fmac_f32_e32 v3, v81, v48
	v_fmac_f32_e32 v3, v79, v49
	ds_read_b128 v[46:49], v1 offset:2464
	ds_read_b128 v[50:53], v1 offset:2480
	v_add_f32_e32 v54, v2, v3
	s_waitcnt lgkmcnt(1)
	v_mov_b32_e32 v2, v46
	s_waitcnt lgkmcnt(0)
	v_mov_b32_e32 v3, v50
	v_mov_b32_e32 v50, v47
	v_pk_mul_f32 v[46:47], v[84:85], v[50:51]
	s_nop 0
	v_pk_fma_f32 v[2:3], v[88:89], v[2:3], v[46:47]
	v_mov_b32_e32 v46, v48
	v_mov_b32_e32 v47, v52
	v_pk_fma_f32 v[2:3], v[86:87], v[46:47], v[2:3]
	v_mov_b32_e32 v52, v49
	v_pk_fma_f32 v[2:3], v[82:83], v[52:53], v[2:3]
	ds_read_b128 v[48:51], v1 offset:2496
	v_add_f32_e32 v2, v54, v2
	v_add_f32_e32 v2, v2, v3
	v_min_f32_e32 v3, 0, v2
	v_mul_f32_e64 v2, |v2|, s4
	v_exp_f32_e32 v2, v2
	s_nop 0
	v_add_f32_e32 v2, 1.0, v2
	v_cmp_gt_f32_e64 s[82:83], s3, v2
	s_nop 1
	v_cndmask_b32_e64 v46, 0, 32, s[82:83]
	v_ldexp_f32 v2, v2, v46
	v_log_f32_e32 v2, v2
	s_nop 0
	v_mul_f32_e32 v46, 0x3f317217, v2
	v_fma_f32 v46, v2, s5, -v46
	v_fmac_f32_e32 v46, 0x3377d1cf, v2
	v_fmac_f32_e32 v46, 0x3f317217, v2
	v_cmp_lt_f32_e64 s[84:85], |v2|, s33
	s_nop 1
	v_cndmask_b32_e64 v2, v2, v46, s[84:85]
	v_cndmask_b32_e64 v46, 0, v208, s[82:83]
	v_sub_f32_e32 v2, v2, v46
	v_sub_f32_e32 v2, v3, v2
	v_mul_f32_e32 v2, 0x3d800000, v2
	v_cndmask_b32_e64 v2, v2, 0, s[12:13]
	v_add_f32_e32 v46, v45, v2
	s_waitcnt lgkmcnt(0)
	v_mul_f32_e32 v2, v76, v49
	v_fmac_f32_e32 v2, v74, v48
	v_fmac_f32_e32 v2, v80, v50
	v_fmac_f32_e32 v2, v78, v51
	ds_read_b128 v[48:51], v1 offset:2512
	v_add_f32_e32 v2, v17, v2
	s_waitcnt lgkmcnt(0)
	v_mul_f32_e32 v3, v77, v49
	v_fmac_f32_e32 v3, v75, v48
	v_fmac_f32_e32 v3, v81, v50
	v_fmac_f32_e32 v3, v79, v51
	ds_read_b128 v[48:51], v1 offset:2528
	ds_read_b128 v[52:55], v1 offset:2544
	v_add_f32_e32 v47, v2, v3
	s_waitcnt lgkmcnt(1)
	v_mov_b32_e32 v2, v48
	s_waitcnt lgkmcnt(0)
	v_mov_b32_e32 v3, v52
	v_mov_b32_e32 v52, v49
	v_pk_mul_f32 v[48:49], v[84:85], v[52:53]
	s_nop 0
	v_pk_fma_f32 v[2:3], v[88:89], v[2:3], v[48:49]
	v_mov_b32_e32 v48, v50
	v_mov_b32_e32 v49, v54
	v_pk_fma_f32 v[2:3], v[86:87], v[48:49], v[2:3]
	v_mov_b32_e32 v54, v51
	v_pk_fma_f32 v[2:3], v[82:83], v[54:55], v[2:3]
	ds_read_b128 v[48:51], v1 offset:2560
	v_add_f32_e32 v2, v47, v2
	v_add_f32_e32 v2, v2, v3
	v_min_f32_e32 v3, 0, v2
	v_mul_f32_e64 v2, |v2|, s4
	v_exp_f32_e32 v2, v2
	s_nop 0
	v_add_f32_e32 v2, 1.0, v2
	v_cmp_gt_f32_e64 s[82:83], s3, v2
	s_nop 1
	v_cndmask_b32_e64 v47, 0, 32, s[82:83]
	v_ldexp_f32 v2, v2, v47
	v_log_f32_e32 v2, v2
	s_nop 0
	v_mul_f32_e32 v47, 0x3f317217, v2
	v_fma_f32 v47, v2, s5, -v47
	v_fmac_f32_e32 v47, 0x3377d1cf, v2
	v_fmac_f32_e32 v47, 0x3f317217, v2
	v_cmp_lt_f32_e64 s[84:85], |v2|, s33
	s_nop 1
	v_cndmask_b32_e64 v2, v2, v47, s[84:85]
	v_cndmask_b32_e64 v47, 0, v208, s[82:83]
	v_sub_f32_e32 v2, v2, v47
	v_sub_f32_e32 v2, v3, v2
	v_mul_f32_e32 v2, 0x3d800000, v2
	v_cndmask_b32_e64 v2, v2, 0, s[12:13]
	v_add_f32_e32 v47, v46, v2
	s_waitcnt lgkmcnt(0)
	v_mul_f32_e32 v2, v76, v49
	v_fmac_f32_e32 v2, v74, v48
	v_fmac_f32_e32 v2, v80, v50
	v_fmac_f32_e32 v2, v78, v51
	ds_read_b128 v[48:51], v1 offset:2576
	v_add_f32_e32 v2, v17, v2
	s_waitcnt lgkmcnt(0)
	v_mul_f32_e32 v3, v77, v49
	v_fmac_f32_e32 v3, v75, v48
	v_fmac_f32_e32 v3, v81, v50
	v_fmac_f32_e32 v3, v79, v51
	ds_read_b128 v[48:51], v1 offset:2592
	ds_read_b128 v[52:55], v1 offset:2608
	v_add_f32_e32 v56, v2, v3
	s_waitcnt lgkmcnt(1)
	v_mov_b32_e32 v2, v48
	s_waitcnt lgkmcnt(0)
; #define LAS __attribute__((address_space(3)))
; __device__ __forceinline__ void gla_prep(LAS unsigned char* lds, const bf16_t* QK, const float* gz, const float* Wg, const float* bias,
;                                          bf16_t* QPimg, bf16_t* KTimg, bf16_t* Aimg, float* dec, int G) {
;     ...
;         float bb[64]; float bs = 0.f;
; #pragma unroll
;         for (int t = 0; t < 64; ++t) {
;             float x = bi;
; #pragma unroll
;             for (int q4 = 0; q4 < 4; ++q4) { const f32x4 g4 = *(const LAS f32x4*)(gzs + t * 16 + q4 * 4); x += g4.x * wg[4 * q4] + g4.y * wg[4 * q4 + 1] + g4.z * wg[4 * q4 + 2] + g4.w * wg[4 * q4 + 3]; }
;             float ls = (fminf(x, 0.f) - __logf(1.f + __expf(-fabsf(x)))) * (1.f / 16.f);
;             if (t >= ntok) ls = 0.f;
;             bs += ls; bb[t] = bs;
	v_mov_b32_e32 v3, v52
	v_mov_b32_e32 v52, v49
	v_pk_mul_f32 v[48:49], v[84:85], v[52:53]
	s_nop 0
	v_pk_fma_f32 v[2:3], v[88:89], v[2:3], v[48:49]
	v_mov_b32_e32 v48, v50
	v_mov_b32_e32 v49, v54
	v_pk_fma_f32 v[2:3], v[86:87], v[48:49], v[2:3]
	v_mov_b32_e32 v54, v51
	v_pk_fma_f32 v[2:3], v[82:83], v[54:55], v[2:3]
	ds_read_b128 v[50:53], v1 offset:2624
	v_add_f32_e32 v2, v56, v2
	v_add_f32_e32 v2, v2, v3
	v_min_f32_e32 v3, 0, v2
	v_mul_f32_e64 v2, |v2|, s4
	v_exp_f32_e32 v2, v2
	s_nop 0
	v_add_f32_e32 v2, 1.0, v2
	v_cmp_gt_f32_e64 s[82:83], s3, v2
	s_nop 1
	v_cndmask_b32_e64 v48, 0, 32, s[82:83]
	v_ldexp_f32 v2, v2, v48
	v_log_f32_e32 v2, v2
	s_nop 0
	v_mul_f32_e32 v48, 0x3f317217, v2
	v_fma_f32 v48, v2, s5, -v48
	v_fmac_f32_e32 v48, 0x3377d1cf, v2
	v_fmac_f32_e32 v48, 0x3f317217, v2
	v_cmp_lt_f32_e64 s[84:85], |v2|, s33
	s_nop 1
	v_cndmask_b32_e64 v2, v2, v48, s[84:85]
	v_cndmask_b32_e64 v48, 0, v208, s[82:83]
	v_sub_f32_e32 v2, v2, v48
	v_sub_f32_e32 v2, v3, v2
	v_mul_f32_e32 v2, 0x3d800000, v2
	v_cndmask_b32_e64 v2, v2, 0, s[12:13]
	v_add_f32_e32 v48, v47, v2
	s_waitcnt lgkmcnt(0)
	v_mul_f32_e32 v2, v76, v51
	v_fmac_f32_e32 v2, v74, v50
	v_fmac_f32_e32 v2, v80, v52
	v_fmac_f32_e32 v2, v78, v53
	ds_read_b128 v[50:53], v1 offset:2640
	v_add_f32_e32 v2, v17, v2
	s_waitcnt lgkmcnt(0)
	v_mul_f32_e32 v3, v77, v51
	v_fmac_f32_e32 v3, v75, v50
	v_fmac_f32_e32 v3, v81, v52
	v_fmac_f32_e32 v3, v79, v53
	ds_read_b128 v[50:53], v1 offset:2656
	ds_read_b128 v[54:57], v1 offset:2672
	v_add_f32_e32 v49, v2, v3
	s_waitcnt lgkmcnt(1)
	v_mov_b32_e32 v2, v50
	s_waitcnt lgkmcnt(0)
	v_mov_b32_e32 v3, v54
	v_mov_b32_e32 v54, v51
	v_pk_mul_f32 v[50:51], v[84:85], v[54:55]
	s_nop 0
	v_pk_fma_f32 v[2:3], v[88:89], v[2:3], v[50:51]
	v_mov_b32_e32 v50, v52
	v_mov_b32_e32 v51, v56
	v_pk_fma_f32 v[2:3], v[86:87], v[50:51], v[2:3]
	v_mov_b32_e32 v56, v53
	v_pk_fma_f32 v[2:3], v[82:83], v[56:57], v[2:3]
	ds_read_b128 v[50:53], v1 offset:2688
	v_add_f32_e32 v2, v49, v2
	v_add_f32_e32 v2, v2, v3
	v_min_f32_e32 v3, 0, v2
	v_mul_f32_e64 v2, |v2|, s4
	v_exp_f32_e32 v2, v2
	s_nop 0
	v_add_f32_e32 v2, 1.0, v2
	v_cmp_gt_f32_e64 s[82:83], s3, v2
	s_nop 1
	v_cndmask_b32_e64 v49, 0, 32, s[82:83]
	v_ldexp_f32 v2, v2, v49
	v_log_f32_e32 v2, v2
	s_nop 0
	v_mul_f32_e32 v49, 0x3f317217, v2
	v_fma_f32 v49, v2, s5, -v49
	v_fmac_f32_e32 v49, 0x3377d1cf, v2
	v_fmac_f32_e32 v49, 0x3f317217, v2
	v_cmp_lt_f32_e64 s[84:85], |v2|, s33
	s_nop 1
	v_cndmask_b32_e64 v2, v2, v49, s[84:85]
	v_cndmask_b32_e64 v49, 0, v208, s[82:83]
	v_sub_f32_e32 v2, v2, v49
	v_sub_f32_e32 v2, v3, v2
	v_mul_f32_e32 v2, 0x3d800000, v2
	v_cndmask_b32_e64 v2, v2, 0, s[12:13]
	v_add_f32_e32 v49, v48, v2
	s_waitcnt lgkmcnt(0)
	v_mul_f32_e32 v2, v76, v51
	v_fmac_f32_e32 v2, v74, v50
	v_fmac_f32_e32 v2, v80, v52
	v_fmac_f32_e32 v2, v78, v53
	ds_read_b128 v[50:53], v1 offset:2704
	v_add_f32_e32 v2, v17, v2
	s_waitcnt lgkmcnt(0)
	v_mul_f32_e32 v3, v77, v51
	v_fmac_f32_e32 v3, v75, v50
	v_fmac_f32_e32 v3, v81, v52
	v_fmac_f32_e32 v3, v79, v53
	ds_read_b128 v[50:53], v1 offset:2720
	ds_read_b128 v[54:57], v1 offset:2736
	v_add_f32_e32 v58, v2, v3
	s_waitcnt lgkmcnt(1)
	v_mov_b32_e32 v2, v50
	s_waitcnt lgkmcnt(0)
	v_mov_b32_e32 v3, v54
	v_mov_b32_e32 v54, v51
	v_pk_mul_f32 v[50:51], v[84:85], v[54:55]
	s_nop 0
	v_pk_fma_f32 v[2:3], v[88:89], v[2:3], v[50:51]
	v_mov_b32_e32 v50, v52
	v_mov_b32_e32 v51, v56
	v_pk_fma_f32 v[2:3], v[86:87], v[50:51], v[2:3]
	v_mov_b32_e32 v56, v53
	v_pk_fma_f32 v[2:3], v[82:83], v[56:57], v[2:3]
	ds_read_b128 v[52:55], v1 offset:2752
	v_add_f32_e32 v2, v58, v2
	v_add_f32_e32 v2, v2, v3
	v_min_f32_e32 v3, 0, v2
	v_mul_f32_e64 v2, |v2|, s4
	v_exp_f32_e32 v2, v2
	s_nop 0
	v_add_f32_e32 v2, 1.0, v2
	v_cmp_gt_f32_e64 s[82:83], s3, v2
	s_nop 1
	v_cndmask_b32_e64 v50, 0, 32, s[82:83]
	v_ldexp_f32 v2, v2, v50
	v_log_f32_e32 v2, v2
	s_nop 0
	v_mul_f32_e32 v50, 0x3f317217, v2
	v_fma_f32 v50, v2, s5, -v50
	v_fmac_f32_e32 v50, 0x3377d1cf, v2
	v_fmac_f32_e32 v50, 0x3f317217, v2
	v_cmp_lt_f32_e64 s[84:85], |v2|, s33
	s_nop 1
	v_cndmask_b32_e64 v2, v2, v50, s[84:85]
	v_cndmask_b32_e64 v50, 0, v208, s[82:83]
	v_sub_f32_e32 v2, v2, v50
	v_sub_f32_e32 v2, v3, v2
	v_mul_f32_e32 v2, 0x3d800000, v2
	v_cndmask_b32_e64 v2, v2, 0, s[12:13]
	v_add_f32_e32 v50, v49, v2
	s_waitcnt lgkmcnt(0)
	v_mul_f32_e32 v2, v76, v53
	v_fmac_f32_e32 v2, v74, v52
	v_fmac_f32_e32 v2, v80, v54
	v_fmac_f32_e32 v2, v78, v55
	ds_read_b128 v[52:55], v1 offset:2768
	v_add_f32_e32 v2, v17, v2
	s_waitcnt lgkmcnt(0)
	v_mul_f32_e32 v3, v77, v53
	v_fmac_f32_e32 v3, v75, v52
	v_fmac_f32_e32 v3, v81, v54
	v_fmac_f32_e32 v3, v79, v55
	ds_read_b128 v[52:55], v1 offset:2784
	ds_read_b128 v[56:59], v1 offset:2800
	v_add_f32_e32 v51, v2, v3
	s_waitcnt lgkmcnt(1)
	v_mov_b32_e32 v2, v52
	s_waitcnt lgkmcnt(0)
	v_mov_b32_e32 v3, v56
	v_mov_b32_e32 v56, v53
	v_pk_mul_f32 v[52:53], v[84:85], v[56:57]
	s_nop 0
	v_pk_fma_f32 v[2:3], v[88:89], v[2:3], v[52:53]
	v_mov_b32_e32 v52, v54
	v_mov_b32_e32 v53, v58
	v_pk_fma_f32 v[2:3], v[86:87], v[52:53], v[2:3]
	v_mov_b32_e32 v58, v55
	v_pk_fma_f32 v[2:3], v[82:83], v[58:59], v[2:3]
	ds_read_b128 v[52:55], v1 offset:2816
	v_add_f32_e32 v2, v51, v2
	v_add_f32_e32 v2, v2, v3
	v_min_f32_e32 v3, 0, v2
	v_mul_f32_e64 v2, |v2|, s4
	v_exp_f32_e32 v2, v2
	s_nop 0
	v_add_f32_e32 v2, 1.0, v2
	v_cmp_gt_f32_e64 s[82:83], s3, v2
	s_nop 1
	v_cndmask_b32_e64 v51, 0, 32, s[82:83]
	v_ldexp_f32 v2, v2, v51
	v_log_f32_e32 v2, v2
	s_nop 0
	v_mul_f32_e32 v51, 0x3f317217, v2
	v_fma_f32 v51, v2, s5, -v51
	v_fmac_f32_e32 v51, 0x3377d1cf, v2
	v_fmac_f32_e32 v51, 0x3f317217, v2
	v_cmp_lt_f32_e64 s[84:85], |v2|, s33
	s_nop 1
	v_cndmask_b32_e64 v2, v2, v51, s[84:85]
	v_cndmask_b32_e64 v51, 0, v208, s[82:83]
	v_sub_f32_e32 v2, v2, v51
	v_sub_f32_e32 v2, v3, v2
	v_mul_f32_e32 v2, 0x3d800000, v2
	v_cndmask_b32_e64 v2, v2, 0, s[12:13]
	v_add_f32_e32 v51, v50, v2
	s_waitcnt lgkmcnt(0)
; #define LAS __attribute__((address_space(3)))
; __device__ __forceinline__ void gla_prep(LAS unsigned char* lds, const bf16_t* QK, const float* gz, const float* Wg, const float* bias,
;                                          bf16_t* QPimg, bf16_t* KTimg, bf16_t* Aimg, float* dec, int G) {
;     ...
;         float bb[64]; float bs = 0.f;
; #pragma unroll
;         for (int t = 0; t < 64; ++t) {
;             float x = bi;
; #pragma unroll
;             for (int q4 = 0; q4 < 4; ++q4) { const f32x4 g4 = *(const LAS f32x4*)(gzs + t * 16 + q4 * 4); x += g4.x * wg[4 * q4] + g4.y * wg[4 * q4 + 1] + g4.z * wg[4 * q4 + 2] + g4.w * wg[4 * q4 + 3]; }
;             float ls = (fminf(x, 0.f) - __logf(1.f + __expf(-fabsf(x)))) * (1.f / 16.f);
;             if (t >= ntok) ls = 0.f;
;             bs += ls; bb[t] = bs;
	v_mul_f32_e32 v2, v76, v53
	v_fmac_f32_e32 v2, v74, v52
	v_fmac_f32_e32 v2, v80, v54
	v_fmac_f32_e32 v2, v78, v55
	ds_read_b128 v[52:55], v1 offset:2832
	v_add_f32_e32 v2, v17, v2
	s_waitcnt lgkmcnt(0)
	v_mul_f32_e32 v3, v77, v53
	v_fmac_f32_e32 v3, v75, v52
	v_fmac_f32_e32 v3, v81, v54
	v_fmac_f32_e32 v3, v79, v55
	ds_read_b128 v[52:55], v1 offset:2848
	ds_read_b128 v[56:59], v1 offset:2864
	v_add_f32_e32 v60, v2, v3
	s_waitcnt lgkmcnt(1)
	v_mov_b32_e32 v2, v52
	s_waitcnt lgkmcnt(0)
	v_mov_b32_e32 v3, v56
	v_mov_b32_e32 v56, v53
	v_pk_mul_f32 v[52:53], v[84:85], v[56:57]
	s_nop 0
	v_pk_fma_f32 v[2:3], v[88:89], v[2:3], v[52:53]
	v_mov_b32_e32 v52, v54
	v_mov_b32_e32 v53, v58
	v_pk_fma_f32 v[2:3], v[86:87], v[52:53], v[2:3]
	v_mov_b32_e32 v58, v55
	v_pk_fma_f32 v[2:3], v[82:83], v[58:59], v[2:3]
	ds_read_b128 v[54:57], v1 offset:2880
	v_add_f32_e32 v2, v60, v2
	v_add_f32_e32 v2, v2, v3
	v_min_f32_e32 v3, 0, v2
	v_mul_f32_e64 v2, |v2|, s4
	v_exp_f32_e32 v2, v2
	s_nop 0
	v_add_f32_e32 v2, 1.0, v2
	v_cmp_gt_f32_e64 s[82:83], s3, v2
	s_nop 1
	v_cndmask_b32_e64 v52, 0, 32, s[82:83]
	v_ldexp_f32 v2, v2, v52
	v_log_f32_e32 v2, v2
	s_nop 0
	v_mul_f32_e32 v52, 0x3f317217, v2
	v_fma_f32 v52, v2, s5, -v52
	v_fmac_f32_e32 v52, 0x3377d1cf, v2
	v_fmac_f32_e32 v52, 0x3f317217, v2
	v_cmp_lt_f32_e64 s[84:85], |v2|, s33
	s_nop 1
	v_cndmask_b32_e64 v2, v2, v52, s[84:85]
	v_cndmask_b32_e64 v52, 0, v208, s[82:83]
	v_sub_f32_e32 v2, v2, v52
	v_sub_f32_e32 v2, v3, v2
	v_mul_f32_e32 v2, 0x3d800000, v2
	v_cndmask_b32_e64 v2, v2, 0, s[12:13]
	v_add_f32_e32 v52, v51, v2
	s_waitcnt lgkmcnt(0)
	v_mul_f32_e32 v2, v76, v55
	v_fmac_f32_e32 v2, v74, v54
	v_fmac_f32_e32 v2, v80, v56
	v_fmac_f32_e32 v2, v78, v57
	ds_read_b128 v[54:57], v1 offset:2896
	v_add_f32_e32 v2, v17, v2
	s_waitcnt lgkmcnt(0)
	v_mul_f32_e32 v3, v77, v55
	v_fmac_f32_e32 v3, v75, v54
	v_fmac_f32_e32 v3, v81, v56
	v_fmac_f32_e32 v3, v79, v57
	ds_read_b128 v[54:57], v1 offset:2912
	ds_read_b128 v[58:61], v1 offset:2928
	v_add_f32_e32 v53, v2, v3
	s_waitcnt lgkmcnt(1)
	v_mov_b32_e32 v2, v54
	s_waitcnt lgkmcnt(0)
	v_mov_b32_e32 v3, v58
	v_mov_b32_e32 v58, v55
	v_pk_mul_f32 v[54:55], v[84:85], v[58:59]
	s_nop 0
	v_pk_fma_f32 v[2:3], v[88:89], v[2:3], v[54:55]
	v_mov_b32_e32 v54, v56
	v_mov_b32_e32 v55, v60
	v_pk_fma_f32 v[2:3], v[86:87], v[54:55], v[2:3]
	v_mov_b32_e32 v60, v57
	v_pk_fma_f32 v[2:3], v[82:83], v[60:61], v[2:3]
	ds_read_b128 v[54:57], v1 offset:2944
	v_add_f32_e32 v2, v53, v2
	v_add_f32_e32 v2, v2, v3
	v_min_f32_e32 v3, 0, v2
	v_mul_f32_e64 v2, |v2|, s4
	v_exp_f32_e32 v2, v2
	s_nop 0
	v_add_f32_e32 v2, 1.0, v2
	v_cmp_gt_f32_e64 s[82:83], s3, v2
	s_nop 1
	v_cndmask_b32_e64 v53, 0, 32, s[82:83]
	v_ldexp_f32 v2, v2, v53
	v_log_f32_e32 v2, v2
	s_nop 0
	v_mul_f32_e32 v53, 0x3f317217, v2
	v_fma_f32 v53, v2, s5, -v53
	v_fmac_f32_e32 v53, 0x3377d1cf, v2
	v_fmac_f32_e32 v53, 0x3f317217, v2
	v_cmp_lt_f32_e64 s[84:85], |v2|, s33
	s_nop 1
	v_cndmask_b32_e64 v2, v2, v53, s[84:85]
	v_cndmask_b32_e64 v53, 0, v208, s[82:83]
	v_sub_f32_e32 v2, v2, v53
	v_sub_f32_e32 v2, v3, v2
	v_mul_f32_e32 v2, 0x3d800000, v2
	v_cndmask_b32_e64 v2, v2, 0, s[12:13]
	v_add_f32_e32 v53, v52, v2
	s_waitcnt lgkmcnt(0)
	v_mul_f32_e32 v2, v76, v55
	v_fmac_f32_e32 v2, v74, v54
	v_fmac_f32_e32 v2, v80, v56
	v_fmac_f32_e32 v2, v78, v57
	ds_read_b128 v[54:57], v1 offset:2960
	v_add_f32_e32 v2, v17, v2
	s_waitcnt lgkmcnt(0)
	v_mul_f32_e32 v3, v77, v55
	v_fmac_f32_e32 v3, v75, v54
	v_fmac_f32_e32 v3, v81, v56
	v_fmac_f32_e32 v3, v79, v57
	ds_read_b128 v[54:57], v1 offset:2976
	ds_read_b128 v[58:61], v1 offset:2992
	v_add_f32_e32 v62, v2, v3
	s_waitcnt lgkmcnt(1)
	v_mov_b32_e32 v2, v54
	s_waitcnt lgkmcnt(0)
	v_mov_b32_e32 v3, v58
	v_mov_b32_e32 v58, v55
	v_pk_mul_f32 v[54:55], v[84:85], v[58:59]
	s_nop 0
	v_pk_fma_f32 v[2:3], v[88:89], v[2:3], v[54:55]
	v_mov_b32_e32 v54, v56
	v_mov_b32_e32 v55, v60
	v_pk_fma_f32 v[2:3], v[86:87], v[54:55], v[2:3]
	v_mov_b32_e32 v60, v57
	v_pk_fma_f32 v[2:3], v[82:83], v[60:61], v[2:3]
	ds_read_b128 v[56:59], v1 offset:3008
	v_add_f32_e32 v2, v62, v2
	v_add_f32_e32 v2, v2, v3
	v_min_f32_e32 v3, 0, v2
	v_mul_f32_e64 v2, |v2|, s4
	v_exp_f32_e32 v2, v2
	s_nop 0
	v_add_f32_e32 v2, 1.0, v2
	v_cmp_gt_f32_e64 s[82:83], s3, v2
	s_nop 1
	v_cndmask_b32_e64 v54, 0, 32, s[82:83]
	v_ldexp_f32 v2, v2, v54
	v_log_f32_e32 v2, v2
	s_nop 0
	v_mul_f32_e32 v54, 0x3f317217, v2
	v_fma_f32 v54, v2, s5, -v54
	v_fmac_f32_e32 v54, 0x3377d1cf, v2
	v_fmac_f32_e32 v54, 0x3f317217, v2
	v_cmp_lt_f32_e64 s[84:85], |v2|, s33
	s_nop 1
	v_cndmask_b32_e64 v2, v2, v54, s[84:85]
	v_cndmask_b32_e64 v54, 0, v208, s[82:83]
	v_sub_f32_e32 v2, v2, v54
	v_sub_f32_e32 v2, v3, v2
	v_mul_f32_e32 v2, 0x3d800000, v2
	v_cndmask_b32_e64 v2, v2, 0, s[12:13]
	v_add_f32_e32 v55, v53, v2
	s_waitcnt lgkmcnt(0)
	v_mul_f32_e32 v2, v76, v57
	v_fmac_f32_e32 v2, v74, v56
	v_fmac_f32_e32 v2, v80, v58
	v_fmac_f32_e32 v2, v78, v59
	ds_read_b128 v[56:59], v1 offset:3024
	v_add_f32_e32 v2, v17, v2
	s_waitcnt lgkmcnt(0)
	v_mul_f32_e32 v3, v77, v57
	v_fmac_f32_e32 v3, v75, v56
	v_fmac_f32_e32 v3, v81, v58
	v_fmac_f32_e32 v3, v79, v59
	ds_read_b128 v[56:59], v1 offset:3040
	ds_read_b128 v[60:63], v1 offset:3056
	v_add_f32_e32 v54, v2, v3
	s_waitcnt lgkmcnt(1)
	v_mov_b32_e32 v2, v56
	s_waitcnt lgkmcnt(0)
; #define LAS __attribute__((address_space(3)))
; __device__ __forceinline__ void gla_prep(LAS unsigned char* lds, const bf16_t* QK, const float* gz, const float* Wg, const float* bias,
;                                          bf16_t* QPimg, bf16_t* KTimg, bf16_t* Aimg, float* dec, int G) {
;     ...
;         float bb[64]; float bs = 0.f;
; #pragma unroll
;         for (int t = 0; t < 64; ++t) {
;             float x = bi;
; #pragma unroll
;             for (int q4 = 0; q4 < 4; ++q4) { const f32x4 g4 = *(const LAS f32x4*)(gzs + t * 16 + q4 * 4); x += g4.x * wg[4 * q4] + g4.y * wg[4 * q4 + 1] + g4.z * wg[4 * q4 + 2] + g4.w * wg[4 * q4 + 3]; }
;             float ls = (fminf(x, 0.f) - __logf(1.f + __expf(-fabsf(x)))) * (1.f / 16.f);
;             if (t >= ntok) ls = 0.f;
;             bs += ls; bb[t] = bs;
	v_mov_b32_e32 v3, v60
	v_mov_b32_e32 v60, v57
	v_pk_mul_f32 v[56:57], v[84:85], v[60:61]
	s_nop 0
	v_pk_fma_f32 v[2:3], v[88:89], v[2:3], v[56:57]
	v_mov_b32_e32 v56, v58
	v_mov_b32_e32 v57, v62
	v_pk_fma_f32 v[2:3], v[86:87], v[56:57], v[2:3]
	v_mov_b32_e32 v62, v59
	v_pk_fma_f32 v[2:3], v[82:83], v[62:63], v[2:3]
	ds_read_b128 v[58:61], v1 offset:3072
	v_add_f32_e32 v2, v54, v2
	v_add_f32_e32 v2, v2, v3
	v_min_f32_e32 v3, 0, v2
	v_mul_f32_e64 v2, |v2|, s4
	v_exp_f32_e32 v2, v2
	s_nop 0
	v_add_f32_e32 v2, 1.0, v2
	v_cmp_gt_f32_e64 s[82:83], s3, v2
	s_nop 1
	v_cndmask_b32_e64 v54, 0, 32, s[82:83]
	v_ldexp_f32 v2, v2, v54
	v_log_f32_e32 v2, v2
	s_nop 0
	v_mul_f32_e32 v54, 0x3f317217, v2
	v_fma_f32 v54, v2, s5, -v54
	v_fmac_f32_e32 v54, 0x3377d1cf, v2
	v_fmac_f32_e32 v54, 0x3f317217, v2
	v_cmp_lt_f32_e64 s[84:85], |v2|, s33
	s_nop 1
	v_cndmask_b32_e64 v2, v2, v54, s[84:85]
	v_cndmask_b32_e64 v54, 0, v208, s[82:83]
	v_sub_f32_e32 v2, v2, v54
	v_sub_f32_e32 v2, v3, v2
	v_mul_f32_e32 v2, 0x3d800000, v2
	v_cndmask_b32_e64 v2, v2, 0, s[12:13]
	v_add_f32_e32 v57, v55, v2
	s_waitcnt lgkmcnt(0)
	v_mul_f32_e32 v2, v76, v59
	v_fmac_f32_e32 v2, v74, v58
	v_fmac_f32_e32 v2, v80, v60
	v_fmac_f32_e32 v2, v78, v61
	ds_read_b128 v[58:61], v1 offset:3088
	v_add_f32_e32 v2, v17, v2
	s_waitcnt lgkmcnt(0)
	v_mul_f32_e32 v3, v77, v59
	v_fmac_f32_e32 v3, v75, v58
	v_fmac_f32_e32 v3, v81, v60
	v_fmac_f32_e32 v3, v79, v61
	ds_read_b128 v[58:61], v1 offset:3104
	ds_read_b128 v[62:65], v1 offset:3120
	v_add_f32_e32 v54, v2, v3
	s_waitcnt lgkmcnt(1)
	v_mov_b32_e32 v2, v58
	s_waitcnt lgkmcnt(0)
	v_mov_b32_e32 v3, v62
	v_mov_b32_e32 v62, v59
	v_pk_mul_f32 v[58:59], v[84:85], v[62:63]
	s_nop 0
	v_pk_fma_f32 v[2:3], v[88:89], v[2:3], v[58:59]
	v_mov_b32_e32 v58, v60
	v_mov_b32_e32 v59, v64
	v_pk_fma_f32 v[2:3], v[86:87], v[58:59], v[2:3]
	v_mov_b32_e32 v64, v61
	v_pk_fma_f32 v[2:3], v[82:83], v[64:65], v[2:3]
	ds_read_b128 v[62:65], v1 offset:3136
	v_add_f32_e32 v2, v54, v2
	v_add_f32_e32 v2, v2, v3
	v_min_f32_e32 v3, 0, v2
	v_mul_f32_e64 v2, |v2|, s4
	v_exp_f32_e32 v2, v2
	s_nop 0
	v_add_f32_e32 v2, 1.0, v2
	v_cmp_gt_f32_e64 s[82:83], s3, v2
	s_nop 1
	v_cndmask_b32_e64 v54, 0, 32, s[82:83]
	v_ldexp_f32 v2, v2, v54
	v_log_f32_e32 v2, v2
	s_nop 0
	v_mul_f32_e32 v54, 0x3f317217, v2
	v_fma_f32 v54, v2, s5, -v54
	v_fmac_f32_e32 v54, 0x3377d1cf, v2
	v_fmac_f32_e32 v54, 0x3f317217, v2
	v_cmp_lt_f32_e64 s[84:85], |v2|, s33
	s_nop 1
	v_cndmask_b32_e64 v2, v2, v54, s[84:85]
	v_cndmask_b32_e64 v54, 0, v208, s[82:83]
	v_sub_f32_e32 v2, v2, v54
	v_sub_f32_e32 v2, v3, v2
	v_mul_f32_e32 v2, 0x3d800000, v2
	v_cndmask_b32_e64 v2, v2, 0, s[12:13]
	v_add_f32_e32 v60, v57, v2
	s_waitcnt lgkmcnt(0)
	v_mul_f32_e32 v2, v76, v63
	v_fmac_f32_e32 v2, v74, v62
	v_fmac_f32_e32 v2, v80, v64
	v_fmac_f32_e32 v2, v78, v65
	ds_read_b128 v[62:65], v1 offset:3152
	v_add_f32_e32 v2, v17, v2
	s_waitcnt lgkmcnt(0)
	v_mul_f32_e32 v3, v77, v63
	v_fmac_f32_e32 v3, v75, v62
	v_fmac_f32_e32 v3, v81, v64
	v_fmac_f32_e32 v3, v79, v65
	ds_read_b128 v[62:65], v1 offset:3168
	ds_read_b128 v[66:69], v1 offset:3184
	v_add_f32_e32 v54, v2, v3
	s_waitcnt lgkmcnt(1)
	v_mov_b32_e32 v2, v62
	s_waitcnt lgkmcnt(0)
	v_mov_b32_e32 v3, v66
	v_mov_b32_e32 v66, v63
	v_pk_mul_f32 v[58:59], v[84:85], v[66:67]
	s_nop 0
	v_pk_fma_f32 v[2:3], v[88:89], v[2:3], v[58:59]
	v_mov_b32_e32 v58, v64
	v_mov_b32_e32 v59, v68
	v_pk_fma_f32 v[2:3], v[86:87], v[58:59], v[2:3]
	v_mov_b32_e32 v68, v65
	v_pk_fma_f32 v[2:3], v[82:83], v[68:69], v[2:3]
	ds_read_b128 v[62:65], v1 offset:3200
	v_add_f32_e32 v2, v54, v2
	v_add_f32_e32 v2, v2, v3
	v_min_f32_e32 v3, 0, v2
	v_mul_f32_e64 v2, |v2|, s4
	v_exp_f32_e32 v2, v2
	s_nop 0
	v_add_f32_e32 v2, 1.0, v2
	v_cmp_gt_f32_e64 s[82:83], s3, v2
	s_nop 1
	v_cndmask_b32_e64 v54, 0, 32, s[82:83]
	v_ldexp_f32 v2, v2, v54
	v_log_f32_e32 v2, v2
	s_nop 0
	v_mul_f32_e32 v54, 0x3f317217, v2
	v_fma_f32 v54, v2, s5, -v54
	v_fmac_f32_e32 v54, 0x3377d1cf, v2
	v_fmac_f32_e32 v54, 0x3f317217, v2
	v_cmp_lt_f32_e64 s[84:85], |v2|, s33
	s_nop 1
	v_cndmask_b32_e64 v2, v2, v54, s[84:85]
	v_cndmask_b32_e64 v54, 0, v208, s[82:83]
	v_sub_f32_e32 v2, v2, v54
	v_sub_f32_e32 v2, v3, v2
	v_mul_f32_e32 v2, 0x3d800000, v2
	v_cndmask_b32_e64 v2, v2, 0, s[12:13]
	v_add_f32_e32 v61, v60, v2
	s_waitcnt lgkmcnt(0)
	v_mul_f32_e32 v2, v76, v63
	v_fmac_f32_e32 v2, v74, v62
	v_fmac_f32_e32 v2, v80, v64
	v_fmac_f32_e32 v2, v78, v65
	ds_read_b128 v[62:65], v1 offset:3216
	v_add_f32_e32 v2, v17, v2
	s_waitcnt lgkmcnt(0)
	v_mul_f32_e32 v3, v77, v63
	v_fmac_f32_e32 v3, v75, v62
	v_fmac_f32_e32 v3, v81, v64
	v_fmac_f32_e32 v3, v79, v65
	ds_read_b128 v[62:65], v1 offset:3232
	ds_read_b128 v[66:69], v1 offset:3248
	v_add_f32_e32 v54, v2, v3
	s_waitcnt lgkmcnt(1)
	v_mov_b32_e32 v2, v62
	s_waitcnt lgkmcnt(0)
	v_mov_b32_e32 v3, v66
	v_mov_b32_e32 v66, v63
	v_pk_mul_f32 v[58:59], v[84:85], v[66:67]
	s_nop 0
	v_pk_fma_f32 v[2:3], v[88:89], v[2:3], v[58:59]
	v_mov_b32_e32 v58, v64
	v_mov_b32_e32 v59, v68
	v_pk_fma_f32 v[2:3], v[86:87], v[58:59], v[2:3]
	v_mov_b32_e32 v68, v65
	v_pk_fma_f32 v[2:3], v[82:83], v[68:69], v[2:3]
	ds_read_b128 v[64:67], v1 offset:3264
	v_add_f32_e32 v2, v54, v2
	v_add_f32_e32 v2, v2, v3
	v_min_f32_e32 v3, 0, v2
	v_mul_f32_e64 v2, |v2|, s4
	v_exp_f32_e32 v2, v2
	s_nop 0
	v_add_f32_e32 v2, 1.0, v2
	v_cmp_gt_f32_e64 s[82:83], s3, v2
	s_nop 1
	v_cndmask_b32_e64 v54, 0, 32, s[82:83]
	v_ldexp_f32 v2, v2, v54
	v_log_f32_e32 v2, v2
	s_nop 0
	v_mul_f32_e32 v54, 0x3f317217, v2
	v_fma_f32 v54, v2, s5, -v54
	v_fmac_f32_e32 v54, 0x3377d1cf, v2
	v_fmac_f32_e32 v54, 0x3f317217, v2
	v_cmp_lt_f32_e64 s[84:85], |v2|, s33
	s_nop 1
	v_cndmask_b32_e64 v2, v2, v54, s[84:85]
	v_cndmask_b32_e64 v54, 0, v208, s[82:83]
	v_sub_f32_e32 v2, v2, v54
	v_sub_f32_e32 v2, v3, v2
	v_mul_f32_e32 v2, 0x3d800000, v2
	v_cndmask_b32_e64 v2, v2, 0, s[12:13]
	v_add_f32_e32 v62, v61, v2
	s_waitcnt lgkmcnt(0)
; #define LAS __attribute__((address_space(3)))
; __device__ __forceinline__ void gla_prep(LAS unsigned char* lds, const bf16_t* QK, const float* gz, const float* Wg, const float* bias,
;                                          bf16_t* QPimg, bf16_t* KTimg, bf16_t* Aimg, float* dec, int G) {
;     ...
;         float bb[64]; float bs = 0.f;
; #pragma unroll
;         for (int t = 0; t < 64; ++t) {
;             float x = bi;
; #pragma unroll
;             for (int q4 = 0; q4 < 4; ++q4) { const f32x4 g4 = *(const LAS f32x4*)(gzs + t * 16 + q4 * 4); x += g4.x * wg[4 * q4] + g4.y * wg[4 * q4 + 1] + g4.z * wg[4 * q4 + 2] + g4.w * wg[4 * q4 + 3]; }
;             float ls = (fminf(x, 0.f) - __logf(1.f + __expf(-fabsf(x)))) * (1.f / 16.f);
;             if (t >= ntok) ls = 0.f;
;             bs += ls; bb[t] = bs;
;         }
	v_mul_f32_e32 v2, v76, v65
	v_fmac_f32_e32 v2, v74, v64
	v_fmac_f32_e32 v2, v80, v66
	v_fmac_f32_e32 v2, v78, v67
	ds_read_b128 v[64:67], v1 offset:3280
	v_add_f32_e32 v2, v17, v2
	s_waitcnt lgkmcnt(0)
	v_mul_f32_e32 v3, v77, v65
	v_fmac_f32_e32 v3, v75, v64
	v_fmac_f32_e32 v3, v81, v66
	v_fmac_f32_e32 v3, v79, v67
	ds_read_b128 v[64:67], v1 offset:3296
	ds_read_b128 v[68:71], v1 offset:3312
	v_add_f32_e32 v54, v2, v3
	s_waitcnt lgkmcnt(1)
	v_mov_b32_e32 v2, v64
	s_waitcnt lgkmcnt(0)
	v_mov_b32_e32 v3, v68
	v_mov_b32_e32 v68, v65
	v_pk_mul_f32 v[58:59], v[84:85], v[68:69]
	s_nop 0
	v_pk_fma_f32 v[2:3], v[88:89], v[2:3], v[58:59]
	v_mov_b32_e32 v58, v66
	v_mov_b32_e32 v59, v70
	v_pk_fma_f32 v[2:3], v[86:87], v[58:59], v[2:3]
	v_mov_b32_e32 v70, v67
	v_pk_fma_f32 v[2:3], v[82:83], v[70:71], v[2:3]
	ds_read_b128 v[64:67], v1 offset:3328
	v_add_f32_e32 v2, v54, v2
	v_add_f32_e32 v2, v2, v3
	v_min_f32_e32 v3, 0, v2
	v_mul_f32_e64 v2, |v2|, s4
	v_exp_f32_e32 v2, v2
	s_nop 0
	v_add_f32_e32 v2, 1.0, v2
	v_cmp_gt_f32_e64 s[82:83], s3, v2
	s_nop 1
	v_cndmask_b32_e64 v54, 0, 32, s[82:83]
	v_ldexp_f32 v2, v2, v54
	v_log_f32_e32 v2, v2
	s_nop 0
	v_mul_f32_e32 v54, 0x3f317217, v2
	v_fma_f32 v54, v2, s5, -v54
	v_fmac_f32_e32 v54, 0x3377d1cf, v2
	v_fmac_f32_e32 v54, 0x3f317217, v2
	v_cmp_lt_f32_e64 s[84:85], |v2|, s33
	s_nop 1
	v_cndmask_b32_e64 v2, v2, v54, s[84:85]
	v_cndmask_b32_e64 v54, 0, v208, s[82:83]
	v_sub_f32_e32 v2, v2, v54
	v_sub_f32_e32 v2, v3, v2
	v_mul_f32_e32 v2, 0x3d800000, v2
	v_cndmask_b32_e64 v2, v2, 0, s[12:13]
	v_add_f32_e32 v63, v62, v2
	s_waitcnt lgkmcnt(0)
	v_mul_f32_e32 v2, v76, v65
	v_fmac_f32_e32 v2, v74, v64
	v_fmac_f32_e32 v2, v80, v66
	v_fmac_f32_e32 v2, v78, v67
	ds_read_b128 v[64:67], v1 offset:3344
	v_add_f32_e32 v2, v17, v2
	s_waitcnt lgkmcnt(0)
	v_mul_f32_e32 v3, v77, v65
	v_fmac_f32_e32 v3, v75, v64
	v_fmac_f32_e32 v3, v81, v66
	v_fmac_f32_e32 v3, v79, v67
	ds_read_b128 v[64:67], v1 offset:3360
	ds_read_b128 v[68:71], v1 offset:3376
	v_add_f32_e32 v54, v2, v3
	s_waitcnt lgkmcnt(1)
	v_mov_b32_e32 v2, v64
	s_waitcnt lgkmcnt(0)
	v_mov_b32_e32 v3, v68
	v_mov_b32_e32 v68, v65
	v_pk_mul_f32 v[58:59], v[84:85], v[68:69]
	s_nop 0
	v_pk_fma_f32 v[2:3], v[88:89], v[2:3], v[58:59]
	v_mov_b32_e32 v58, v66
	v_mov_b32_e32 v59, v70
	v_pk_fma_f32 v[2:3], v[86:87], v[58:59], v[2:3]
	v_mov_b32_e32 v70, v67
	v_pk_fma_f32 v[2:3], v[82:83], v[70:71], v[2:3]
	ds_read_b128 v[66:69], v1 offset:3392
	v_add_f32_e32 v2, v54, v2
	v_add_f32_e32 v2, v2, v3
	v_min_f32_e32 v3, 0, v2
	v_mul_f32_e64 v2, |v2|, s4
	v_exp_f32_e32 v2, v2
	s_nop 0
	v_add_f32_e32 v2, 1.0, v2
	v_cmp_gt_f32_e64 s[82:83], s3, v2
	s_nop 1
	v_cndmask_b32_e64 v54, 0, 32, s[82:83]
	v_ldexp_f32 v2, v2, v54
	v_log_f32_e32 v2, v2
	s_nop 0
	v_mul_f32_e32 v54, 0x3f317217, v2
	v_fma_f32 v54, v2, s5, -v54
	v_fmac_f32_e32 v54, 0x3377d1cf, v2
	v_fmac_f32_e32 v54, 0x3f317217, v2
	v_cmp_lt_f32_e64 s[84:85], |v2|, s33
	s_nop 1
	v_cndmask_b32_e64 v2, v2, v54, s[84:85]
	v_cndmask_b32_e64 v54, 0, v208, s[82:83]
	v_sub_f32_e32 v2, v2, v54
	v_sub_f32_e32 v2, v3, v2
	v_mul_f32_e32 v2, 0x3d800000, v2
	v_cndmask_b32_e64 v2, v2, 0, s[12:13]
	v_add_f32_e32 v64, v63, v2
	s_waitcnt lgkmcnt(0)
	v_mul_f32_e32 v2, v76, v67
	v_fmac_f32_e32 v2, v74, v66
	v_fmac_f32_e32 v2, v80, v68
	v_fmac_f32_e32 v2, v78, v69
	ds_read_b128 v[66:69], v1 offset:3408
	v_add_f32_e32 v2, v17, v2
	s_waitcnt lgkmcnt(0)
	v_mul_f32_e32 v3, v77, v67
	v_fmac_f32_e32 v3, v75, v66
	v_fmac_f32_e32 v3, v81, v68
	v_fmac_f32_e32 v3, v79, v69
	ds_read_b128 v[66:69], v1 offset:3424
	ds_read_b128 v[70:73], v1 offset:3440
	v_add_f32_e32 v54, v2, v3
	s_waitcnt lgkmcnt(1)
	v_mov_b32_e32 v2, v66
	s_waitcnt lgkmcnt(0)
	v_mov_b32_e32 v3, v70
	v_mov_b32_e32 v70, v67
	v_pk_mul_f32 v[58:59], v[84:85], v[70:71]
	s_nop 0
	v_pk_fma_f32 v[2:3], v[88:89], v[2:3], v[58:59]
	v_mov_b32_e32 v58, v68
	v_mov_b32_e32 v59, v72
	v_pk_fma_f32 v[2:3], v[86:87], v[58:59], v[2:3]
	v_mov_b32_e32 v72, v69
	v_pk_fma_f32 v[2:3], v[82:83], v[72:73], v[2:3]
	ds_read_b128 v[66:69], v1 offset:3456
	v_add_f32_e32 v2, v54, v2
	v_add_f32_e32 v2, v2, v3
	v_min_f32_e32 v3, 0, v2
	v_mul_f32_e64 v2, |v2|, s4
	v_exp_f32_e32 v2, v2
	s_nop 0
	v_add_f32_e32 v2, 1.0, v2
	v_cmp_gt_f32_e64 s[82:83], s3, v2
	s_nop 1
	v_cndmask_b32_e64 v54, 0, 32, s[82:83]
	v_ldexp_f32 v2, v2, v54
	v_log_f32_e32 v2, v2
	s_nop 0
	v_mul_f32_e32 v54, 0x3f317217, v2
	v_fma_f32 v54, v2, s5, -v54
	v_fmac_f32_e32 v54, 0x3377d1cf, v2
	v_fmac_f32_e32 v54, 0x3f317217, v2
	v_cmp_lt_f32_e64 s[84:85], |v2|, s33
	s_nop 1
	v_cndmask_b32_e64 v2, v2, v54, s[84:85]
	v_cndmask_b32_e64 v54, 0, v208, s[82:83]
	v_sub_f32_e32 v2, v2, v54
	v_sub_f32_e32 v2, v3, v2
	v_mul_f32_e32 v2, 0x3d800000, v2
	v_cndmask_b32_e64 v2, v2, 0, s[12:13]
	v_add_f32_e32 v65, v64, v2
	s_waitcnt lgkmcnt(0)
	v_mul_f32_e32 v2, v76, v67
	v_fmac_f32_e32 v2, v74, v66
	v_fmac_f32_e32 v2, v80, v68
	v_fmac_f32_e32 v2, v78, v69
	ds_read_b128 v[66:69], v1 offset:3472
	v_add_f32_e32 v2, v17, v2
	s_waitcnt lgkmcnt(0)
	v_mul_f32_e32 v3, v77, v67
	v_fmac_f32_e32 v3, v75, v66
	v_fmac_f32_e32 v3, v81, v68
	v_fmac_f32_e32 v3, v79, v69
	ds_read_b128 v[66:69], v1 offset:3488
	ds_read_b128 v[70:73], v1 offset:3504
	v_add_f32_e32 v54, v2, v3
	s_waitcnt lgkmcnt(1)
	v_mov_b32_e32 v2, v66
	s_waitcnt lgkmcnt(0)
; #define LAS __attribute__((address_space(3)))
; __device__ __forceinline__ void gla_prep(LAS unsigned char* lds, const bf16_t* QK, const float* gz, const float* Wg, const float* bias,
;                                          bf16_t* QPimg, bf16_t* KTimg, bf16_t* Aimg, float* dec, int G) {
;     ...
;         float bb[64]; float bs = 0.f;
; #pragma unroll
;         for (int t = 0; t < 64; ++t) {
;             float x = bi;
; #pragma unroll
;             for (int q4 = 0; q4 < 4; ++q4) { const f32x4 g4 = *(const LAS f32x4*)(gzs + t * 16 + q4 * 4); x += g4.x * wg[4 * q4] + g4.y * wg[4 * q4 + 1] + g4.z * wg[4 * q4 + 2] + g4.w * wg[4 * q4 + 3]; }
;             float ls = (fminf(x, 0.f) - __logf(1.f + __expf(-fabsf(x)))) * (1.f / 16.f);
;             if (t >= ntok) ls = 0.f;
;             bs += ls; bb[t] = bs;
;         }
	v_mov_b32_e32 v3, v70
	v_mov_b32_e32 v70, v67
	v_pk_mul_f32 v[58:59], v[84:85], v[70:71]
	s_nop 0
	v_pk_fma_f32 v[2:3], v[88:89], v[2:3], v[58:59]
	v_mov_b32_e32 v58, v68
	v_mov_b32_e32 v59, v72
	v_pk_fma_f32 v[2:3], v[86:87], v[58:59], v[2:3]
	v_mov_b32_e32 v72, v69
	v_pk_fma_f32 v[2:3], v[82:83], v[72:73], v[2:3]
	ds_read_b128 v[68:71], v1 offset:3520
	v_add_f32_e32 v2, v54, v2
	v_add_f32_e32 v2, v2, v3
	v_min_f32_e32 v3, 0, v2
	v_mul_f32_e64 v2, |v2|, s4
	v_exp_f32_e32 v2, v2
	s_nop 0
	v_add_f32_e32 v2, 1.0, v2
	v_cmp_gt_f32_e64 s[82:83], s3, v2
	s_nop 1
	v_cndmask_b32_e64 v54, 0, 32, s[82:83]
	v_ldexp_f32 v2, v2, v54
	v_log_f32_e32 v2, v2
	s_nop 0
	v_mul_f32_e32 v54, 0x3f317217, v2
	v_fma_f32 v54, v2, s5, -v54
	v_fmac_f32_e32 v54, 0x3377d1cf, v2
	v_fmac_f32_e32 v54, 0x3f317217, v2
	v_cmp_lt_f32_e64 s[84:85], |v2|, s33
	s_nop 1
	v_cndmask_b32_e64 v2, v2, v54, s[84:85]
	v_cndmask_b32_e64 v54, 0, v208, s[82:83]
	v_sub_f32_e32 v2, v2, v54
	v_sub_f32_e32 v2, v3, v2
	v_mul_f32_e32 v2, 0x3d800000, v2
	v_cndmask_b32_e64 v2, v2, 0, s[12:13]
	v_add_f32_e32 v66, v65, v2
	s_waitcnt lgkmcnt(0)
	v_mul_f32_e32 v2, v76, v69
	v_fmac_f32_e32 v2, v74, v68
	v_fmac_f32_e32 v2, v80, v70
	v_fmac_f32_e32 v2, v78, v71
	ds_read_b128 v[68:71], v1 offset:3536
	v_add_f32_e32 v2, v17, v2
	s_waitcnt lgkmcnt(0)
	v_mul_f32_e32 v3, v77, v69
	v_fmac_f32_e32 v3, v75, v68
	v_fmac_f32_e32 v3, v81, v70
	v_fmac_f32_e32 v3, v79, v71
	ds_read_b128 v[68:71], v1 offset:3552
	ds_read_b128 v[196:199], v1 offset:3568
	v_add_f32_e32 v54, v2, v3
	s_waitcnt lgkmcnt(1)
	v_mov_b32_e32 v2, v68
	s_waitcnt lgkmcnt(0)
	v_mov_b32_e32 v3, v196
	v_mov_b32_e32 v196, v69
	v_pk_mul_f32 v[58:59], v[84:85], v[196:197]
	s_nop 0
	v_pk_fma_f32 v[2:3], v[88:89], v[2:3], v[58:59]
	v_mov_b32_e32 v58, v70
	v_mov_b32_e32 v59, v198
	v_pk_fma_f32 v[2:3], v[86:87], v[58:59], v[2:3]
	v_mov_b32_e32 v198, v71
	v_pk_fma_f32 v[2:3], v[82:83], v[198:199], v[2:3]
	ds_read_b128 v[68:71], v1 offset:3584
	v_add_f32_e32 v2, v54, v2
	v_add_f32_e32 v2, v2, v3
	v_min_f32_e32 v3, 0, v2
	v_mul_f32_e64 v2, |v2|, s4
	v_exp_f32_e32 v2, v2
	s_nop 0
	v_add_f32_e32 v2, 1.0, v2
	v_cmp_gt_f32_e64 s[82:83], s3, v2
	s_nop 1
	v_cndmask_b32_e64 v54, 0, 32, s[82:83]
	v_ldexp_f32 v2, v2, v54
	v_log_f32_e32 v2, v2
	s_nop 0
	v_mul_f32_e32 v54, 0x3f317217, v2
	v_fma_f32 v54, v2, s5, -v54
	v_fmac_f32_e32 v54, 0x3377d1cf, v2
	v_fmac_f32_e32 v54, 0x3f317217, v2
	v_cmp_lt_f32_e64 s[84:85], |v2|, s33
	s_nop 1
	v_cndmask_b32_e64 v2, v2, v54, s[84:85]
	v_cndmask_b32_e64 v54, 0, v208, s[82:83]
	v_sub_f32_e32 v2, v2, v54
	v_sub_f32_e32 v2, v3, v2
	v_mul_f32_e32 v2, 0x3d800000, v2
	v_cndmask_b32_e64 v2, v2, 0, s[12:13]
	v_add_f32_e32 v67, v66, v2
	s_waitcnt lgkmcnt(0)
	v_mul_f32_e32 v2, v76, v69
	v_fmac_f32_e32 v2, v74, v68
	v_fmac_f32_e32 v2, v80, v70
	v_fmac_f32_e32 v2, v78, v71
	ds_read_b128 v[68:71], v1 offset:3600
	v_add_f32_e32 v2, v17, v2
	s_waitcnt lgkmcnt(0)
	v_mul_f32_e32 v3, v77, v69
	v_fmac_f32_e32 v3, v75, v68
	v_fmac_f32_e32 v3, v81, v70
	v_fmac_f32_e32 v3, v79, v71
	ds_read_b128 v[68:71], v1 offset:3616
	ds_read_b128 v[196:199], v1 offset:3632
	v_add_f32_e32 v54, v2, v3
	s_waitcnt lgkmcnt(1)
	v_mov_b32_e32 v2, v68
	s_waitcnt lgkmcnt(0)
	v_mov_b32_e32 v3, v196
	v_mov_b32_e32 v196, v69
	v_pk_mul_f32 v[58:59], v[84:85], v[196:197]
	s_nop 0
	v_pk_fma_f32 v[2:3], v[88:89], v[2:3], v[58:59]
	v_mov_b32_e32 v58, v70
	v_mov_b32_e32 v59, v198
	v_pk_fma_f32 v[2:3], v[86:87], v[58:59], v[2:3]
	v_mov_b32_e32 v198, v71
	v_pk_fma_f32 v[2:3], v[82:83], v[198:199], v[2:3]
	ds_read_b128 v[70:73], v1 offset:3648
	v_add_f32_e32 v2, v54, v2
	v_add_f32_e32 v2, v2, v3
	v_min_f32_e32 v3, 0, v2
	v_mul_f32_e64 v2, |v2|, s4
	v_exp_f32_e32 v2, v2
	s_nop 0
	v_add_f32_e32 v2, 1.0, v2
	v_cmp_gt_f32_e64 s[82:83], s3, v2
	s_nop 1
	v_cndmask_b32_e64 v54, 0, 32, s[82:83]
	v_ldexp_f32 v2, v2, v54
	v_log_f32_e32 v2, v2
	s_nop 0
	v_mul_f32_e32 v54, 0x3f317217, v2
	v_fma_f32 v54, v2, s5, -v54
	v_fmac_f32_e32 v54, 0x3377d1cf, v2
	v_fmac_f32_e32 v54, 0x3f317217, v2
	v_cmp_lt_f32_e64 s[84:85], |v2|, s33
	s_nop 1
	v_cndmask_b32_e64 v2, v2, v54, s[84:85]
	v_cndmask_b32_e64 v54, 0, v208, s[82:83]
	v_sub_f32_e32 v2, v2, v54
	v_sub_f32_e32 v2, v3, v2
	v_mul_f32_e32 v2, 0x3d800000, v2
	v_cndmask_b32_e64 v2, v2, 0, s[12:13]
	v_add_f32_e32 v68, v67, v2
	s_waitcnt lgkmcnt(0)
	v_mul_f32_e32 v2, v76, v71
	v_fmac_f32_e32 v2, v74, v70
	v_fmac_f32_e32 v2, v80, v72
	v_fmac_f32_e32 v2, v78, v73
	ds_read_b128 v[70:73], v1 offset:3664
	v_add_f32_e32 v2, v17, v2
	s_waitcnt lgkmcnt(0)
	v_mul_f32_e32 v3, v77, v71
	v_fmac_f32_e32 v3, v75, v70
	v_fmac_f32_e32 v3, v81, v72
	v_fmac_f32_e32 v3, v79, v73
	ds_read_b128 v[70:73], v1 offset:3680
	ds_read_b128 v[196:199], v1 offset:3696
	v_add_f32_e32 v54, v2, v3
	s_waitcnt lgkmcnt(1)
	v_mov_b32_e32 v2, v70
	s_waitcnt lgkmcnt(0)
	v_mov_b32_e32 v3, v196
	v_mov_b32_e32 v196, v71
	v_pk_mul_f32 v[58:59], v[84:85], v[196:197]
	s_nop 0
	v_pk_fma_f32 v[2:3], v[88:89], v[2:3], v[58:59]
	v_mov_b32_e32 v58, v72
	v_mov_b32_e32 v59, v198
	v_pk_fma_f32 v[2:3], v[86:87], v[58:59], v[2:3]
	v_mov_b32_e32 v198, v73
	v_pk_fma_f32 v[2:3], v[82:83], v[198:199], v[2:3]
	ds_read_b128 v[70:73], v1 offset:3712
	v_add_f32_e32 v2, v54, v2
	v_add_f32_e32 v2, v2, v3
	v_min_f32_e32 v3, 0, v2
	v_mul_f32_e64 v2, |v2|, s4
	v_exp_f32_e32 v2, v2
	s_nop 0
	v_add_f32_e32 v2, 1.0, v2
	v_cmp_gt_f32_e64 s[82:83], s3, v2
	s_nop 1
	v_cndmask_b32_e64 v54, 0, 32, s[82:83]
	v_ldexp_f32 v2, v2, v54
	v_log_f32_e32 v2, v2
	s_nop 0
	v_mul_f32_e32 v54, 0x3f317217, v2
	v_fma_f32 v54, v2, s5, -v54
	v_fmac_f32_e32 v54, 0x3377d1cf, v2
	v_fmac_f32_e32 v54, 0x3f317217, v2
	v_cmp_lt_f32_e64 s[84:85], |v2|, s33
	s_nop 1
	v_cndmask_b32_e64 v2, v2, v54, s[84:85]
	v_cndmask_b32_e64 v54, 0, v208, s[82:83]
	v_sub_f32_e32 v2, v2, v54
	v_sub_f32_e32 v2, v3, v2
	v_mul_f32_e32 v2, 0x3d800000, v2
	v_cndmask_b32_e64 v2, v2, 0, s[12:13]
	v_add_f32_e32 v69, v68, v2
	s_waitcnt lgkmcnt(0)
; #define LAS __attribute__((address_space(3)))
; __device__ __forceinline__ void gla_prep(LAS unsigned char* lds, const bf16_t* QK, const float* gz, const float* Wg, const float* bias,
;                                          bf16_t* QPimg, bf16_t* KTimg, bf16_t* Aimg, float* dec, int G) {
;     ...
;         float bb[64]; float bs = 0.f;
; #pragma unroll
;         for (int t = 0; t < 64; ++t) {
;             float x = bi;
; #pragma unroll
;             for (int q4 = 0; q4 < 4; ++q4) { const f32x4 g4 = *(const LAS f32x4*)(gzs + t * 16 + q4 * 4); x += g4.x * wg[4 * q4] + g4.y * wg[4 * q4 + 1] + g4.z * wg[4 * q4 + 2] + g4.w * wg[4 * q4 + 3]; }
;             float ls = (fminf(x, 0.f) - __logf(1.f + __expf(-fabsf(x)))) * (1.f / 16.f);
;             if (t >= ntok) ls = 0.f;
;             bs += ls; bb[t] = bs;
;         }
	v_mul_f32_e32 v2, v76, v71
	v_fmac_f32_e32 v2, v74, v70
	v_fmac_f32_e32 v2, v80, v72
	v_fmac_f32_e32 v2, v78, v73
	ds_read_b128 v[70:73], v1 offset:3728
	v_add_f32_e32 v2, v17, v2
	s_waitcnt lgkmcnt(0)
	v_mul_f32_e32 v3, v77, v71
	v_fmac_f32_e32 v3, v75, v70
	v_fmac_f32_e32 v3, v81, v72
	v_fmac_f32_e32 v3, v79, v73
	ds_read_b128 v[70:73], v1 offset:3744
	ds_read_b128 v[196:199], v1 offset:3760
	v_add_f32_e32 v54, v2, v3
	s_waitcnt lgkmcnt(1)
	v_mov_b32_e32 v2, v70
	s_waitcnt lgkmcnt(0)
	v_mov_b32_e32 v3, v196
	v_mov_b32_e32 v196, v71
	v_pk_mul_f32 v[58:59], v[84:85], v[196:197]
	s_nop 0
	v_pk_fma_f32 v[2:3], v[88:89], v[2:3], v[58:59]
	v_mov_b32_e32 v58, v72
	v_mov_b32_e32 v59, v198
	v_pk_fma_f32 v[2:3], v[86:87], v[58:59], v[2:3]
	v_mov_b32_e32 v198, v73
	v_pk_fma_f32 v[2:3], v[82:83], v[198:199], v[2:3]
	ds_read_b128 v[196:199], v1 offset:3776
	v_add_f32_e32 v2, v54, v2
	v_add_f32_e32 v2, v2, v3
	v_min_f32_e32 v3, 0, v2
	v_mul_f32_e64 v2, |v2|, s4
	v_exp_f32_e32 v2, v2
	s_nop 0
	v_add_f32_e32 v2, 1.0, v2
	v_cmp_gt_f32_e64 s[82:83], s3, v2
	s_nop 1
	v_cndmask_b32_e64 v54, 0, 32, s[82:83]
	v_ldexp_f32 v2, v2, v54
	v_log_f32_e32 v2, v2
	s_nop 0
	v_mul_f32_e32 v54, 0x3f317217, v2
	v_fma_f32 v54, v2, s5, -v54
	v_fmac_f32_e32 v54, 0x3377d1cf, v2
	v_fmac_f32_e32 v54, 0x3f317217, v2
	v_cmp_lt_f32_e64 s[84:85], |v2|, s33
	s_nop 1
	v_cndmask_b32_e64 v2, v2, v54, s[84:85]
	v_cndmask_b32_e64 v54, 0, v208, s[82:83]
	v_sub_f32_e32 v2, v2, v54
	v_sub_f32_e32 v2, v3, v2
	v_mul_f32_e32 v2, 0x3d800000, v2
	v_cndmask_b32_e64 v2, v2, 0, s[12:13]
	v_add_f32_e32 v70, v69, v2
	s_waitcnt lgkmcnt(0)
	v_mul_f32_e32 v2, v76, v197
	v_fmac_f32_e32 v2, v74, v196
	v_fmac_f32_e32 v2, v80, v198
	v_fmac_f32_e32 v2, v78, v199
	ds_read_b128 v[196:199], v1 offset:3792
	v_add_f32_e32 v2, v17, v2
	s_waitcnt lgkmcnt(0)
	v_mul_f32_e32 v3, v77, v197
	v_fmac_f32_e32 v3, v75, v196
	v_fmac_f32_e32 v3, v81, v198
	v_fmac_f32_e32 v3, v79, v199
	ds_read_b128 v[196:199], v1 offset:3808
	ds_read_b128 v[202:205], v1 offset:3824
	v_add_f32_e32 v54, v2, v3
	s_waitcnt lgkmcnt(1)
	v_mov_b32_e32 v2, v196
	s_waitcnt lgkmcnt(0)
	v_mov_b32_e32 v3, v202
	v_mov_b32_e32 v202, v197
	v_pk_mul_f32 v[58:59], v[84:85], v[202:203]
	s_nop 0
	v_pk_fma_f32 v[2:3], v[88:89], v[2:3], v[58:59]
	v_mov_b32_e32 v58, v198
	v_mov_b32_e32 v59, v204
	v_pk_fma_f32 v[2:3], v[86:87], v[58:59], v[2:3]
	v_mov_b32_e32 v204, v199
	v_pk_fma_f32 v[2:3], v[82:83], v[204:205], v[2:3]
	ds_read_b128 v[196:199], v1 offset:3840
	v_add_f32_e32 v2, v54, v2
	v_add_f32_e32 v2, v2, v3
	v_min_f32_e32 v3, 0, v2
	v_mul_f32_e64 v2, |v2|, s4
	v_exp_f32_e32 v2, v2
	s_nop 0
	v_add_f32_e32 v2, 1.0, v2
	v_cmp_gt_f32_e64 s[82:83], s3, v2
	s_nop 1
	v_cndmask_b32_e64 v54, 0, 32, s[82:83]
	v_ldexp_f32 v2, v2, v54
	v_log_f32_e32 v2, v2
	s_nop 0
	v_mul_f32_e32 v54, 0x3f317217, v2
	v_fma_f32 v54, v2, s5, -v54
	v_fmac_f32_e32 v54, 0x3377d1cf, v2
	v_fmac_f32_e32 v54, 0x3f317217, v2
	v_cmp_lt_f32_e64 s[84:85], |v2|, s33
	s_nop 1
	v_cndmask_b32_e64 v2, v2, v54, s[84:85]
	v_cndmask_b32_e64 v54, 0, v208, s[82:83]
	v_sub_f32_e32 v2, v2, v54
	v_sub_f32_e32 v2, v3, v2
	v_mul_f32_e32 v2, 0x3d800000, v2
	v_cndmask_b32_e64 v2, v2, 0, s[12:13]
	v_add_f32_e32 v71, v70, v2
	s_waitcnt lgkmcnt(0)
	v_mul_f32_e32 v2, v76, v197
	v_fmac_f32_e32 v2, v74, v196
	v_fmac_f32_e32 v2, v80, v198
	v_fmac_f32_e32 v2, v78, v199
	ds_read_b128 v[196:199], v1 offset:3856
	v_add_f32_e32 v2, v17, v2
	s_waitcnt lgkmcnt(0)
	v_mul_f32_e32 v3, v77, v197
	v_fmac_f32_e32 v3, v75, v196
	v_fmac_f32_e32 v3, v81, v198
	v_fmac_f32_e32 v3, v79, v199
	ds_read_b128 v[196:199], v1 offset:3872
	ds_read_b128 v[202:205], v1 offset:3888
	v_add_f32_e32 v54, v2, v3
	s_waitcnt lgkmcnt(1)
	v_mov_b32_e32 v2, v196
	s_waitcnt lgkmcnt(0)
	v_mov_b32_e32 v3, v202
	v_mov_b32_e32 v202, v197
	v_pk_mul_f32 v[58:59], v[84:85], v[202:203]
	s_nop 0
	v_pk_fma_f32 v[2:3], v[88:89], v[2:3], v[58:59]
	v_mov_b32_e32 v58, v198
	v_mov_b32_e32 v59, v204
	v_pk_fma_f32 v[2:3], v[86:87], v[58:59], v[2:3]
	v_mov_b32_e32 v204, v199
	v_pk_fma_f32 v[2:3], v[82:83], v[204:205], v[2:3]
	ds_read_b128 v[196:199], v1 offset:3904
	v_add_f32_e32 v2, v54, v2
	v_add_f32_e32 v2, v2, v3
	v_min_f32_e32 v3, 0, v2
	v_mul_f32_e64 v2, |v2|, s4
	v_exp_f32_e32 v2, v2
	s_nop 0
	v_add_f32_e32 v2, 1.0, v2
	v_cmp_gt_f32_e64 s[82:83], s3, v2
	s_nop 1
	v_cndmask_b32_e64 v54, 0, 32, s[82:83]
	v_ldexp_f32 v2, v2, v54
	v_log_f32_e32 v2, v2
	s_nop 0
	v_mul_f32_e32 v54, 0x3f317217, v2
	v_fma_f32 v54, v2, s5, -v54
	v_fmac_f32_e32 v54, 0x3377d1cf, v2
	v_fmac_f32_e32 v54, 0x3f317217, v2
	v_cmp_lt_f32_e64 s[84:85], |v2|, s33
	s_nop 1
	v_cndmask_b32_e64 v2, v2, v54, s[84:85]
	v_cndmask_b32_e64 v54, 0, v208, s[82:83]
	v_sub_f32_e32 v2, v2, v54
	v_sub_f32_e32 v2, v3, v2
	v_mul_f32_e32 v2, 0x3d800000, v2
	v_cndmask_b32_e64 v2, v2, 0, s[12:13]
	v_add_f32_e32 v54, v71, v2
	s_waitcnt lgkmcnt(0)
	v_mul_f32_e32 v2, v76, v197
	v_fmac_f32_e32 v2, v74, v196
	v_fmac_f32_e32 v2, v80, v198
	v_fmac_f32_e32 v2, v78, v199
	ds_read_b128 v[196:199], v1 offset:3920
	v_add_f32_e32 v2, v17, v2
	s_waitcnt lgkmcnt(0)
	v_mul_f32_e32 v3, v77, v197
	v_fmac_f32_e32 v3, v75, v196
	v_fmac_f32_e32 v3, v81, v198
	v_fmac_f32_e32 v3, v79, v199
	ds_read_b128 v[196:199], v1 offset:3936
	ds_read_b128 v[202:205], v1 offset:3952
	v_add_f32_e32 v56, v2, v3
	s_waitcnt lgkmcnt(1)
	v_mov_b32_e32 v2, v196
	s_waitcnt lgkmcnt(0)
; #define LAS __attribute__((address_space(3)))
; __device__ __forceinline__ void gla_prep(LAS unsigned char* lds, const bf16_t* QK, const float* gz, const float* Wg, const float* bias,
;                                          bf16_t* QPimg, bf16_t* KTimg, bf16_t* Aimg, float* dec, int G) {
;     ...
;         float bb[64]; float bs = 0.f;
; #pragma unroll
;         for (int t = 0; t < 64; ++t) {
;             float x = bi;
; #pragma unroll
;             for (int q4 = 0; q4 < 4; ++q4) { const f32x4 g4 = *(const LAS f32x4*)(gzs + t * 16 + q4 * 4); x += g4.x * wg[4 * q4] + g4.y * wg[4 * q4 + 1] + g4.z * wg[4 * q4 + 2] + g4.w * wg[4 * q4 + 3]; }
;             float ls = (fminf(x, 0.f) - __logf(1.f + __expf(-fabsf(x)))) * (1.f / 16.f);
;             if (t >= ntok) ls = 0.f;
;             bs += ls; bb[t] = bs;
;         }
	v_mov_b32_e32 v3, v202
	v_mov_b32_e32 v202, v197
	v_pk_mul_f32 v[58:59], v[84:85], v[202:203]
	s_nop 0
	v_pk_fma_f32 v[2:3], v[88:89], v[2:3], v[58:59]
	v_mov_b32_e32 v58, v198
	v_mov_b32_e32 v59, v204
	v_pk_fma_f32 v[2:3], v[86:87], v[58:59], v[2:3]
	v_mov_b32_e32 v204, v199
	v_pk_fma_f32 v[2:3], v[82:83], v[204:205], v[2:3]
	ds_read_b128 v[196:199], v1 offset:3968
	v_add_f32_e32 v2, v56, v2
	v_add_f32_e32 v2, v2, v3
	v_min_f32_e32 v3, 0, v2
	v_mul_f32_e64 v2, |v2|, s4
	v_exp_f32_e32 v2, v2
	s_nop 0
	v_add_f32_e32 v2, 1.0, v2
	v_cmp_gt_f32_e64 s[82:83], s3, v2
	s_nop 1
	v_cndmask_b32_e64 v56, 0, 32, s[82:83]
	v_ldexp_f32 v2, v2, v56
	v_log_f32_e32 v2, v2
	s_nop 0
	v_mul_f32_e32 v56, 0x3f317217, v2
	v_fma_f32 v56, v2, s5, -v56
	v_fmac_f32_e32 v56, 0x3377d1cf, v2
	v_fmac_f32_e32 v56, 0x3f317217, v2
	v_cmp_lt_f32_e64 s[84:85], |v2|, s33
	s_nop 1
	v_cndmask_b32_e64 v2, v2, v56, s[84:85]
	v_cndmask_b32_e64 v56, 0, v208, s[82:83]
	v_sub_f32_e32 v2, v2, v56
	v_sub_f32_e32 v2, v3, v2
	v_mul_f32_e32 v2, 0x3d800000, v2
	v_cndmask_b32_e64 v2, v2, 0, s[12:13]
	v_add_f32_e32 v56, v54, v2
	s_waitcnt lgkmcnt(0)
	v_mul_f32_e32 v2, v76, v197
	v_fmac_f32_e32 v2, v74, v196
	v_fmac_f32_e32 v2, v80, v198
	v_fmac_f32_e32 v2, v78, v199
	ds_read_b128 v[196:199], v1 offset:3984
	v_add_f32_e32 v2, v17, v2
	s_waitcnt lgkmcnt(0)
	v_mul_f32_e32 v3, v77, v197
	v_fmac_f32_e32 v3, v75, v196
	v_fmac_f32_e32 v3, v81, v198
	v_fmac_f32_e32 v3, v79, v199
	ds_read_b128 v[196:199], v1 offset:4000
	ds_read_b128 v[202:205], v1 offset:4016
	v_add_f32_e32 v72, v2, v3
	s_waitcnt lgkmcnt(1)
	v_mov_b32_e32 v2, v196
	s_waitcnt lgkmcnt(0)
	v_mov_b32_e32 v3, v202
	v_mov_b32_e32 v202, v197
	v_pk_mul_f32 v[58:59], v[84:85], v[202:203]
	s_nop 0
	v_pk_fma_f32 v[2:3], v[88:89], v[2:3], v[58:59]
	v_mov_b32_e32 v58, v198
	v_mov_b32_e32 v59, v204
	v_pk_fma_f32 v[2:3], v[86:87], v[58:59], v[2:3]
	v_mov_b32_e32 v204, v199
	v_pk_fma_f32 v[2:3], v[82:83], v[204:205], v[2:3]
	ds_read_b128 v[196:199], v1 offset:4032
	ds_read_b128 v[202:205], v1 offset:4048
	v_add_f32_e32 v2, v72, v2
	v_add_f32_e32 v2, v2, v3
	v_min_f32_e32 v3, 0, v2
	v_mul_f32_e64 v2, |v2|, s4
	v_exp_f32_e32 v2, v2
	s_nop 0
	v_add_f32_e32 v2, 1.0, v2
	v_cmp_gt_f32_e64 s[82:83], s3, v2
	s_nop 1
	v_cndmask_b32_e64 v58, 0, 32, s[82:83]
	v_ldexp_f32 v2, v2, v58
	v_log_f32_e32 v2, v2
	s_nop 0
	v_mul_f32_e32 v58, 0x3f317217, v2
	v_fma_f32 v58, v2, s5, -v58
	v_fmac_f32_e32 v58, 0x3377d1cf, v2
	v_fmac_f32_e32 v58, 0x3f317217, v2
	v_cmp_lt_f32_e64 s[84:85], |v2|, s33
	s_nop 1
	v_cndmask_b32_e64 v2, v2, v58, s[84:85]
	v_cndmask_b32_e64 v58, 0, v208, s[82:83]
	v_sub_f32_e32 v2, v2, v58
	v_sub_f32_e32 v2, v3, v2
	v_mul_f32_e32 v2, 0x3d800000, v2
	v_cndmask_b32_e64 v2, v2, 0, s[12:13]
	s_waitcnt lgkmcnt(0)
	v_mov_b32_e32 v3, v202
	v_mov_b32_e32 v202, v197
	v_add_f32_e32 v59, v56, v2
	v_mov_b32_e32 v2, v196
	v_pk_mul_f32 v[72:73], v[76:77], v[202:203]
	s_nop 0
	v_pk_fma_f32 v[2:3], v[74:75], v[2:3], v[72:73]
	v_mov_b32_e32 v72, v198
	v_mov_b32_e32 v73, v204
	v_pk_fma_f32 v[2:3], v[80:81], v[72:73], v[2:3]
	v_mov_b32_e32 v204, v199
	v_pk_fma_f32 v[2:3], v[78:79], v[204:205], v[2:3]
	ds_read_b128 v[196:199], v1 offset:4064
	ds_read_b128 v[202:205], v1 offset:4080
	v_add_f32_e32 v2, v17, v2
	v_add_f32_e32 v58, v2, v3
	s_waitcnt lgkmcnt(1)
	v_mov_b32_e32 v2, v196
	s_waitcnt lgkmcnt(0)
	v_mov_b32_e32 v3, v202
	v_mov_b32_e32 v202, v197
	v_pk_mul_f32 v[72:73], v[84:85], v[202:203]
	s_nop 0
	v_pk_fma_f32 v[2:3], v[88:89], v[2:3], v[72:73]
	v_mov_b32_e32 v72, v198
	v_mov_b32_e32 v73, v204
	v_pk_fma_f32 v[2:3], v[86:87], v[72:73], v[2:3]
	v_mov_b32_e32 v204, v199
	v_pk_fma_f32 v[2:3], v[82:83], v[204:205], v[2:3]
	ds_read_u16 v72, v139
	v_add_f32_e32 v2, v58, v2
	v_add_f32_e32 v3, v2, v3
	v_min_f32_e32 v2, 0, v3
	v_mul_f32_e64 v3, |v3|, s4
	v_exp_f32_e32 v3, v3
	s_nop 0
	v_add_f32_e32 v3, 1.0, v3
	v_cmp_gt_f32_e64 s[82:83], s3, v3
	s_nop 1
	v_cndmask_b32_e64 v58, 0, 32, s[82:83]
	v_ldexp_f32 v3, v3, v58
	v_log_f32_e32 v3, v3
	s_nop 0
	v_mul_f32_e32 v58, 0x3f317217, v3
	v_fma_f32 v58, v3, s5, -v58
	v_fmac_f32_e32 v58, 0x3377d1cf, v3
	v_fmac_f32_e32 v58, 0x3f317217, v3
	v_cmp_lt_f32_e64 s[84:85], |v3|, s33
	v_readlane_b32 s4, v254, 17
	v_readlane_b32 s5, v254, 18
	v_cndmask_b32_e64 v3, v3, v58, s[84:85]
	v_cndmask_b32_e64 v58, 0, v208, s[82:83]
	v_sub_f32_e32 v3, v3, v58
	v_sub_f32_e32 v2, v2, v3
	v_mul_f32_e32 v2, 0x3d800000, v2
	v_cndmask_b32_e64 v2, v2, 0, s[12:13]
	v_add_f32_e32 v58, v59, v2
; __device__ __forceinline__ unsigned pk_bf16(float lo, float hi) { f32x2_t v = {lo, hi}; bf16x2_t b = __builtin_convertvector(v, bf16x2_t); return __builtin_bit_cast(unsigned, b); }
; __device__ __forceinline__ float bf2f(bf16_t v) { return __uint_as_float((unsigned)v << 16); }
; __device__ __forceinline__ bf16_t f2bf(float f) { return (bf16_t)(pk_bf16(f, 0.f) & 0xffffu); }
; __device__ __forceinline__ void gla_prep(LAS unsigned char* lds, const bf16_t* QK, const float* gz, const float* Wg, const float* bias,
;                                          bf16_t* QPimg, bf16_t* KTimg, bf16_t* Aimg, float* dec, int G) {
;     ...
; #pragma unroll
;         for (int t8 = 0; t8 < 8; ++t8) {
;             float kh[8];
; #pragma unroll
;             for (int tt = 0; tt < 8; ++tt) { const int t = t8 * 8 + tt;
;                 const float qv = bf2f(Qs[t * GP_PITCH + tid]), kv = bf2f(Ks[t * GP_PITCH + tid]);
;                 Qs[t * GP_PITCH + tid] = f2bf(qv * __expf(bb[t]) * 0.08838834764831845f);
;                 Ks[t * GP_PITCH + tid] = f2bf(kv * __expf(-bb[t]));
;                 kh[tt] = kv * __expf(blast - bb[t]); }
;             u32x4 w; w.x = pk_bf16(kh[0], kh[1]); w.y = pk_bf16(kh[2], kh[3]); w.z = pk_bf16(kh[4], kh[5]); w.w = pk_bf16(kh[6], kh[7]);
;             *(u32x4*)(KTimg + ((((size_t)u * 4 + hh) * 8 + t8) * 128 + dk) * 8) = w;
;         }
.Lprep_gate_done:
	ds_read_u16 v2, v137 offset:4096
	v_mul_f32_e32 v3, 0x3fb8aa3b, v4
	v_exp_f32_e32 v3, v3
	s_waitcnt lgkmcnt(0)
	v_lshlrev_b32_e32 v2, 16, v2
	v_mul_f32_e32 v2, v3, v2
	v_mul_f32_e32 v2, 0x3db504f3, v2
	v_cvt_pk_bf16_f32 v2, v2, s0
	ds_write_b16 v137, v2 offset:4096
	v_mul_f32_e32 v2, 0xbfb8aa3b, v4
	ds_read_u16 v3, v137 offset:5136
	v_exp_f32_e32 v73, v2
	v_sub_f32_e32 v2, v58, v4
	v_mul_f32_e32 v4, 0x3fb8aa3b, v5
	v_exp_f32_e32 v4, v4
	s_waitcnt lgkmcnt(0)
	v_lshlrev_b32_e32 v3, 16, v3
	v_mul_f32_e32 v2, 0x3fb8aa3b, v2
	v_exp_f32_e32 v2, v2
	v_mul_f32_e32 v3, v4, v3
	v_mul_f32_e32 v3, 0x3db504f3, v3
	v_cvt_pk_bf16_f32 v3, v3, s0
	ds_write_b16 v137, v3 offset:5136
	v_mul_f32_e32 v3, 0xbfb8aa3b, v5
	v_exp_f32_e32 v196, v3
	v_sub_f32_e32 v3, v58, v5
	ds_read_u16 v5, v140
	v_mul_f32_e32 v3, 0x3fb8aa3b, v3
	v_exp_f32_e32 v3, v3
	v_lshlrev_b32_e32 v4, 16, v72
	v_mul_f32_e32 v72, v73, v4
	s_waitcnt lgkmcnt(0)
	v_lshlrev_b32_e32 v5, 16, v5
	v_pk_mul_f32 v[2:3], v[2:3], v[4:5]
	v_mul_f32_e32 v4, v196, v5
	v_cvt_pk_bf16_f32 v4, v4, s0
	ds_write_b16 v140, v4
	ds_read_u16 v4, v137 offset:6176
	v_mul_f32_e32 v5, 0x3fb8aa3b, v6
	v_exp_f32_e32 v5, v5
	v_cvt_pk_bf16_f32 v72, v72, s0
	ds_write_b16 v139, v72
	s_waitcnt lgkmcnt(1)
	v_lshlrev_b32_e32 v4, 16, v4
	v_mul_f32_e32 v4, v5, v4
	v_mul_f32_e32 v4, 0x3db504f3, v4
	v_cvt_pk_bf16_f32 v4, v4, s0
	ds_write_b16 v137, v4 offset:6176
	v_mul_f32_e32 v4, 0xbfb8aa3b, v6
	ds_read_u16 v5, v137 offset:7216
	v_exp_f32_e32 v72, v4
	v_sub_f32_e32 v4, v58, v6
	v_mul_f32_e32 v6, 0x3fb8aa3b, v7
	v_exp_f32_e32 v6, v6
	s_waitcnt lgkmcnt(0)
	v_lshlrev_b32_e32 v5, 16, v5
	v_mul_f32_e32 v4, 0x3fb8aa3b, v4
	v_exp_f32_e32 v4, v4
	v_mul_f32_e32 v5, v6, v5
	v_mul_f32_e32 v5, 0x3db504f3, v5
	v_cvt_pk_bf16_f32 v5, v5, s0
	ds_write_b16 v137, v5 offset:7216
	v_mul_f32_e32 v5, 0xbfb8aa3b, v7
	v_exp_f32_e32 v73, v5
	v_sub_f32_e32 v5, v58, v7
	ds_read_u16 v6, v141
	ds_read_u16 v7, v142
	v_mul_f32_e32 v5, 0x3fb8aa3b, v5
	v_exp_f32_e32 v5, v5
	v_cvt_pk_bf16_f32 v2, v2, v3
	s_waitcnt lgkmcnt(1)
	v_lshlrev_b32_e32 v6, 16, v6
	s_waitcnt lgkmcnt(0)
	v_lshlrev_b32_e32 v7, 16, v7
	v_mul_f32_e32 v72, v72, v6
	v_pk_mul_f32 v[4:5], v[4:5], v[6:7]
	v_mul_f32_e32 v6, v73, v7
	v_cvt_pk_bf16_f32 v6, v6, s0
	ds_write_b16 v142, v6
	ds_read_u16 v6, v137 offset:8256
	v_mul_f32_e32 v7, 0x3fb8aa3b, v8
	v_exp_f32_e32 v7, v7
	v_cvt_pk_bf16_f32 v72, v72, s0
	ds_write_b16 v141, v72
	s_waitcnt lgkmcnt(1)
	v_lshlrev_b32_e32 v6, 16, v6
	v_mul_f32_e32 v6, v7, v6
	v_mul_f32_e32 v6, 0x3db504f3, v6
	v_cvt_pk_bf16_f32 v6, v6, s0
	ds_write_b16 v137, v6 offset:8256
	v_mul_f32_e32 v6, 0xbfb8aa3b, v8
	v_exp_f32_e32 v196, v6
	v_sub_f32_e32 v6, v58, v8
	ds_read_u16 v8, v143
	ds_read_u16 v7, v137 offset:9296
	v_mul_f32_e32 v72, 0x3fb8aa3b, v10
	v_exp_f32_e32 v72, v72
	ds_read_u16 v73, v144
	v_mul_f32_e32 v6, 0x3fb8aa3b, v6
	s_waitcnt lgkmcnt(1)
	v_lshlrev_b32_e32 v7, 16, v7
	v_mul_f32_e32 v7, v72, v7
	v_mul_f32_e32 v7, 0x3db504f3, v7
	v_cvt_pk_bf16_f32 v7, v7, s0
	ds_write_b16 v137, v7 offset:9296
	v_mul_f32_e32 v7, 0xbfb8aa3b, v10
	v_exp_f32_e32 v197, v7
	v_lshlrev_b32_e32 v72, 16, v8
	v_mul_f32_e32 v8, v196, v72
	s_waitcnt lgkmcnt(1)
	v_lshlrev_b32_e32 v73, 16, v73
	v_cvt_pk_bf16_f32 v8, v8, s0
	ds_write_b16 v143, v8
	v_mul_f32_e32 v8, v197, v73
	v_cvt_pk_bf16_f32 v8, v8, s0
	ds_write_b16 v144, v8
	ds_read_u16 v8, v137 offset:10336
	v_sub_f32_e32 v7, v58, v10
	v_mul_f32_e32 v10, 0x3fb8aa3b, v11
	v_exp_f32_e32 v10, v10
	v_mul_f32_e32 v7, 0x3fb8aa3b, v7
	s_waitcnt lgkmcnt(0)
	v_lshlrev_b32_e32 v8, 16, v8
	v_exp_f32_e32 v6, v6
	v_exp_f32_e32 v7, v7
	v_mul_f32_e32 v8, v10, v8
	v_mul_f32_e32 v8, 0x3db504f3, v8
	v_cvt_pk_bf16_f32 v8, v8, s0
	ds_write_b16 v137, v8 offset:10336
	v_mul_f32_e32 v8, 0xbfb8aa3b, v11
	v_pk_mul_f32 v[6:7], v[6:7], v[72:73]
	ds_read_u16 v10, v145
	v_exp_f32_e32 v72, v8
	v_sub_f32_e32 v8, v58, v11
	ds_read_u16 v11, v137 offset:11376
	v_mul_f32_e32 v73, 0x3fb8aa3b, v9
	v_exp_f32_e32 v73, v73
	v_mul_f32_e32 v8, 0x3fb8aa3b, v8
	v_exp_f32_e32 v8, v8
	s_waitcnt lgkmcnt(0)
	v_lshlrev_b32_e32 v11, 16, v11
	v_mul_f32_e32 v11, v73, v11
	v_mul_f32_e32 v11, 0x3db504f3, v11
	v_cvt_pk_bf16_f32 v11, v11, s0
	ds_read_u16 v73, v146
	ds_write_b16 v137, v11 offset:11376
	v_mul_f32_e32 v11, 0xbfb8aa3b, v9
	v_sub_f32_e32 v9, v58, v9
	v_mul_f32_e32 v9, 0x3fb8aa3b, v9
	v_exp_f32_e32 v196, v11
	v_exp_f32_e32 v9, v9
	v_lshlrev_b32_e32 v10, 16, v10
	s_waitcnt lgkmcnt(1)
	v_lshlrev_b32_e32 v11, 16, v73
	v_mul_f32_e32 v72, v72, v10
	v_pk_mul_f32 v[8:9], v[8:9], v[10:11]
	v_mul_f32_e32 v10, v196, v11
	v_cvt_pk_bf16_f32 v10, v10, s0
	v_cvt_pk_bf16_f32 v3, v4, v5
	v_cvt_pk_bf16_f32 v4, v6, v7
	v_lshl_add_u64 v[6:7], s[8:9], 0, v[94:95]
	ds_write_b16 v146, v10
	v_add_co_u32_e64 v10, s[82:83], s2, v6
	s_mov_b32 s2, 0x18871000
	s_nop 0
	v_addc_co_u32_e64 v11, s[82:83], 0, v7, s[82:83]
	v_cvt_pk_bf16_f32 v5, v8, v9
	v_add_co_u32_e64 v8, s[82:83], s2, v6
	v_cvt_pk_bf16_f32 v72, v72, s0
	s_nop 0
	v_addc_co_u32_e64 v9, s[82:83], 0, v7, s[82:83]
	global_store_dwordx4 v[8:9], v[2:5], off offset:-4096
	ds_read_u16 v2, v137 offset:12416
	ds_read_u16 v4, v147
	v_mul_f32_e32 v3, 0x3fb8aa3b, v12
	v_exp_f32_e32 v3, v3
	v_mul_f32_e32 v5, 0x3fb8aa3b, v13
	s_waitcnt lgkmcnt(1)
	v_lshlrev_b32_e32 v2, 16, v2
	v_exp_f32_e32 v5, v5
	v_mul_f32_e32 v2, v3, v2
	ds_read_u16 v3, v137 offset:13456
	v_mul_f32_e32 v2, 0x3db504f3, v2
	v_cvt_pk_bf16_f32 v2, v2, s0
	ds_write_b16 v137, v2 offset:12416
	v_mul_f32_e32 v2, 0xbfb8aa3b, v12
	s_waitcnt lgkmcnt(1)
; __device__ __forceinline__ unsigned pk_bf16(float lo, float hi) { f32x2_t v = {lo, hi}; bf16x2_t b = __builtin_convertvector(v, bf16x2_t); return __builtin_bit_cast(unsigned, b); }
; __device__ __forceinline__ float bf2f(bf16_t v) { return __uint_as_float((unsigned)v << 16); }
; __device__ __forceinline__ bf16_t f2bf(float f) { return (bf16_t)(pk_bf16(f, 0.f) & 0xffffu); }
; __device__ __forceinline__ void gla_prep(LAS unsigned char* lds, const bf16_t* QK, const float* gz, const float* Wg, const float* bias,
;                                          bf16_t* QPimg, bf16_t* KTimg, bf16_t* Aimg, float* dec, int G) {
;     ...
; #pragma unroll
;         for (int t8 = 0; t8 < 8; ++t8) {
;             float kh[8];
; #pragma unroll
;             for (int tt = 0; tt < 8; ++tt) { const int t = t8 * 8 + tt;
;                 const float qv = bf2f(Qs[t * GP_PITCH + tid]), kv = bf2f(Ks[t * GP_PITCH + tid]);
;                 Qs[t * GP_PITCH + tid] = f2bf(qv * __expf(bb[t]) * 0.08838834764831845f);
;                 Ks[t * GP_PITCH + tid] = f2bf(kv * __expf(-bb[t]));
;                 kh[tt] = kv * __expf(blast - bb[t]); }
;             u32x4 w; w.x = pk_bf16(kh[0], kh[1]); w.y = pk_bf16(kh[2], kh[3]); w.z = pk_bf16(kh[4], kh[5]); w.w = pk_bf16(kh[6], kh[7]);
;             *(u32x4*)(KTimg + ((((size_t)u * 4 + hh) * 8 + t8) * 128 + dk) * 8) = w;
;         }
	v_lshlrev_b32_e32 v3, 16, v3
	v_mul_f32_e32 v3, v5, v3
	v_mul_f32_e32 v3, 0x3db504f3, v3
	v_cvt_pk_bf16_f32 v3, v3, s0
	ds_write_b16 v137, v3 offset:13456
	v_mul_f32_e32 v3, 0xbfb8aa3b, v13
	ds_write_b16 v145, v72
	v_exp_f32_e32 v72, v2
	v_sub_f32_e32 v2, v58, v12
	ds_read_u16 v5, v148
	v_exp_f32_e32 v12, v3
	v_sub_f32_e32 v3, v58, v13
	v_mul_f32_e32 v2, 0x3fb8aa3b, v2
	v_mul_f32_e32 v3, 0x3fb8aa3b, v3
	v_exp_f32_e32 v2, v2
	v_exp_f32_e32 v3, v3
	v_lshlrev_b32_e32 v4, 16, v4
	s_waitcnt lgkmcnt(0)
	v_lshlrev_b32_e32 v5, 16, v5
	v_mul_f32_e32 v13, v72, v4
	v_pk_mul_f32 v[2:3], v[2:3], v[4:5]
	v_mul_f32_e32 v4, v12, v5
	v_cvt_pk_bf16_f32 v4, v4, s0
	ds_write_b16 v148, v4
	ds_read_u16 v4, v137 offset:14496
	ds_read_u16 v12, v149
	v_mul_f32_e32 v5, 0x3fb8aa3b, v18
	v_exp_f32_e32 v5, v5
	v_cvt_pk_bf16_f32 v13, v13, s0
	s_waitcnt lgkmcnt(1)
	v_lshlrev_b32_e32 v4, 16, v4
	ds_write_b16 v147, v13
	v_mul_f32_e32 v4, v5, v4
	ds_read_u16 v5, v137 offset:15536
	v_mul_f32_e32 v13, 0x3fb8aa3b, v19
	v_exp_f32_e32 v13, v13
	v_mul_f32_e32 v4, 0x3db504f3, v4
	v_cvt_pk_bf16_f32 v4, v4, s0
	s_waitcnt lgkmcnt(0)
	v_lshlrev_b32_e32 v5, 16, v5
	v_mul_f32_e32 v5, v13, v5
	v_mul_f32_e32 v5, 0x3db504f3, v5
	v_cvt_pk_bf16_f32 v5, v5, s0
	ds_write_b16 v137, v4 offset:14496
	v_mul_f32_e32 v4, 0xbfb8aa3b, v18
	ds_write_b16 v137, v5 offset:15536
	v_mul_f32_e32 v5, 0xbfb8aa3b, v19
	v_exp_f32_e32 v72, v4
	v_sub_f32_e32 v4, v58, v18
	ds_read_u16 v13, v150
	v_exp_f32_e32 v18, v5
	v_sub_f32_e32 v5, v58, v19
	v_mul_f32_e32 v4, 0x3fb8aa3b, v4
	v_mul_f32_e32 v5, 0x3fb8aa3b, v5
	v_exp_f32_e32 v4, v4
	v_exp_f32_e32 v5, v5
	v_lshlrev_b32_e32 v12, 16, v12
	s_waitcnt lgkmcnt(0)
	v_lshlrev_b32_e32 v13, 16, v13
	v_mul_f32_e32 v19, v72, v12
	v_pk_mul_f32 v[4:5], v[4:5], v[12:13]
	v_mul_f32_e32 v12, v18, v13
	v_cvt_pk_bf16_f32 v12, v12, s0
	ds_write_b16 v150, v12
	ds_read_u16 v12, v137 offset:16576
	ds_read_u16 v18, v151
	v_mul_f32_e32 v13, 0x3fb8aa3b, v20
	v_exp_f32_e32 v13, v13
	v_cvt_pk_bf16_f32 v19, v19, s0
	s_waitcnt lgkmcnt(1)
	v_lshlrev_b32_e32 v12, 16, v12
	ds_write_b16 v149, v19
	v_mul_f32_e32 v12, v13, v12
	ds_read_u16 v13, v137 offset:17616
	v_mul_f32_e32 v19, 0x3fb8aa3b, v22
	v_exp_f32_e32 v19, v19
	v_mul_f32_e32 v12, 0x3db504f3, v12
	v_cvt_pk_bf16_f32 v12, v12, s0
	s_waitcnt lgkmcnt(0)
	v_lshlrev_b32_e32 v13, 16, v13
	v_mul_f32_e32 v13, v19, v13
	v_mul_f32_e32 v13, 0x3db504f3, v13
	v_cvt_pk_bf16_f32 v13, v13, s0
	ds_write_b16 v137, v12 offset:16576
	v_mul_f32_e32 v12, 0xbfb8aa3b, v20
	ds_write_b16 v137, v13 offset:17616
	v_mul_f32_e32 v13, 0xbfb8aa3b, v22
	v_exp_f32_e32 v72, v12
	v_sub_f32_e32 v12, v58, v20
	ds_read_u16 v19, v152
	v_exp_f32_e32 v20, v13
	v_sub_f32_e32 v13, v58, v22
	v_mul_f32_e32 v12, 0x3fb8aa3b, v12
	v_mul_f32_e32 v13, 0x3fb8aa3b, v13
	v_exp_f32_e32 v12, v12
	v_exp_f32_e32 v13, v13
	v_lshlrev_b32_e32 v18, 16, v18
	s_waitcnt lgkmcnt(0)
	v_lshlrev_b32_e32 v19, 16, v19
	v_mul_f32_e32 v22, v72, v18
	v_pk_mul_f32 v[12:13], v[12:13], v[18:19]
	v_mul_f32_e32 v18, v20, v19
	v_cvt_pk_bf16_f32 v18, v18, s0
	ds_write_b16 v152, v18
	ds_read_u16 v18, v137 offset:18656
	ds_read_u16 v20, v153
	v_mul_f32_e32 v19, 0x3fb8aa3b, v23
	v_exp_f32_e32 v19, v19
	v_cvt_pk_bf16_f32 v22, v22, s0
	s_waitcnt lgkmcnt(1)
	v_lshlrev_b32_e32 v18, 16, v18
	ds_write_b16 v151, v22
	v_mul_f32_e32 v18, v19, v18
	v_mul_f32_e32 v18, 0x3db504f3, v18
	v_cvt_pk_bf16_f32 v18, v18, s0
	ds_write_b16 v137, v18 offset:18656
	v_mul_f32_e32 v18, 0xbfb8aa3b, v23
	ds_read_u16 v19, v137 offset:19696
	v_exp_f32_e32 v22, v18
	v_sub_f32_e32 v18, v58, v23
	v_mul_f32_e32 v23, 0x3fb8aa3b, v21
	v_exp_f32_e32 v23, v23
	s_waitcnt lgkmcnt(0)
	v_lshlrev_b32_e32 v19, 16, v19
	v_mul_f32_e32 v18, 0x3fb8aa3b, v18
	v_exp_f32_e32 v18, v18
	v_mul_f32_e32 v19, v23, v19
	v_mul_f32_e32 v19, 0x3db504f3, v19
	v_cvt_pk_bf16_f32 v19, v19, s0
	ds_write_b16 v137, v19 offset:19696
	v_mul_f32_e32 v19, 0xbfb8aa3b, v21
	ds_read_u16 v23, v162
	v_exp_f32_e32 v72, v19
	v_sub_f32_e32 v19, v58, v21
	v_mul_f32_e32 v19, 0x3fb8aa3b, v19
	v_exp_f32_e32 v19, v19
	v_lshlrev_b32_e32 v20, 16, v20
	s_waitcnt lgkmcnt(0)
	v_lshlrev_b32_e32 v21, 16, v23
	v_cvt_pk_bf16_f32 v2, v2, v3
	v_pk_mul_f32 v[18:19], v[18:19], v[20:21]
	v_cvt_pk_bf16_f32 v3, v4, v5
	v_cvt_pk_bf16_f32 v4, v12, v13
	v_cvt_pk_bf16_f32 v5, v18, v19
	global_store_dwordx4 v[10:11], v[2:5], off offset:2048
	ds_read_u16 v2, v137 offset:20736
	ds_read_u16 v4, v163
	v_mul_f32_e32 v3, 0x3fb8aa3b, v24
	v_exp_f32_e32 v3, v3
	v_mul_f32_e32 v5, 0x3fb8aa3b, v25
	s_waitcnt lgkmcnt(1)
	v_lshlrev_b32_e32 v2, 16, v2
	v_exp_f32_e32 v5, v5
	v_mul_f32_e32 v2, v3, v2
	v_mul_f32_e32 v2, 0x3db504f3, v2
	v_cvt_pk_bf16_f32 v2, v2, s0
	ds_write_b16 v137, v2 offset:20736
	v_mul_f32_e32 v2, 0xbfb8aa3b, v24
	v_exp_f32_e32 v10, v2
	ds_read_u16 v3, v137 offset:21776
	s_waitcnt lgkmcnt(2)
	v_lshlrev_b32_e32 v4, 16, v4
	v_sub_f32_e32 v2, v58, v24
	v_mul_f32_e32 v10, v10, v4
	v_cvt_pk_bf16_f32 v10, v10, s0
	ds_write_b16 v163, v10
	ds_read_u16 v10, v165
	s_waitcnt lgkmcnt(2)
	v_lshlrev_b32_e32 v3, 16, v3
	v_mul_f32_e32 v3, v5, v3
	v_mul_f32_e32 v3, 0x3db504f3, v3
	v_cvt_pk_bf16_f32 v3, v3, s0
	ds_write_b16 v137, v3 offset:21776
	v_mul_f32_e32 v3, 0xbfb8aa3b, v25
	ds_read_u16 v5, v164
	v_exp_f32_e32 v11, v3
	v_sub_f32_e32 v3, v58, v25
	v_mul_f32_e32 v2, 0x3fb8aa3b, v2
	v_mul_f32_e32 v3, 0x3fb8aa3b, v3
	v_exp_f32_e32 v2, v2
	v_exp_f32_e32 v3, v3
	s_waitcnt lgkmcnt(0)
	v_lshlrev_b32_e32 v5, 16, v5
	v_lshlrev_b32_e32 v10, 16, v10
	v_mul_f32_e32 v22, v22, v20
	v_pk_mul_f32 v[2:3], v[2:3], v[4:5]
	v_mul_f32_e32 v4, v11, v5
	v_cvt_pk_bf16_f32 v4, v4, s0
	ds_write_b16 v164, v4
	ds_read_u16 v4, v137 offset:22816
	v_mul_f32_e32 v5, 0x3fb8aa3b, v26
	v_exp_f32_e32 v5, v5
	v_mul_f32_e32 v11, 0x3fb8aa3b, v27
	v_exp_f32_e32 v11, v11
	s_waitcnt lgkmcnt(0)
; __device__ __forceinline__ unsigned pk_bf16(float lo, float hi) { f32x2_t v = {lo, hi}; bf16x2_t b = __builtin_convertvector(v, bf16x2_t); return __builtin_bit_cast(unsigned, b); }
; __device__ __forceinline__ float bf2f(bf16_t v) { return __uint_as_float((unsigned)v << 16); }
; __device__ __forceinline__ bf16_t f2bf(float f) { return (bf16_t)(pk_bf16(f, 0.f) & 0xffffu); }
; __device__ __forceinline__ void gla_prep(LAS unsigned char* lds, const bf16_t* QK, const float* gz, const float* Wg, const float* bias,
;                                          bf16_t* QPimg, bf16_t* KTimg, bf16_t* Aimg, float* dec, int G) {
;     ...
; #pragma unroll
;         for (int t8 = 0; t8 < 8; ++t8) {
;             float kh[8];
; #pragma unroll
;             for (int tt = 0; tt < 8; ++tt) { const int t = t8 * 8 + tt;
;                 const float qv = bf2f(Qs[t * GP_PITCH + tid]), kv = bf2f(Ks[t * GP_PITCH + tid]);
;                 Qs[t * GP_PITCH + tid] = f2bf(qv * __expf(bb[t]) * 0.08838834764831845f);
;                 Ks[t * GP_PITCH + tid] = f2bf(kv * __expf(-bb[t]));
;                 kh[tt] = kv * __expf(blast - bb[t]); }
;             u32x4 w; w.x = pk_bf16(kh[0], kh[1]); w.y = pk_bf16(kh[2], kh[3]); w.z = pk_bf16(kh[4], kh[5]); w.w = pk_bf16(kh[6], kh[7]);
;             *(u32x4*)(KTimg + ((((size_t)u * 4 + hh) * 8 + t8) * 128 + dk) * 8) = w;
;         }
	v_lshlrev_b32_e32 v4, 16, v4
	v_mul_f32_e32 v4, v5, v4
	v_mul_f32_e32 v4, 0x3db504f3, v4
	v_cvt_pk_bf16_f32 v4, v4, s0
	ds_write_b16 v137, v4 offset:22816
	v_mul_f32_e32 v4, 0xbfb8aa3b, v26
	v_exp_f32_e32 v12, v4
	ds_read_u16 v5, v137 offset:23856
	v_sub_f32_e32 v4, v58, v26
	v_mul_f32_e32 v4, 0x3fb8aa3b, v4
	v_mul_f32_e32 v12, v12, v10
	v_cvt_pk_bf16_f32 v12, v12, s0
	ds_write_b16 v165, v12
	ds_read_u16 v12, v167
	s_waitcnt lgkmcnt(2)
	v_lshlrev_b32_e32 v5, 16, v5
	v_mul_f32_e32 v5, v11, v5
	v_mul_f32_e32 v5, 0x3db504f3, v5
	v_cvt_pk_bf16_f32 v5, v5, s0
	ds_write_b16 v137, v5 offset:23856
	v_mul_f32_e32 v5, 0xbfb8aa3b, v27
	ds_read_u16 v11, v166
	v_exp_f32_e32 v13, v5
	v_sub_f32_e32 v5, v58, v27
	v_mul_f32_e32 v5, 0x3fb8aa3b, v5
	v_exp_f32_e32 v4, v4
	v_exp_f32_e32 v5, v5
	s_waitcnt lgkmcnt(0)
	v_lshlrev_b32_e32 v11, 16, v11
	v_lshlrev_b32_e32 v12, 16, v12
	v_mul_f32_e32 v20, v72, v21
	v_pk_mul_f32 v[4:5], v[4:5], v[10:11]
	v_mul_f32_e32 v10, v13, v11
	v_cvt_pk_bf16_f32 v10, v10, s0
	ds_write_b16 v166, v10
	ds_read_u16 v10, v137 offset:24896
	v_mul_f32_e32 v11, 0x3fb8aa3b, v28
	v_exp_f32_e32 v11, v11
	v_mul_f32_e32 v13, 0x3fb8aa3b, v30
	v_exp_f32_e32 v13, v13
	s_waitcnt lgkmcnt(0)
	v_lshlrev_b32_e32 v10, 16, v10
	v_mul_f32_e32 v10, v11, v10
	v_mul_f32_e32 v10, 0x3db504f3, v10
	v_cvt_pk_bf16_f32 v10, v10, s0
	ds_write_b16 v137, v10 offset:24896
	v_mul_f32_e32 v10, 0xbfb8aa3b, v28
	v_exp_f32_e32 v18, v10
	ds_read_u16 v11, v137 offset:25936
	v_sub_f32_e32 v10, v58, v28
	v_mul_f32_e32 v10, 0x3fb8aa3b, v10
	v_mul_f32_e32 v18, v18, v12
	v_cvt_pk_bf16_f32 v18, v18, s0
	ds_write_b16 v167, v18
	ds_read_u16 v18, v169
	s_waitcnt lgkmcnt(2)
	v_lshlrev_b32_e32 v11, 16, v11
	v_mul_f32_e32 v11, v13, v11
	v_mul_f32_e32 v11, 0x3db504f3, v11
	v_cvt_pk_bf16_f32 v11, v11, s0
	ds_write_b16 v137, v11 offset:25936
	v_mul_f32_e32 v11, 0xbfb8aa3b, v30
	ds_read_u16 v13, v168
	v_exp_f32_e32 v19, v11
	v_sub_f32_e32 v11, v58, v30
	v_mul_f32_e32 v11, 0x3fb8aa3b, v11
	v_exp_f32_e32 v10, v10
	v_exp_f32_e32 v11, v11
	s_waitcnt lgkmcnt(0)
	v_lshlrev_b32_e32 v13, 16, v13
	v_cvt_pk_bf16_f32 v20, v20, s0
	ds_write_b16 v162, v20
	v_pk_mul_f32 v[10:11], v[10:11], v[12:13]
	v_mul_f32_e32 v12, v19, v13
	v_cvt_pk_bf16_f32 v12, v12, s0
	ds_write_b16 v168, v12
	ds_read_u16 v12, v137 offset:26976
	v_mul_f32_e32 v13, 0x3fb8aa3b, v31
	v_exp_f32_e32 v13, v13
	v_mul_f32_e32 v19, 0x3fb8aa3b, v29
	v_exp_f32_e32 v19, v19
	s_waitcnt lgkmcnt(0)
	v_lshlrev_b32_e32 v12, 16, v12
	v_mul_f32_e32 v12, v13, v12
	ds_read_u16 v13, v137 offset:28016
	v_mul_f32_e32 v12, 0x3db504f3, v12
	v_cvt_pk_bf16_f32 v12, v12, s0
	ds_write_b16 v137, v12 offset:26976
	v_mul_f32_e32 v12, 0xbfb8aa3b, v31
	s_waitcnt lgkmcnt(1)
	v_lshlrev_b32_e32 v13, 16, v13
	v_mul_f32_e32 v13, v19, v13
	v_mul_f32_e32 v13, 0x3db504f3, v13
	v_cvt_pk_bf16_f32 v13, v13, s0
	ds_write_b16 v137, v13 offset:28016
	v_mul_f32_e32 v13, 0xbfb8aa3b, v29
	v_exp_f32_e32 v20, v12
	v_sub_f32_e32 v12, v58, v31
	ds_read_u16 v19, v170
	v_exp_f32_e32 v21, v13
	v_sub_f32_e32 v13, v58, v29
	v_mul_f32_e32 v12, 0x3fb8aa3b, v12
	v_mul_f32_e32 v13, 0x3fb8aa3b, v13
	v_exp_f32_e32 v12, v12
	v_exp_f32_e32 v13, v13
	v_lshlrev_b32_e32 v18, 16, v18
	s_waitcnt lgkmcnt(0)
	v_lshlrev_b32_e32 v19, 16, v19
	v_cvt_pk_bf16_f32 v2, v2, v3
	v_pk_mul_f32 v[12:13], v[12:13], v[18:19]
	v_cvt_pk_bf16_f32 v3, v4, v5
	v_cvt_pk_bf16_f32 v4, v10, v11
	v_cvt_pk_bf16_f32 v5, v12, v13
	global_store_dwordx4 v[8:9], v[2:5], off
	ds_read_u16 v2, v137 offset:29056
	ds_read_u16 v4, v171
	v_mul_f32_e32 v3, 0x3fb8aa3b, v32
	v_exp_f32_e32 v3, v3
	v_mul_f32_e32 v5, 0x3fb8aa3b, v33
	s_waitcnt lgkmcnt(1)
	v_lshlrev_b32_e32 v2, 16, v2
	v_exp_f32_e32 v5, v5
	v_mul_f32_e32 v2, v3, v2
	ds_read_u16 v3, v137 offset:30096
	v_mul_f32_e32 v2, 0x3db504f3, v2
	v_cvt_pk_bf16_f32 v2, v2, s0
	ds_write_b16 v137, v2 offset:29056
	v_mul_f32_e32 v2, 0xbfb8aa3b, v32
	s_waitcnt lgkmcnt(1)
	v_lshlrev_b32_e32 v3, 16, v3
	v_mul_f32_e32 v3, v5, v3
	v_mul_f32_e32 v3, 0x3db504f3, v3
	v_cvt_pk_bf16_f32 v3, v3, s0
	ds_write_b16 v137, v3 offset:30096
	v_mul_f32_e32 v3, 0xbfb8aa3b, v33
	v_exp_f32_e32 v10, v2
	v_sub_f32_e32 v2, v58, v32
	ds_read_u16 v5, v172
	v_exp_f32_e32 v11, v3
	v_sub_f32_e32 v3, v58, v33
	v_mul_f32_e32 v2, 0x3fb8aa3b, v2
	v_mul_f32_e32 v3, 0x3fb8aa3b, v3
	v_exp_f32_e32 v2, v2
	v_exp_f32_e32 v3, v3
	v_lshlrev_b32_e32 v4, 16, v4
	s_waitcnt lgkmcnt(0)
	v_lshlrev_b32_e32 v5, 16, v5
	v_mul_f32_e32 v10, v10, v4
	v_pk_mul_f32 v[2:3], v[2:3], v[4:5]
	v_mul_f32_e32 v4, v11, v5
	v_cvt_pk_bf16_f32 v4, v4, s0
	v_cvt_pk_bf16_f32 v10, v10, s0
	ds_write_b16 v172, v4
	ds_read_u16 v4, v137 offset:31136
	ds_read_u16 v5, v173
	ds_write_b16 v171, v10
	v_mul_f32_e32 v10, 0x3fb8aa3b, v34
	v_exp_f32_e32 v10, v10
	s_waitcnt lgkmcnt(2)
	v_lshlrev_b32_e32 v4, 16, v4
	s_waitcnt lgkmcnt(1)
	v_lshlrev_b32_e32 v5, 16, v5
	v_mul_f32_e32 v11, 0x3fb8aa3b, v35
	v_mul_f32_e32 v4, v10, v4
	v_mul_f32_e32 v4, 0x3db504f3, v4
	v_cvt_pk_bf16_f32 v4, v4, s0
	ds_write_b16 v137, v4 offset:31136
	v_mul_f32_e32 v4, 0xbfb8aa3b, v34
	v_exp_f32_e32 v4, v4
	v_exp_f32_e32 v11, v11
	ds_read_u16 v10, v174
	v_mul_f32_e32 v12, 0x3fb8aa3b, v36
	v_mul_f32_e32 v4, v4, v5
	v_cvt_pk_bf16_f32 v4, v4, s0
	ds_write_b16 v173, v4
	v_sub_f32_e32 v4, v58, v34
	v_mul_f32_e32 v4, 0x3fb8aa3b, v4
	v_exp_f32_e32 v4, v4
	s_waitcnt lgkmcnt(1)
	v_lshlrev_b32_e32 v10, 16, v10
	v_exp_f32_e32 v12, v12
	v_mul_f32_e32 v13, 0x3fb8aa3b, v37
	v_mul_f32_e32 v4, v4, v5
	ds_read_u16 v5, v137 offset:32176
	v_exp_f32_e32 v13, v13
	v_mul_f32_e32 v20, v20, v18
	v_mul_f32_e32 v18, v21, v19
	v_cvt_pk_bf16_f32 v18, v18, s0
	s_waitcnt lgkmcnt(0)
; __device__ __forceinline__ unsigned pk_bf16(float lo, float hi) { f32x2_t v = {lo, hi}; bf16x2_t b = __builtin_convertvector(v, bf16x2_t); return __builtin_bit_cast(unsigned, b); }
; __device__ __forceinline__ float bf2f(bf16_t v) { return __uint_as_float((unsigned)v << 16); }
; __device__ __forceinline__ bf16_t f2bf(float f) { return (bf16_t)(pk_bf16(f, 0.f) & 0xffffu); }
; __device__ __forceinline__ void gla_prep(LAS unsigned char* lds, const bf16_t* QK, const float* gz, const float* Wg, const float* bias,
;                                          bf16_t* QPimg, bf16_t* KTimg, bf16_t* Aimg, float* dec, int G) {
;     ...
; #pragma unroll
;         for (int t8 = 0; t8 < 8; ++t8) {
;             float kh[8];
; #pragma unroll
;             for (int tt = 0; tt < 8; ++tt) { const int t = t8 * 8 + tt;
;                 const float qv = bf2f(Qs[t * GP_PITCH + tid]), kv = bf2f(Ks[t * GP_PITCH + tid]);
;                 Qs[t * GP_PITCH + tid] = f2bf(qv * __expf(bb[t]) * 0.08838834764831845f);
;                 Ks[t * GP_PITCH + tid] = f2bf(kv * __expf(-bb[t]));
;                 kh[tt] = kv * __expf(blast - bb[t]); }
;             u32x4 w; w.x = pk_bf16(kh[0], kh[1]); w.y = pk_bf16(kh[2], kh[3]); w.z = pk_bf16(kh[4], kh[5]); w.w = pk_bf16(kh[6], kh[7]);
;             *(u32x4*)(KTimg + ((((size_t)u * 4 + hh) * 8 + t8) * 128 + dk) * 8) = w;
;         }
	v_lshlrev_b32_e32 v5, 16, v5
	v_mul_f32_e32 v5, v11, v5
	v_mul_f32_e32 v5, 0x3db504f3, v5
	v_cvt_pk_bf16_f32 v5, v5, s0
	ds_write_b16 v137, v5 offset:32176
	v_mul_f32_e32 v5, 0xbfb8aa3b, v35
	v_exp_f32_e32 v5, v5
	ds_read_u16 v11, v175
	ds_write_b16 v170, v18
	v_mul_f32_e32 v18, 0x3fb8aa3b, v38
	v_mul_f32_e32 v5, v5, v10
	v_cvt_pk_bf16_f32 v5, v5, s0
	ds_write_b16 v174, v5
	v_sub_f32_e32 v5, v58, v35
	v_mul_f32_e32 v5, 0x3fb8aa3b, v5
	v_exp_f32_e32 v5, v5
	s_waitcnt lgkmcnt(2)
	v_lshlrev_b32_e32 v11, 16, v11
	v_exp_f32_e32 v18, v18
	v_mul_f32_e32 v19, 0x3fb8aa3b, v39
	v_mul_f32_e32 v5, v5, v10
	ds_read_u16 v10, v137 offset:33216
	v_exp_f32_e32 v19, v19
	v_cvt_pk_bf16_f32 v2, v2, v3
	v_cvt_pk_bf16_f32 v3, v4, v5
	s_mov_b32 s2, 0x18872000
	s_waitcnt lgkmcnt(0)
	v_lshlrev_b32_e32 v10, 16, v10
	v_mul_f32_e32 v10, v12, v10
	v_mul_f32_e32 v10, 0x3db504f3, v10
	v_cvt_pk_bf16_f32 v10, v10, s0
	ds_write_b16 v137, v10 offset:33216
	v_mul_f32_e32 v10, 0xbfb8aa3b, v36
	v_exp_f32_e32 v10, v10
	ds_read_u16 v12, v176
	v_cvt_pk_bf16_f32 v22, v22, s0
	v_cvt_pk_bf16_f32 v20, v20, s0
	v_mul_f32_e32 v10, v10, v11
	v_cvt_pk_bf16_f32 v10, v10, s0
	ds_write_b16 v175, v10
	v_sub_f32_e32 v10, v58, v36
	v_mul_f32_e32 v10, 0x3fb8aa3b, v10
	v_exp_f32_e32 v10, v10
	s_waitcnt lgkmcnt(1)
	v_lshlrev_b32_e32 v12, 16, v12
	ds_write_b16 v153, v22
	ds_write_b16 v169, v20
	v_mul_f32_e32 v10, v10, v11
	ds_read_u16 v11, v137 offset:34256
	v_lshl_add_u64 v[94:95], v[94:95], 0, s[4:5]
	s_waitcnt lgkmcnt(0)
	v_lshlrev_b32_e32 v11, 16, v11
	v_mul_f32_e32 v11, v13, v11
	v_mul_f32_e32 v11, 0x3db504f3, v11
	v_cvt_pk_bf16_f32 v11, v11, s0
	ds_write_b16 v137, v11 offset:34256
	v_mul_f32_e32 v11, 0xbfb8aa3b, v37
	v_exp_f32_e32 v11, v11
	ds_read_u16 v13, v177
	v_mul_f32_e32 v11, v11, v12
	v_cvt_pk_bf16_f32 v11, v11, s0
	ds_write_b16 v176, v11
	v_sub_f32_e32 v11, v58, v37
	v_mul_f32_e32 v11, 0x3fb8aa3b, v11
	v_exp_f32_e32 v11, v11
	s_waitcnt lgkmcnt(1)
	v_lshlrev_b32_e32 v13, 16, v13
	v_mul_f32_e32 v11, v11, v12
	ds_read_u16 v12, v137 offset:35296
	v_cvt_pk_bf16_f32 v4, v10, v11
	v_mul_f32_e32 v10, 0x3fb8aa3b, v44
	v_exp_f32_e32 v10, v10
	v_mul_f32_e32 v11, 0x3fb8aa3b, v45
	s_waitcnt lgkmcnt(0)
	v_lshlrev_b32_e32 v12, 16, v12
	v_mul_f32_e32 v12, v18, v12
	v_mul_f32_e32 v12, 0x3db504f3, v12
	v_cvt_pk_bf16_f32 v12, v12, s0
	ds_write_b16 v137, v12 offset:35296
	v_mul_f32_e32 v12, 0xbfb8aa3b, v38
	v_exp_f32_e32 v12, v12
	ds_read_u16 v18, v178
	v_exp_f32_e32 v11, v11
	v_mul_f32_e32 v12, v12, v13
	v_cvt_pk_bf16_f32 v12, v12, s0
	ds_write_b16 v177, v12
	v_sub_f32_e32 v12, v58, v38
	v_mul_f32_e32 v12, 0x3fb8aa3b, v12
	v_exp_f32_e32 v12, v12
	s_waitcnt lgkmcnt(1)
	v_lshlrev_b32_e32 v18, 16, v18
	v_mul_f32_e32 v12, v12, v13
	ds_read_u16 v13, v137 offset:36336
	s_waitcnt lgkmcnt(0)
	v_lshlrev_b32_e32 v13, 16, v13
	v_mul_f32_e32 v13, v19, v13
	v_mul_f32_e32 v13, 0x3db504f3, v13
	v_cvt_pk_bf16_f32 v13, v13, s0
	ds_write_b16 v137, v13 offset:36336
	v_mul_f32_e32 v13, 0xbfb8aa3b, v39
	v_exp_f32_e32 v13, v13
	v_mul_f32_e32 v19, 0x3fb8aa3b, v57
	v_exp_f32_e32 v19, v19
	v_mul_f32_e32 v13, v13, v18
	v_cvt_pk_bf16_f32 v13, v13, s0
	ds_write_b16 v178, v13
	v_sub_f32_e32 v13, v58, v39
	v_mul_f32_e32 v13, 0x3fb8aa3b, v13
	v_exp_f32_e32 v13, v13
	s_nop 0
	v_mul_f32_e32 v13, v13, v18
	v_cvt_pk_bf16_f32 v5, v12, v13
	global_store_dwordx4 v[8:9], v[2:5], off offset:2048
	ds_read_u16 v2, v137 offset:37376
	ds_read_u16 v3, v179
	v_mul_f32_e32 v4, 0x3fb8aa3b, v40
	v_exp_f32_e32 v4, v4
	v_mul_f32_e32 v5, 0x3fb8aa3b, v41
	s_waitcnt lgkmcnt(1)
	v_lshlrev_b32_e32 v2, 16, v2
	s_waitcnt lgkmcnt(0)
	v_lshlrev_b32_e32 v3, 16, v3
	v_mul_f32_e32 v2, v4, v2
	v_mul_f32_e32 v2, 0x3db504f3, v2
	v_cvt_pk_bf16_f32 v2, v2, s0
	ds_write_b16 v137, v2 offset:37376
	v_mul_f32_e32 v2, 0xbfb8aa3b, v40
	v_exp_f32_e32 v2, v2
	v_exp_f32_e32 v5, v5
	ds_read_u16 v4, v180
	v_mul_f32_e32 v8, 0x3fb8aa3b, v42
	v_mul_f32_e32 v2, v2, v3
	v_cvt_pk_bf16_f32 v2, v2, s0
	ds_write_b16 v179, v2
	v_sub_f32_e32 v2, v58, v40
	v_mul_f32_e32 v2, 0x3fb8aa3b, v2
	v_exp_f32_e32 v2, v2
	s_waitcnt lgkmcnt(1)
	v_lshlrev_b32_e32 v4, 16, v4
	v_exp_f32_e32 v8, v8
	v_mul_f32_e32 v9, 0x3fb8aa3b, v43
	v_mul_f32_e32 v2, v2, v3
	ds_read_u16 v3, v137 offset:38416
	v_exp_f32_e32 v9, v9
	v_mul_f32_e32 v12, 0x3fb8aa3b, v46
	v_exp_f32_e32 v12, v12
	v_mul_f32_e32 v13, 0x3fb8aa3b, v47
	s_waitcnt lgkmcnt(0)
	v_lshlrev_b32_e32 v3, 16, v3
	v_mul_f32_e32 v3, v5, v3
	v_mul_f32_e32 v3, 0x3db504f3, v3
	v_cvt_pk_bf16_f32 v3, v3, s0
	ds_write_b16 v137, v3 offset:38416
	v_mul_f32_e32 v3, 0xbfb8aa3b, v41
	v_exp_f32_e32 v3, v3
	ds_read_u16 v5, v181
	v_exp_f32_e32 v13, v13
	v_mul_f32_e32 v18, 0x3fb8aa3b, v55
	v_mul_f32_e32 v3, v3, v4
	v_cvt_pk_bf16_f32 v3, v3, s0
	ds_write_b16 v180, v3
	v_sub_f32_e32 v3, v58, v41
	v_mul_f32_e32 v3, 0x3fb8aa3b, v3
	v_exp_f32_e32 v3, v3
	s_waitcnt lgkmcnt(1)
	v_lshlrev_b32_e32 v5, 16, v5
	v_exp_f32_e32 v18, v18
	v_mul_f32_e32 v3, v3, v4
	ds_read_u16 v4, v137 offset:39456
	s_waitcnt lgkmcnt(0)
	v_lshlrev_b32_e32 v4, 16, v4
	v_mul_f32_e32 v4, v8, v4
	v_mul_f32_e32 v4, 0x3db504f3, v4
	v_cvt_pk_bf16_f32 v4, v4, s0
	ds_write_b16 v137, v4 offset:39456
	v_mul_f32_e32 v4, 0xbfb8aa3b, v42
	v_exp_f32_e32 v4, v4
	ds_read_u16 v8, v182
	v_mul_f32_e32 v4, v4, v5
	v_cvt_pk_bf16_f32 v4, v4, s0
	ds_write_b16 v181, v4
	v_sub_f32_e32 v4, v58, v42
	v_mul_f32_e32 v4, 0x3fb8aa3b, v4
	v_exp_f32_e32 v4, v4
	s_waitcnt lgkmcnt(1)
	v_lshlrev_b32_e32 v8, 16, v8
	v_mul_f32_e32 v4, v4, v5
	ds_read_u16 v5, v137 offset:40496
	s_waitcnt lgkmcnt(0)
; __device__ __forceinline__ unsigned pk_bf16(float lo, float hi) { f32x2_t v = {lo, hi}; bf16x2_t b = __builtin_convertvector(v, bf16x2_t); return __builtin_bit_cast(unsigned, b); }
; __device__ __forceinline__ float bf2f(bf16_t v) { return __uint_as_float((unsigned)v << 16); }
; __device__ __forceinline__ bf16_t f2bf(float f) { return (bf16_t)(pk_bf16(f, 0.f) & 0xffffu); }
; __device__ __forceinline__ void gla_prep(LAS unsigned char* lds, const bf16_t* QK, const float* gz, const float* Wg, const float* bias,
;                                          bf16_t* QPimg, bf16_t* KTimg, bf16_t* Aimg, float* dec, int G) {
;     ...
; #pragma unroll
;         for (int t8 = 0; t8 < 8; ++t8) {
;             float kh[8];
; #pragma unroll
;             for (int tt = 0; tt < 8; ++tt) { const int t = t8 * 8 + tt;
;                 const float qv = bf2f(Qs[t * GP_PITCH + tid]), kv = bf2f(Ks[t * GP_PITCH + tid]);
;                 Qs[t * GP_PITCH + tid] = f2bf(qv * __expf(bb[t]) * 0.08838834764831845f);
;                 Ks[t * GP_PITCH + tid] = f2bf(kv * __expf(-bb[t]));
;                 kh[tt] = kv * __expf(blast - bb[t]); }
;             u32x4 w; w.x = pk_bf16(kh[0], kh[1]); w.y = pk_bf16(kh[2], kh[3]); w.z = pk_bf16(kh[4], kh[5]); w.w = pk_bf16(kh[6], kh[7]);
;             *(u32x4*)(KTimg + ((((size_t)u * 4 + hh) * 8 + t8) * 128 + dk) * 8) = w;
;         }
	v_lshlrev_b32_e32 v5, 16, v5
	v_mul_f32_e32 v5, v9, v5
	v_mul_f32_e32 v5, 0x3db504f3, v5
	v_cvt_pk_bf16_f32 v5, v5, s0
	ds_write_b16 v137, v5 offset:40496
	v_mul_f32_e32 v5, 0xbfb8aa3b, v43
	v_exp_f32_e32 v5, v5
	ds_read_u16 v9, v183
	v_mul_f32_e32 v5, v5, v8
	v_cvt_pk_bf16_f32 v5, v5, s0
	ds_write_b16 v182, v5
	v_sub_f32_e32 v5, v58, v43
	v_mul_f32_e32 v5, 0x3fb8aa3b, v5
	v_exp_f32_e32 v5, v5
	s_waitcnt lgkmcnt(1)
	v_lshlrev_b32_e32 v9, 16, v9
	v_mul_f32_e32 v5, v5, v8
	ds_read_u16 v8, v137 offset:41536
	s_waitcnt lgkmcnt(0)
	v_lshlrev_b32_e32 v8, 16, v8
	v_mul_f32_e32 v8, v10, v8
	v_mul_f32_e32 v8, 0x3db504f3, v8
	v_cvt_pk_bf16_f32 v8, v8, s0
	ds_write_b16 v137, v8 offset:41536
	v_mul_f32_e32 v8, 0xbfb8aa3b, v44
	v_exp_f32_e32 v8, v8
	s_nop 0
	v_mul_f32_e32 v8, v8, v9
	v_cvt_pk_bf16_f32 v8, v8, s0
	ds_write_b16 v183, v8
	v_sub_f32_e32 v8, v58, v44
	v_mul_f32_e32 v8, 0x3fb8aa3b, v8
	v_exp_f32_e32 v8, v8
	s_nop 0
	v_mul_f32_e32 v10, v8, v9
	ds_read_u16 v8, v137 offset:42576
	ds_read_u16 v9, v184
	s_waitcnt lgkmcnt(1)
	v_lshlrev_b32_e32 v8, 16, v8
	v_mul_f32_e32 v8, v11, v8
	v_mul_f32_e32 v8, 0x3db504f3, v8
	v_cvt_pk_bf16_f32 v8, v8, s0
	ds_write_b16 v137, v8 offset:42576
	v_mul_f32_e32 v8, 0xbfb8aa3b, v45
	v_exp_f32_e32 v8, v8
	s_waitcnt lgkmcnt(1)
	v_lshlrev_b32_e32 v9, 16, v9
	v_mul_f32_e32 v8, v8, v9
	v_cvt_pk_bf16_f32 v8, v8, s0
	ds_write_b16 v184, v8
	v_sub_f32_e32 v8, v58, v45
	v_mul_f32_e32 v8, 0x3fb8aa3b, v8
	v_exp_f32_e32 v8, v8
	s_nop 0
	v_mul_f32_e32 v11, v8, v9
	ds_read_u16 v8, v137 offset:43616
	ds_read_u16 v9, v185
	v_cvt_pk_bf16_f32 v10, v10, v11
	s_waitcnt lgkmcnt(1)
	v_lshlrev_b32_e32 v8, 16, v8
	v_mul_f32_e32 v8, v12, v8
	v_mul_f32_e32 v8, 0x3db504f3, v8
	v_cvt_pk_bf16_f32 v8, v8, s0
	ds_write_b16 v137, v8 offset:43616
	v_mul_f32_e32 v8, 0xbfb8aa3b, v46
	v_exp_f32_e32 v8, v8
	s_waitcnt lgkmcnt(1)
	v_lshlrev_b32_e32 v9, 16, v9
	v_mul_f32_e32 v8, v8, v9
	v_cvt_pk_bf16_f32 v8, v8, s0
	ds_write_b16 v185, v8
	v_sub_f32_e32 v8, v58, v46
	v_mul_f32_e32 v8, 0x3fb8aa3b, v8
	v_exp_f32_e32 v8, v8
	s_nop 0
	v_mul_f32_e32 v12, v8, v9
	ds_read_u16 v8, v137 offset:44656
	ds_read_u16 v9, v186
	s_waitcnt lgkmcnt(1)
	v_lshlrev_b32_e32 v8, 16, v8
	v_mul_f32_e32 v8, v13, v8
	v_mul_f32_e32 v8, 0x3db504f3, v8
	v_cvt_pk_bf16_f32 v8, v8, s0
	ds_write_b16 v137, v8 offset:44656
	v_mul_f32_e32 v8, 0xbfb8aa3b, v47
	v_exp_f32_e32 v8, v8
	s_waitcnt lgkmcnt(1)
	v_lshlrev_b32_e32 v9, 16, v9
	v_mul_f32_e32 v8, v8, v9
	v_cvt_pk_bf16_f32 v8, v8, s0
	ds_write_b16 v186, v8
	v_sub_f32_e32 v8, v58, v47
	v_mul_f32_e32 v8, 0x3fb8aa3b, v8
	v_exp_f32_e32 v8, v8
	s_nop 0
	v_mul_f32_e32 v13, v8, v9
	v_cvt_pk_bf16_f32 v11, v12, v13
	v_add_co_u32_e64 v12, s[82:83], s2, v6
	v_cvt_pk_bf16_f32 v9, v4, v5
	s_nop 0
	v_addc_co_u32_e64 v13, s[82:83], 0, v7, s[82:83]
	s_mov_b32 s2, 0x18873000
	ds_read_u16 v4, v137 offset:45696
	ds_read_u16 v5, v187
	v_cvt_pk_bf16_f32 v8, v2, v3
	v_add_co_u32_e64 v2, s[82:83], s2, v6
	v_mul_f32_e32 v6, 0x3fb8aa3b, v48
	v_exp_f32_e32 v6, v6
	s_waitcnt lgkmcnt(1)
	v_lshlrev_b32_e32 v4, 16, v4
	s_waitcnt lgkmcnt(0)
	v_lshlrev_b32_e32 v5, 16, v5
	v_addc_co_u32_e64 v3, s[82:83], 0, v7, s[82:83]
	v_mul_f32_e32 v4, v6, v4
	v_mul_f32_e32 v4, 0x3db504f3, v4
	v_cvt_pk_bf16_f32 v4, v4, s0
	ds_write_b16 v137, v4 offset:45696
	v_mul_f32_e32 v4, 0xbfb8aa3b, v48
	v_exp_f32_e32 v4, v4
	v_mul_f32_e32 v7, 0x3fb8aa3b, v49
	v_exp_f32_e32 v7, v7
	ds_read_u16 v6, v188
	v_mul_f32_e32 v4, v4, v5
	v_cvt_pk_bf16_f32 v4, v4, s0
	ds_write_b16 v187, v4
	v_sub_f32_e32 v4, v58, v48
	v_mul_f32_e32 v4, 0x3fb8aa3b, v4
	v_exp_f32_e32 v4, v4
	s_waitcnt lgkmcnt(1)
	v_lshlrev_b32_e32 v6, 16, v6
	global_store_dwordx4 v[2:3], v[8:11], off offset:-4096
	v_readlane_b32 s2, v255, 8
	v_mul_f32_e32 v4, v4, v5
	ds_read_u16 v5, v137 offset:46736
	v_mul_f32_e32 v8, 0x3fb8aa3b, v50
	v_exp_f32_e32 v8, v8
	v_mul_f32_e32 v9, 0x3fb8aa3b, v51
	v_exp_f32_e32 v9, v9
	s_waitcnt lgkmcnt(0)
	v_lshlrev_b32_e32 v5, 16, v5
	v_mul_f32_e32 v5, v7, v5
	v_mul_f32_e32 v5, 0x3db504f3, v5
	v_cvt_pk_bf16_f32 v5, v5, s0
	ds_write_b16 v137, v5 offset:46736
	v_mul_f32_e32 v5, 0xbfb8aa3b, v49
	v_exp_f32_e32 v5, v5
	ds_read_u16 v7, v189
	v_mul_f32_e32 v10, 0x3fb8aa3b, v52
	v_exp_f32_e32 v10, v10
	v_mul_f32_e32 v5, v5, v6
	v_cvt_pk_bf16_f32 v5, v5, s0
	ds_write_b16 v188, v5
	v_sub_f32_e32 v5, v58, v49
	v_mul_f32_e32 v5, 0x3fb8aa3b, v5
	v_exp_f32_e32 v5, v5
	s_waitcnt lgkmcnt(1)
	v_lshlrev_b32_e32 v7, 16, v7
	v_mul_f32_e32 v11, 0x3fb8aa3b, v53
	v_exp_f32_e32 v11, v11
	v_mul_f32_e32 v5, v5, v6
	ds_read_u16 v6, v137 offset:47776
	v_cvt_pk_bf16_f32 v4, v4, v5
	v_readlane_b32 s3, v255, 9
	s_waitcnt lgkmcnt(0)
	v_lshlrev_b32_e32 v6, 16, v6
	v_mul_f32_e32 v6, v8, v6
	v_mul_f32_e32 v6, 0x3db504f3, v6
	v_cvt_pk_bf16_f32 v6, v6, s0
	ds_write_b16 v137, v6 offset:47776
	v_mul_f32_e32 v6, 0xbfb8aa3b, v50
	v_exp_f32_e32 v6, v6
	ds_read_u16 v8, v190
	v_mul_f32_e32 v6, v6, v7
	v_cvt_pk_bf16_f32 v6, v6, s0
	ds_write_b16 v189, v6
	v_sub_f32_e32 v6, v58, v50
	v_mul_f32_e32 v6, 0x3fb8aa3b, v6
	v_exp_f32_e32 v6, v6
	s_waitcnt lgkmcnt(1)
	v_lshlrev_b32_e32 v8, 16, v8
	v_mul_f32_e32 v6, v6, v7
	ds_read_u16 v7, v137 offset:48816
	s_waitcnt lgkmcnt(0)
	v_lshlrev_b32_e32 v7, 16, v7
	v_mul_f32_e32 v7, v9, v7
	v_mul_f32_e32 v7, 0x3db504f3, v7
	v_cvt_pk_bf16_f32 v7, v7, s0
	ds_write_b16 v137, v7 offset:48816
	v_mul_f32_e32 v7, 0xbfb8aa3b, v51
	v_exp_f32_e32 v7, v7
	ds_read_u16 v9, v191
	v_mul_f32_e32 v7, v7, v8
	v_cvt_pk_bf16_f32 v7, v7, s0
	ds_write_b16 v190, v7
	v_sub_f32_e32 v7, v58, v51
	v_mul_f32_e32 v7, 0x3fb8aa3b, v7
	v_exp_f32_e32 v7, v7
	s_waitcnt lgkmcnt(1)
	v_lshlrev_b32_e32 v9, 16, v9
	v_mul_f32_e32 v7, v7, v8
	ds_read_u16 v8, v137 offset:49856
	v_cvt_pk_bf16_f32 v5, v6, v7
	s_waitcnt lgkmcnt(0)
; __device__ __forceinline__ unsigned pk_bf16(float lo, float hi) { f32x2_t v = {lo, hi}; bf16x2_t b = __builtin_convertvector(v, bf16x2_t); return __builtin_bit_cast(unsigned, b); }
; __device__ __forceinline__ float bf2f(bf16_t v) { return __uint_as_float((unsigned)v << 16); }
; __device__ __forceinline__ bf16_t f2bf(float f) { return (bf16_t)(pk_bf16(f, 0.f) & 0xffffu); }
; __device__ __forceinline__ void gla_prep(LAS unsigned char* lds, const bf16_t* QK, const float* gz, const float* Wg, const float* bias,
;                                          bf16_t* QPimg, bf16_t* KTimg, bf16_t* Aimg, float* dec, int G) {
;     ...
; #pragma unroll
;         for (int t8 = 0; t8 < 8; ++t8) {
;             float kh[8];
; #pragma unroll
;             for (int tt = 0; tt < 8; ++tt) { const int t = t8 * 8 + tt;
;                 const float qv = bf2f(Qs[t * GP_PITCH + tid]), kv = bf2f(Ks[t * GP_PITCH + tid]);
;                 Qs[t * GP_PITCH + tid] = f2bf(qv * __expf(bb[t]) * 0.08838834764831845f);
;                 Ks[t * GP_PITCH + tid] = f2bf(kv * __expf(-bb[t]));
;                 kh[tt] = kv * __expf(blast - bb[t]); }
;             u32x4 w; w.x = pk_bf16(kh[0], kh[1]); w.y = pk_bf16(kh[2], kh[3]); w.z = pk_bf16(kh[4], kh[5]); w.w = pk_bf16(kh[6], kh[7]);
;             *(u32x4*)(KTimg + ((((size_t)u * 4 + hh) * 8 + t8) * 128 + dk) * 8) = w;
;         }
	v_lshlrev_b32_e32 v8, 16, v8
	v_mul_f32_e32 v8, v10, v8
	v_mul_f32_e32 v8, 0x3db504f3, v8
	v_cvt_pk_bf16_f32 v8, v8, s0
	ds_write_b16 v137, v8 offset:49856
	v_mul_f32_e32 v8, 0xbfb8aa3b, v52
	v_exp_f32_e32 v8, v8
	ds_read_u16 v10, v192
	v_mul_f32_e32 v8, v8, v9
	v_cvt_pk_bf16_f32 v8, v8, s0
	ds_write_b16 v191, v8
	v_sub_f32_e32 v8, v58, v52
	v_mul_f32_e32 v8, 0x3fb8aa3b, v8
	v_exp_f32_e32 v8, v8
	s_waitcnt lgkmcnt(1)
	v_lshlrev_b32_e32 v10, 16, v10
	v_mul_f32_e32 v8, v8, v9
	ds_read_u16 v9, v137 offset:50896
	s_waitcnt lgkmcnt(0)
	v_lshlrev_b32_e32 v9, 16, v9
	v_mul_f32_e32 v9, v11, v9
	v_mul_f32_e32 v9, 0x3db504f3, v9
	v_cvt_pk_bf16_f32 v9, v9, s0
	ds_write_b16 v137, v9 offset:50896
	v_mul_f32_e32 v9, 0xbfb8aa3b, v53
	v_exp_f32_e32 v9, v9
	ds_read_u16 v11, v193
	v_mul_f32_e32 v9, v9, v10
	v_cvt_pk_bf16_f32 v9, v9, s0
	ds_write_b16 v192, v9
	v_sub_f32_e32 v9, v58, v53
	v_mul_f32_e32 v9, 0x3fb8aa3b, v9
	v_exp_f32_e32 v9, v9
	s_waitcnt lgkmcnt(1)
	v_lshlrev_b32_e32 v11, 16, v11
	v_mul_f32_e32 v9, v9, v10
	ds_read_u16 v10, v137 offset:51936
	v_cvt_pk_bf16_f32 v6, v8, v9
	v_mul_f32_e32 v8, 0x3fb8aa3b, v62
	v_exp_f32_e32 v8, v8
	v_mul_f32_e32 v9, 0x3fb8aa3b, v63
	s_waitcnt lgkmcnt(0)
	v_lshlrev_b32_e32 v10, 16, v10
	v_mul_f32_e32 v10, v18, v10
	v_mul_f32_e32 v10, 0x3db504f3, v10
	v_cvt_pk_bf16_f32 v10, v10, s0
	ds_write_b16 v137, v10 offset:51936
	v_mul_f32_e32 v10, 0xbfb8aa3b, v55
	v_exp_f32_e32 v10, v10
	ds_read_u16 v18, v209
	v_exp_f32_e32 v9, v9
	v_mul_f32_e32 v10, v10, v11
	v_cvt_pk_bf16_f32 v10, v10, s0
	ds_write_b16 v193, v10
	v_sub_f32_e32 v10, v58, v55
	v_mul_f32_e32 v10, 0x3fb8aa3b, v10
	v_exp_f32_e32 v10, v10
	s_waitcnt lgkmcnt(1)
	v_lshlrev_b32_e32 v18, 16, v18
	v_mul_f32_e32 v10, v10, v11
	ds_read_u16 v11, v137 offset:52976
	s_waitcnt lgkmcnt(0)
	v_lshlrev_b32_e32 v11, 16, v11
	v_mul_f32_e32 v11, v19, v11
	v_mul_f32_e32 v11, 0x3db504f3, v11
	v_cvt_pk_bf16_f32 v11, v11, s0
	ds_write_b16 v137, v11 offset:52976
	v_mul_f32_e32 v11, 0xbfb8aa3b, v57
	v_exp_f32_e32 v11, v11
	s_nop 0
	v_mul_f32_e32 v11, v11, v18
	v_cvt_pk_bf16_f32 v11, v11, s0
	ds_write_b16 v209, v11
	v_sub_f32_e32 v11, v58, v57
	v_mul_f32_e32 v11, 0x3fb8aa3b, v11
	v_exp_f32_e32 v11, v11
	s_nop 0
	v_mul_f32_e32 v11, v11, v18
	v_cvt_pk_bf16_f32 v7, v10, v11
	global_store_dwordx4 v[12:13], v[4:7], off offset:2048
	ds_read_u16 v4, v137 offset:54016
	ds_read_u16 v5, v210
	v_mul_f32_e32 v6, 0x3fb8aa3b, v60
	v_exp_f32_e32 v6, v6
	v_mul_f32_e32 v7, 0x3fb8aa3b, v61
	s_waitcnt lgkmcnt(1)
	v_lshlrev_b32_e32 v4, 16, v4
	s_waitcnt lgkmcnt(0)
	v_lshlrev_b32_e32 v5, 16, v5
	v_mul_f32_e32 v4, v6, v4
	v_mul_f32_e32 v4, 0x3db504f3, v4
	v_cvt_pk_bf16_f32 v4, v4, s0
	ds_write_b16 v137, v4 offset:54016
	v_mul_f32_e32 v4, 0xbfb8aa3b, v60
	v_exp_f32_e32 v4, v4
	v_exp_f32_e32 v7, v7
	ds_read_u16 v6, v211
	v_mul_f32_e32 v10, 0x3fb8aa3b, v64
	v_mul_f32_e32 v4, v4, v5
	v_cvt_pk_bf16_f32 v4, v4, s0
	ds_write_b16 v210, v4
	v_sub_f32_e32 v4, v58, v60
	v_mul_f32_e32 v4, 0x3fb8aa3b, v4
	v_exp_f32_e32 v4, v4
	s_waitcnt lgkmcnt(1)
	v_lshlrev_b32_e32 v6, 16, v6
	v_exp_f32_e32 v10, v10
	v_mul_f32_e32 v11, 0x3fb8aa3b, v65
	v_mul_f32_e32 v4, v4, v5
	ds_read_u16 v5, v137 offset:55056
	v_exp_f32_e32 v11, v11
	v_mul_f32_e32 v12, 0x3fb8aa3b, v66
	v_exp_f32_e32 v12, v12
	v_mul_f32_e32 v13, 0x3fb8aa3b, v67
	s_waitcnt lgkmcnt(0)
	v_lshlrev_b32_e32 v5, 16, v5
	v_mul_f32_e32 v5, v7, v5
	v_mul_f32_e32 v5, 0x3db504f3, v5
	v_cvt_pk_bf16_f32 v5, v5, s0
	ds_write_b16 v137, v5 offset:55056
	v_mul_f32_e32 v5, 0xbfb8aa3b, v61
	v_exp_f32_e32 v5, v5
	ds_read_u16 v7, v212
	v_exp_f32_e32 v13, v13
	v_mul_f32_e32 v5, v5, v6
	v_cvt_pk_bf16_f32 v5, v5, s0
	ds_write_b16 v211, v5
	v_sub_f32_e32 v5, v58, v61
	v_mul_f32_e32 v5, 0x3fb8aa3b, v5
	v_exp_f32_e32 v5, v5
	s_waitcnt lgkmcnt(1)
	v_lshlrev_b32_e32 v7, 16, v7
	v_mul_f32_e32 v5, v5, v6
	ds_read_u16 v6, v137 offset:56096
	v_cvt_pk_bf16_f32 v4, v4, v5
	s_waitcnt lgkmcnt(0)
	v_lshlrev_b32_e32 v6, 16, v6
	v_mul_f32_e32 v6, v8, v6
	v_mul_f32_e32 v6, 0x3db504f3, v6
	v_cvt_pk_bf16_f32 v6, v6, s0
	ds_write_b16 v137, v6 offset:56096
	v_mul_f32_e32 v6, 0xbfb8aa3b, v62
	v_exp_f32_e32 v6, v6
	ds_read_u16 v8, v213
	v_mul_f32_e32 v6, v6, v7
	v_cvt_pk_bf16_f32 v6, v6, s0
	ds_write_b16 v212, v6
	v_sub_f32_e32 v6, v58, v62
	v_mul_f32_e32 v6, 0x3fb8aa3b, v6
	v_exp_f32_e32 v6, v6
	s_waitcnt lgkmcnt(1)
	v_lshlrev_b32_e32 v8, 16, v8
	v_mul_f32_e32 v6, v6, v7
	ds_read_u16 v7, v137 offset:57136
	s_waitcnt lgkmcnt(0)
	v_lshlrev_b32_e32 v7, 16, v7
	v_mul_f32_e32 v7, v9, v7
	v_mul_f32_e32 v7, 0x3db504f3, v7
	v_cvt_pk_bf16_f32 v7, v7, s0
	ds_write_b16 v137, v7 offset:57136
	v_mul_f32_e32 v7, 0xbfb8aa3b, v63
	v_exp_f32_e32 v7, v7
	ds_read_u16 v9, v214
	v_mul_f32_e32 v7, v7, v8
	v_cvt_pk_bf16_f32 v7, v7, s0
	ds_write_b16 v213, v7
	v_sub_f32_e32 v7, v58, v63
	v_mul_f32_e32 v7, 0x3fb8aa3b, v7
	v_exp_f32_e32 v7, v7
	s_waitcnt lgkmcnt(1)
	v_lshlrev_b32_e32 v9, 16, v9
	v_mul_f32_e32 v7, v7, v8
	ds_read_u16 v8, v137 offset:58176
	v_cvt_pk_bf16_f32 v5, v6, v7
	s_waitcnt lgkmcnt(0)
	v_lshlrev_b32_e32 v8, 16, v8
	v_mul_f32_e32 v8, v10, v8
	v_mul_f32_e32 v8, 0x3db504f3, v8
	v_cvt_pk_bf16_f32 v8, v8, s0
	ds_write_b16 v137, v8 offset:58176
	v_mul_f32_e32 v8, 0xbfb8aa3b, v64
	v_exp_f32_e32 v8, v8
	ds_read_u16 v10, v215
	v_mul_f32_e32 v8, v8, v9
	v_cvt_pk_bf16_f32 v8, v8, s0
	ds_write_b16 v214, v8
	v_sub_f32_e32 v8, v58, v64
	v_mul_f32_e32 v8, 0x3fb8aa3b, v8
	v_exp_f32_e32 v8, v8
	s_waitcnt lgkmcnt(1)
	v_lshlrev_b32_e32 v10, 16, v10
	v_mul_f32_e32 v8, v8, v9
	ds_read_u16 v9, v137 offset:59216
	s_waitcnt lgkmcnt(0)
; __device__ __forceinline__ unsigned pk_bf16(float lo, float hi) { f32x2_t v = {lo, hi}; bf16x2_t b = __builtin_convertvector(v, bf16x2_t); return __builtin_bit_cast(unsigned, b); }
; __device__ __forceinline__ float bf2f(bf16_t v) { return __uint_as_float((unsigned)v << 16); }
; __device__ __forceinline__ bf16_t f2bf(float f) { return (bf16_t)(pk_bf16(f, 0.f) & 0xffffu); }
; __device__ __forceinline__ void gla_prep(LAS unsigned char* lds, const bf16_t* QK, const float* gz, const float* Wg, const float* bias,
;                                          bf16_t* QPimg, bf16_t* KTimg, bf16_t* Aimg, float* dec, int G) {
;     ...
; #pragma unroll
;         for (int t8 = 0; t8 < 8; ++t8) {
;             float kh[8];
; #pragma unroll
;             for (int tt = 0; tt < 8; ++tt) { const int t = t8 * 8 + tt;
;                 const float qv = bf2f(Qs[t * GP_PITCH + tid]), kv = bf2f(Ks[t * GP_PITCH + tid]);
;                 Qs[t * GP_PITCH + tid] = f2bf(qv * __expf(bb[t]) * 0.08838834764831845f);
;                 Ks[t * GP_PITCH + tid] = f2bf(kv * __expf(-bb[t]));
;                 kh[tt] = kv * __expf(blast - bb[t]); }
;             u32x4 w; w.x = pk_bf16(kh[0], kh[1]); w.y = pk_bf16(kh[2], kh[3]); w.z = pk_bf16(kh[4], kh[5]); w.w = pk_bf16(kh[6], kh[7]);
;             *(u32x4*)(KTimg + ((((size_t)u * 4 + hh) * 8 + t8) * 128 + dk) * 8) = w;
;         }
;         dec[((size_t)u * 4 + hh) * 256 + dk] = __expf(blast);
;         __syncthreads();
	v_lshlrev_b32_e32 v9, 16, v9
	v_mul_f32_e32 v9, v11, v9
	v_mul_f32_e32 v9, 0x3db504f3, v9
	v_cvt_pk_bf16_f32 v9, v9, s0
	ds_write_b16 v137, v9 offset:59216
	v_mul_f32_e32 v9, 0xbfb8aa3b, v65
	v_exp_f32_e32 v9, v9
	ds_read_u16 v11, v216
	v_mul_f32_e32 v9, v9, v10
	v_cvt_pk_bf16_f32 v9, v9, s0
	ds_write_b16 v215, v9
	v_sub_f32_e32 v9, v58, v65
	v_mul_f32_e32 v9, 0x3fb8aa3b, v9
	v_exp_f32_e32 v9, v9
	s_waitcnt lgkmcnt(1)
	v_lshlrev_b32_e32 v11, 16, v11
	v_mul_f32_e32 v9, v9, v10
	ds_read_u16 v10, v137 offset:60256
	v_cvt_pk_bf16_f32 v6, v8, v9
	v_mul_f32_e32 v8, 0x3fb8aa3b, v70
	v_exp_f32_e32 v8, v8
	v_mul_f32_e32 v9, 0x3fb8aa3b, v71
	s_waitcnt lgkmcnt(0)
	v_lshlrev_b32_e32 v10, 16, v10
	v_mul_f32_e32 v10, v12, v10
	v_mul_f32_e32 v10, 0x3db504f3, v10
	v_cvt_pk_bf16_f32 v10, v10, s0
	ds_write_b16 v137, v10 offset:60256
	v_mul_f32_e32 v10, 0xbfb8aa3b, v66
	v_exp_f32_e32 v10, v10
	ds_read_u16 v12, v217
	v_exp_f32_e32 v9, v9
	v_mul_f32_e32 v10, v10, v11
	v_cvt_pk_bf16_f32 v10, v10, s0
	ds_write_b16 v216, v10
	v_sub_f32_e32 v10, v58, v66
	v_mul_f32_e32 v10, 0x3fb8aa3b, v10
	v_exp_f32_e32 v10, v10
	s_waitcnt lgkmcnt(1)
	v_lshlrev_b32_e32 v12, 16, v12
	v_mul_f32_e32 v10, v10, v11
	ds_read_u16 v11, v137 offset:61296
	s_waitcnt lgkmcnt(0)
	v_lshlrev_b32_e32 v11, 16, v11
	v_mul_f32_e32 v11, v13, v11
	v_mul_f32_e32 v11, 0x3db504f3, v11
	v_cvt_pk_bf16_f32 v11, v11, s0
	ds_write_b16 v137, v11 offset:61296
	v_mul_f32_e32 v11, 0xbfb8aa3b, v67
	v_exp_f32_e32 v11, v11
	v_mul_f32_e32 v13, 0x3fb8aa3b, v58
	v_exp_f32_e32 v13, v13
	v_mul_f32_e32 v11, v11, v12
	v_cvt_pk_bf16_f32 v11, v11, s0
	ds_write_b16 v217, v11
	v_sub_f32_e32 v11, v58, v67
	v_mul_f32_e32 v11, 0x3fb8aa3b, v11
	v_exp_f32_e32 v11, v11
	s_nop 0
	v_mul_f32_e32 v11, v11, v12
	v_cvt_pk_bf16_f32 v7, v10, v11
	global_store_dwordx4 v[2:3], v[4:7], off
	ds_read_u16 v4, v137 offset:62336
	ds_read_u16 v5, v218
	v_mul_f32_e32 v6, 0x3fb8aa3b, v68
	v_exp_f32_e32 v6, v6
	v_mul_f32_e32 v7, 0x3fb8aa3b, v69
	s_waitcnt lgkmcnt(1)
	v_lshlrev_b32_e32 v4, 16, v4
	s_waitcnt lgkmcnt(0)
	v_lshlrev_b32_e32 v5, 16, v5
	v_mul_f32_e32 v4, v6, v4
	v_mul_f32_e32 v4, 0x3db504f3, v4
	v_cvt_pk_bf16_f32 v4, v4, s0
	ds_write_b16 v137, v4 offset:62336
	v_mul_f32_e32 v4, 0xbfb8aa3b, v68
	v_exp_f32_e32 v4, v4
	v_exp_f32_e32 v7, v7
	ds_read_u16 v6, v219
	v_mul_f32_e32 v10, 0x3fb8aa3b, v54
	v_mul_f32_e32 v4, v4, v5
	v_cvt_pk_bf16_f32 v4, v4, s0
	ds_write_b16 v218, v4
	v_sub_f32_e32 v4, v58, v68
	v_mul_f32_e32 v4, 0x3fb8aa3b, v4
	v_exp_f32_e32 v4, v4
	s_waitcnt lgkmcnt(1)
	v_lshlrev_b32_e32 v6, 16, v6
	v_exp_f32_e32 v10, v10
	v_mul_f32_e32 v11, 0x3fb8aa3b, v56
	v_mul_f32_e32 v4, v4, v5
	ds_read_u16 v5, v137 offset:63376
	v_exp_f32_e32 v11, v11
	v_mul_f32_e32 v12, 0x3fb8aa3b, v59
	v_exp_f32_e32 v12, v12
	s_waitcnt lgkmcnt(0)
	v_lshlrev_b32_e32 v5, 16, v5
	v_mul_f32_e32 v5, v7, v5
	v_mul_f32_e32 v5, 0x3db504f3, v5
	v_cvt_pk_bf16_f32 v5, v5, s0
	ds_write_b16 v137, v5 offset:63376
	v_mul_f32_e32 v5, 0xbfb8aa3b, v69
	v_exp_f32_e32 v5, v5
	ds_read_u16 v7, v220
	v_mul_f32_e32 v5, v5, v6
	v_cvt_pk_bf16_f32 v5, v5, s0
	ds_write_b16 v219, v5
	v_sub_f32_e32 v5, v58, v69
	v_mul_f32_e32 v5, 0x3fb8aa3b, v5
	v_exp_f32_e32 v5, v5
	s_waitcnt lgkmcnt(1)
	v_lshlrev_b32_e32 v7, 16, v7
	v_mul_f32_e32 v5, v5, v6
	ds_read_u16 v6, v137 offset:64416
	v_cvt_pk_bf16_f32 v4, v4, v5
	s_waitcnt lgkmcnt(0)
	v_lshlrev_b32_e32 v6, 16, v6
	v_mul_f32_e32 v6, v8, v6
	v_mul_f32_e32 v6, 0x3db504f3, v6
	v_cvt_pk_bf16_f32 v6, v6, s0
	ds_write_b16 v137, v6 offset:64416
	v_mul_f32_e32 v6, 0xbfb8aa3b, v70
	v_exp_f32_e32 v6, v6
	ds_read_u16 v8, v221
	v_mul_f32_e32 v6, v6, v7
	v_cvt_pk_bf16_f32 v6, v6, s0
	ds_write_b16 v220, v6
	v_sub_f32_e32 v6, v58, v70
	v_mul_f32_e32 v6, 0x3fb8aa3b, v6
	v_exp_f32_e32 v6, v6
	s_waitcnt lgkmcnt(1)
	v_lshlrev_b32_e32 v8, 16, v8
	v_mul_f32_e32 v6, v6, v7
	ds_read_u16 v7, v137 offset:65456
	s_waitcnt lgkmcnt(0)
	v_lshlrev_b32_e32 v7, 16, v7
	v_mul_f32_e32 v7, v9, v7
	v_mul_f32_e32 v7, 0x3db504f3, v7
	v_cvt_pk_bf16_f32 v7, v7, s0
	ds_write_b16 v137, v7 offset:65456
	v_mul_f32_e32 v7, 0xbfb8aa3b, v71
	v_exp_f32_e32 v7, v7
	ds_read_u16 v9, v222
	v_mul_f32_e32 v7, v7, v8
	v_cvt_pk_bf16_f32 v7, v7, s0
	ds_write_b16 v221, v7
	v_sub_f32_e32 v7, v58, v71
	v_mul_f32_e32 v7, 0x3fb8aa3b, v7
	v_exp_f32_e32 v7, v7
	s_waitcnt lgkmcnt(1)
	v_lshlrev_b32_e32 v9, 16, v9
	v_mul_f32_e32 v7, v7, v8
	ds_read_u16 v8, v138 offset:62400
	v_cvt_pk_bf16_f32 v5, v6, v7
	s_waitcnt lgkmcnt(0)
	v_lshlrev_b32_e32 v8, 16, v8
	v_mul_f32_e32 v8, v10, v8
	v_mul_f32_e32 v8, 0x3db504f3, v8
	v_cvt_pk_bf16_f32 v8, v8, s0
	ds_write_b16 v138, v8 offset:62400
	v_mul_f32_e32 v8, 0xbfb8aa3b, v54
	v_exp_f32_e32 v8, v8
	ds_read_u16 v10, v223
	v_mul_f32_e32 v8, v8, v9
	v_cvt_pk_bf16_f32 v8, v8, s0
	ds_write_b16 v222, v8
	v_sub_f32_e32 v8, v58, v54
	v_mul_f32_e32 v8, 0x3fb8aa3b, v8
	v_exp_f32_e32 v8, v8
	s_waitcnt lgkmcnt(1)
	v_lshlrev_b32_e32 v10, 16, v10
	v_mul_f32_e32 v8, v8, v9
	ds_read_u16 v9, v138 offset:63440
	s_waitcnt lgkmcnt(0)
	v_lshlrev_b32_e32 v9, 16, v9
	v_mul_f32_e32 v9, v11, v9
	v_mul_f32_e32 v9, 0x3db504f3, v9
	v_cvt_pk_bf16_f32 v9, v9, s0
	ds_write_b16 v138, v9 offset:63440
	v_mul_f32_e32 v9, 0xbfb8aa3b, v56
	v_exp_f32_e32 v9, v9
	ds_read_u16 v11, v224
	v_mul_f32_e32 v9, v9, v10
	v_cvt_pk_bf16_f32 v9, v9, s0
	ds_write_b16 v223, v9
	v_sub_f32_e32 v9, v58, v56
	v_mul_f32_e32 v9, 0x3fb8aa3b, v9
	v_exp_f32_e32 v9, v9
	s_waitcnt lgkmcnt(1)
	v_lshlrev_b32_e32 v11, 16, v11
	v_mul_f32_e32 v9, v9, v10
	ds_read_u16 v10, v138 offset:64480
	v_cvt_pk_bf16_f32 v6, v8, v9
	s_waitcnt lgkmcnt(0)
	v_lshlrev_b32_e32 v10, 16, v10
	v_mul_f32_e32 v10, v12, v10
	v_mul_f32_e32 v10, 0x3db504f3, v10
	v_cvt_pk_bf16_f32 v10, v10, s0
	ds_write_b16 v138, v10 offset:64480
	v_mul_f32_e32 v10, 0xbfb8aa3b, v59
	v_exp_f32_e32 v10, v10
	ds_read_u16 v12, v225
	v_mul_f32_e32 v10, v10, v11
	v_cvt_pk_bf16_f32 v10, v10, s0
	ds_write_b16 v224, v10
	v_sub_f32_e32 v10, v58, v59
	v_mul_f32_e32 v10, 0x3fb8aa3b, v10
	v_exp_f32_e32 v10, v10
	s_waitcnt lgkmcnt(1)
	v_lshlrev_b32_e32 v12, 16, v12
	v_mul_f32_e32 v10, v10, v11
	ds_read_u16 v11, v138 offset:65520
	s_waitcnt lgkmcnt(0)
	v_lshlrev_b32_e32 v11, 16, v11
	v_mul_f32_e32 v11, v13, v11
	v_mul_f32_e32 v11, 0x3db504f3, v11
	v_cvt_pk_bf16_f32 v11, v11, s0
	ds_write_b16 v138, v11 offset:65520
	v_mul_f32_e32 v11, 0xbfb8aa3b, v58
	v_exp_f32_e32 v11, v11
	s_nop 0
	v_mul_f32_e32 v11, v11, v12
	v_cvt_pk_bf16_f32 v11, v11, s0
	ds_write_b16 v225, v11
	v_sub_f32_e32 v11, v58, v58
	v_mul_f32_e32 v11, 0x3fb8aa3b, v11
	v_exp_f32_e32 v11, v11
	s_nop 0
	v_mul_f32_e32 v11, v11, v12
	v_cvt_pk_bf16_f32 v7, v10, v11
	global_store_dwordx4 v[2:3], v[4:7], off offset:2048
	v_lshl_add_u64 v[2:3], s[8:9], 0, v[118:119]
	global_store_dword v[2:3], v13, off
	s_waitcnt lgkmcnt(0)
	s_barrier
; #define LAS __attribute__((address_space(3)))
; __device__ __forceinline__ void gla_prep(LAS unsigned char* lds, const bf16_t* QK, const float* gz, const float* Wg, const float* bias,
;                                          bf16_t* QPimg, bf16_t* KTimg, bf16_t* Aimg, float* dec, int G) {
;     ...
; #pragma unroll
;         for (int i = 0; i < 8; ++i) { const int it = tid + 512 * i, t = it & 63, ch = (it >> 6) & 15, h2 = it >> 10; const int dkb = 32 * (ch >> 2) + 16 * ((ch >> 1) & 1) + 4 * (ch & 1);
;             const u32x2 a = *(const LAS u32x2*)(Qs + t * GP_PITCH + h2 * 128 + dkb), b2 = *(const LAS u32x2*)(Qs + t * GP_PITCH + h2 * 128 + dkb + 8);
;             *(u32x4*)(QPimg + ((((size_t)u * 4 + h2) * 16 + ch) * 64 + t) * 8) = (u32x4){a.x, a.y, b2.x, b2.y}; }
;         { const int h2 = wid >> 1, tt = wid & 1; const int t = 32 * tt + l31;
; #pragma unroll
;           for (int jt = 0; jt < 2; ++jt) {
;             f32x16 acc;
; #pragma unroll
;             for (int r = 0; r < 16; ++r) acc[r] = 0.f;
; #pragma unroll
;             for (int ks = 0; ks < 8; ++ks) {
;                 const bf16x8 af = *(const LAS bf16x8*)(Ks + (32 * jt + l31) * GP_PITCH + h2 * 128 + 16 * ks + 8 * hi);
;                 const bf16x8 bf = *(const LAS bf16x8*)(Qs + t * GP_PITCH + h2 * 128 + 16 * ks + 8 * hi);
;                 acc = __builtin_amdgcn_mfma_f32_32x32x16_bf16(af, bf, acc, 0, 0, 0);
;             }
	ds_read2_b64 v[2:5], v227 offset1:2
	v_lshl_add_u64 v[6:7], s[8:9], 0, v[112:113]
	v_lshl_add_u64 v[112:113], v[112:113], 0, s[4:5]
	s_waitcnt lgkmcnt(0)
	global_store_dwordx4 v[6:7], v[2:5], off
	ds_read2_b64 v[2:5], v228 offset1:2
	v_lshl_add_u64 v[6:7], s[8:9], 0, v[110:111]
	v_lshl_add_u64 v[110:111], v[110:111], 0, s[4:5]
	s_waitcnt lgkmcnt(0)
	global_store_dwordx4 v[6:7], v[2:5], off
	ds_read2_b64 v[2:5], v229 offset1:2
	v_lshl_add_u64 v[6:7], s[8:9], 0, v[108:109]
	v_lshl_add_u64 v[108:109], v[108:109], 0, s[4:5]
	s_waitcnt lgkmcnt(0)
	global_store_dwordx4 v[6:7], v[2:5], off
	ds_read2_b64 v[2:5], v230 offset1:2
	v_lshl_add_u64 v[6:7], s[8:9], 0, v[106:107]
	v_lshl_add_u64 v[106:107], v[106:107], 0, s[4:5]
	s_waitcnt lgkmcnt(0)
	global_store_dwordx4 v[6:7], v[2:5], off
	ds_read2_b64 v[2:5], v231 offset1:2
	v_lshl_add_u64 v[6:7], s[8:9], 0, v[104:105]
	v_lshl_add_u64 v[104:105], v[104:105], 0, s[4:5]
	s_waitcnt lgkmcnt(0)
	global_store_dwordx4 v[6:7], v[2:5], off
	ds_read2_b64 v[2:5], v232 offset1:2
	v_lshl_add_u64 v[6:7], s[8:9], 0, v[102:103]
	v_lshl_add_u64 v[102:103], v[102:103], 0, s[4:5]
	s_waitcnt lgkmcnt(0)
	global_store_dwordx4 v[6:7], v[2:5], off
	ds_read2_b64 v[2:5], v233 offset1:2
	v_lshl_add_u64 v[6:7], s[8:9], 0, v[100:101]
	v_lshl_add_u64 v[100:101], v[100:101], 0, s[4:5]
	s_waitcnt lgkmcnt(0)
	global_store_dwordx4 v[6:7], v[2:5], off
	ds_read2_b64 v[2:5], v234 offset1:2
	v_lshl_add_u64 v[6:7], s[8:9], 0, v[98:99]
	v_lshl_add_u64 v[98:99], v[98:99], 0, s[4:5]
	s_waitcnt lgkmcnt(0)
	global_store_dwordx4 v[6:7], v[2:5], off
	ds_read_b128 v[2:5], v226
	ds_read_b128 v[6:9], v226 offset:32
	ds_read_b128 v[46:49], v121 offset:4096
	ds_read_b128 v[50:53], v121 offset:4128
	s_waitcnt lgkmcnt(1)
	v_mfma_f32_32x32x16_bf16 v[18:33], v[2:5], v[46:49], 0
	ds_read_b128 v[2:5], v226 offset:64
	ds_read_b128 v[42:45], v121 offset:4160
	s_waitcnt lgkmcnt(2)
	v_mfma_f32_32x32x16_bf16 v[18:33], v[6:9], v[50:53], v[18:33]
	s_waitcnt lgkmcnt(0)
	v_mfma_f32_32x32x16_bf16 v[18:33], v[2:5], v[42:45], v[18:33]
	ds_read_b128 v[2:5], v226 offset:96
	ds_read_b128 v[38:41], v121 offset:4192
	s_waitcnt lgkmcnt(0)
	v_mfma_f32_32x32x16_bf16 v[18:33], v[2:5], v[38:41], v[18:33]
	ds_read_b128 v[2:5], v226 offset:128
	ds_read_b128 v[34:37], v121 offset:4224
	s_waitcnt lgkmcnt(0)
	v_mfma_f32_32x32x16_bf16 v[18:33], v[2:5], v[34:37], v[18:33]
	ds_read_b128 v[2:5], v226 offset:160
	ds_read_b128 v[10:13], v121 offset:4256
	s_waitcnt lgkmcnt(0)
	v_mfma_f32_32x32x16_bf16 v[18:33], v[2:5], v[10:13], v[18:33]
	ds_read_b128 v[2:5], v226 offset:192
	ds_read_b128 v[6:9], v121 offset:4288
	s_waitcnt lgkmcnt(0)
	v_mfma_f32_32x32x16_bf16 v[18:33], v[2:5], v[6:9], v[18:33]
	ds_read_b128 v[54:57], v226 offset:224
	ds_read_b128 v[2:5], v121 offset:4320
	s_waitcnt lgkmcnt(0)
; #define LAS __attribute__((address_space(3)))
; __device__ __forceinline__ unsigned pk_bf16(float lo, float hi) { f32x2_t v = {lo, hi}; bf16x2_t b = __builtin_convertvector(v, bf16x2_t); return __builtin_bit_cast(unsigned, b); }
; __device__ __forceinline__ void gla_prep(LAS unsigned char* lds, const bf16_t* QK, const float* gz, const float* Wg, const float* bias,
;                                          bf16_t* QPimg, bf16_t* KTimg, bf16_t* Aimg, float* dec, int G) {
;     ...
;         { const int h2 = wid >> 1, tt = wid & 1; const int t = 32 * tt + l31;
; #pragma unroll
;           for (int jt = 0; jt < 2; ++jt) {
;             f32x16 acc;
; #pragma unroll
;             for (int r = 0; r < 16; ++r) acc[r] = 0.f;
; #pragma unroll
;             for (int ks = 0; ks < 8; ++ks) {
;                 const bf16x8 af = *(const LAS bf16x8*)(Ks + (32 * jt + l31) * GP_PITCH + h2 * 128 + 16 * ks + 8 * hi);
;                 const bf16x8 bf = *(const LAS bf16x8*)(Qs + t * GP_PITCH + h2 * 128 + 16 * ks + 8 * hi);
;                 acc = __builtin_amdgcn_mfma_f32_32x32x16_bf16(af, bf, acc, 0, 0, 0);
;             }
; #pragma unroll
;             for (int g4 = 0; g4 < 4; ++g4) { float v[4];
; #pragma unroll
;                 for (int e = 0; e < 4; ++e) { const int jj = 32 * jt + 8 * g4 + 4 * hi + e; v[e] = (jj <= t) ? acc[4 * g4 + e] : 0.f; }
;                 u32x2 w; w.x = pk_bf16(v[0], v[1]); w.y = pk_bf16(v[2], v[3]);
;                 *(u32x2*)(Aimg + ((((size_t)u * 4 + h2) * 8 + (4 * jt + g4)) * 64 + t) * 8 + 4 * hi) = w; }
;           } }
;         __syncthreads();
	v_mfma_f32_32x32x16_bf16 v[18:33], v[54:57], v[2:5], v[18:33]
	s_nop 11
	v_cndmask_b32_e64 v18, v18, 0, s[2:3]
	v_readlane_b32 s2, v255, 10
	v_readlane_b32 s3, v255, 11
	s_nop 1
	v_cndmask_b32_e64 v19, 0, v19, s[2:3]
	v_readlane_b32 s2, v255, 12
	v_readlane_b32 s3, v255, 13
	v_cvt_pk_bf16_f32 v18, v18, v19
	s_nop 0
	v_cndmask_b32_e64 v20, v20, 0, s[2:3]
	v_readlane_b32 s2, v255, 0
	v_readlane_b32 s3, v255, 1
	s_nop 1
	v_cndmask_b32_e64 v21, v21, 0, s[2:3]
	v_cvt_pk_bf16_f32 v19, v20, v21
	v_lshl_add_u64 v[20:21], s[8:9], 0, v[96:97]
	s_mov_b32 s2, 0x1a890000
	v_add_co_u32_e64 v56, s[82:83], s2, v20
	s_mov_b32 s2, 0x1a891000
	s_nop 0
	v_addc_co_u32_e64 v57, s[82:83], 0, v21, s[82:83]
	v_add_co_u32_e64 v54, s[82:83], s2, v20
	v_readlane_b32 s2, v255, 4
	s_nop 0
	v_addc_co_u32_e64 v55, s[82:83], 0, v21, s[82:83]
	v_readlane_b32 s3, v255, 5
	global_store_dwordx2 v[54:55], v[18:19], off offset:-4096
	s_nop 0
	v_cndmask_b32_e64 v18, v22, 0, s[2:3]
	v_readlane_b32 s2, v255, 14
	v_readlane_b32 s3, v255, 15
	s_nop 1
	v_cndmask_b32_e64 v19, v23, 0, s[2:3]
	v_readlane_b32 s2, v255, 16
	v_readlane_b32 s3, v255, 17
	v_cvt_pk_bf16_f32 v18, v18, v19
	s_nop 0
	v_cndmask_b32_e64 v20, v24, 0, s[2:3]
	v_readlane_b32 s2, v255, 18
	v_readlane_b32 s3, v255, 19
	s_nop 1
	v_cndmask_b32_e64 v21, v25, 0, s[2:3]
	v_readlane_b32 s2, v255, 20
	v_cvt_pk_bf16_f32 v19, v20, v21
	v_readlane_b32 s3, v255, 21
	global_store_dwordx2 v[56:57], v[18:19], off offset:1024
	s_nop 0
	v_cndmask_b32_e64 v18, v26, 0, s[2:3]
	v_readlane_b32 s2, v255, 22
	v_readlane_b32 s3, v255, 23
	s_nop 1
	v_cndmask_b32_e64 v19, v27, 0, s[2:3]
	v_readlane_b32 s2, v255, 24
	v_readlane_b32 s3, v255, 25
	v_cvt_pk_bf16_f32 v18, v18, v19
	s_nop 0
	v_cndmask_b32_e64 v20, v28, 0, s[2:3]
	v_readlane_b32 s2, v255, 26
	v_readlane_b32 s3, v255, 27
	s_nop 1
	v_cndmask_b32_e64 v21, v29, 0, s[2:3]
	v_readlane_b32 s2, v255, 28
	v_cvt_pk_bf16_f32 v19, v20, v21
	v_readlane_b32 s3, v255, 29
	global_store_dwordx2 v[56:57], v[18:19], off offset:2048
	v_cndmask_b32_e64 v19, v31, 0, s[10:11]
	v_cndmask_b32_e64 v18, v30, 0, s[2:3]
	v_cndmask_b32_e64 v20, v32, 0, s[14:15]
	v_cndmask_b32_e64 v21, v33, 0, s[16:17]
	v_cvt_pk_bf16_f32 v18, v18, v19
	v_cvt_pk_bf16_f32 v19, v20, v21
	global_store_dwordx2 v[56:57], v[18:19], off offset:3072
	ds_read_b128 v[18:21], v226 offset:33280
	ds_read_b128 v[56:59], v226 offset:33312
	s_waitcnt lgkmcnt(1)
	v_mfma_f32_32x32x16_bf16 v[18:33], v[18:21], v[46:49], 0
	ds_read_b128 v[46:49], v226 offset:33344
	v_readlane_b32 s2, v255, 6
	v_readlane_b32 s3, v255, 7
	s_waitcnt lgkmcnt(1)
	v_mfma_f32_32x32x16_bf16 v[18:33], v[56:59], v[50:53], v[18:33]
	s_waitcnt lgkmcnt(0)
	v_mfma_f32_32x32x16_bf16 v[18:33], v[46:49], v[42:45], v[18:33]
	ds_read_b128 v[42:45], v226 offset:33376
	s_waitcnt lgkmcnt(0)
	v_mfma_f32_32x32x16_bf16 v[18:33], v[42:45], v[38:41], v[18:33]
	ds_read_b128 v[38:41], v226 offset:33408
	s_waitcnt lgkmcnt(0)
	v_mfma_f32_32x32x16_bf16 v[18:33], v[38:41], v[34:37], v[18:33]
	ds_read_b128 v[34:37], v226 offset:33440
	s_waitcnt lgkmcnt(0)
	v_mfma_f32_32x32x16_bf16 v[18:33], v[34:37], v[10:13], v[18:33]
	ds_read_b128 v[10:13], v226 offset:33472
	s_waitcnt lgkmcnt(0)
	v_mfma_f32_32x32x16_bf16 v[18:33], v[10:13], v[6:9], v[18:33]
	ds_read_b128 v[6:9], v226 offset:33504
	s_waitcnt lgkmcnt(0)
	v_mfma_f32_32x32x16_bf16 v[18:33], v[6:9], v[2:5], v[18:33]
	s_nop 11
	v_cndmask_b32_e64 v2, v18, 0, s[18:19]
	v_cndmask_b32_e64 v3, v19, 0, s[20:21]
	v_cndmask_b32_e64 v4, v20, 0, s[22:23]
	v_cndmask_b32_e64 v5, v21, 0, s[24:25]
	v_cvt_pk_bf16_f32 v2, v2, v3
	v_cvt_pk_bf16_f32 v3, v4, v5
	global_store_dwordx2 v[54:55], v[2:3], off
	v_cndmask_b32_e64 v2, v22, 0, s[26:27]
	v_cndmask_b32_e64 v3, v23, 0, s[28:29]
	v_cndmask_b32_e64 v4, v24, 0, s[30:31]
	v_cndmask_b32_e64 v5, v25, 0, s[34:35]
	v_cvt_pk_bf16_f32 v2, v2, v3
	v_cvt_pk_bf16_f32 v3, v4, v5
	global_store_dwordx2 v[54:55], v[2:3], off offset:1024
	v_cndmask_b32_e64 v2, v26, 0, s[36:37]
	v_cndmask_b32_e64 v3, v27, 0, s[38:39]
	v_cndmask_b32_e64 v4, v28, 0, s[40:41]
	v_cndmask_b32_e64 v5, v29, 0, vcc
	v_cvt_pk_bf16_f32 v2, v2, v3
	v_cvt_pk_bf16_f32 v3, v4, v5
	global_store_dwordx2 v[54:55], v[2:3], off offset:2048
	v_cndmask_b32_e64 v2, v30, 0, s[2:3]
	v_readlane_b32 s2, v254, 16
	s_add_i32 s6, s6, s2
	v_readlane_b32 s2, v254, 19
	v_readlane_b32 s3, v254, 20
	v_cndmask_b32_e64 v3, v31, 0, s[76:77]
	v_cndmask_b32_e64 v4, v32, 0, s[78:79]
	v_lshl_add_u64 v[96:97], v[96:97], 0, s[2:3]
	v_readlane_b32 s2, v254, 34
	v_cndmask_b32_e64 v5, v33, 0, s[80:81]
	v_readlane_b32 s3, v254, 35
	v_cvt_pk_bf16_f32 v2, v2, v3
	v_cvt_pk_bf16_f32 v3, v4, v5
	v_lshl_add_u64 v[118:119], v[118:119], 0, s[2:3]
	s_cmpk_lt_i32 s86, 0x201
	global_store_dwordx2 v[54:55], v[2:3], off offset:3072
	s_barrier
	s_cbranch_scc0 .LBB0_277
